# v24
# speedup vs baseline: 1.0106x; 1.0106x over previous
; #define LDA(dst, b, h)                                                                                               \
;   _Pragma("unroll") for (int m = 0; m < 4; ++m) _Pragma("unroll") for (int k = 0; k < 2; ++k) dst[m][k] =            \
;       *reinterpret_cast<const bf16x8*>(SA(b, h) + lds_byte(wr * 64 + m * 16 + fr, k * 32 + fq * 8))
; #define LDB(dst, b, h)                                                                                               \
;   _Pragma("unroll") for (int n = 0; n < 2; ++n) _Pragma("unroll") for (int k = 0; k < 2; ++k) dst[n][k] =            \
;       *reinterpret_cast<const bf16x8*>(SB(b, h) + lds_byte(wc * 32 + n * 16 + fr, k * 32 + fq * 8))
; #define WAIT_V(n) asm volatile("s_waitcnt vmcnt(" #n ")" ::: "memory")
; #define WAIT_L(n) asm volatile("s_waitcnt lgkmcnt(" #n ")" ::: "memory")
; #define BAR __builtin_amdgcn_s_barrier()
; #define SCHED __builtin_amdgcn_sched_barrier(0)
; template <int EPI>
; __device__ __forceinline__ void gemm_phase(const u16* __restrict__ A, const u16* __restrict__ Bt, const int K,
;                                            const int nN, char* shm, const EpiArgs& ea) {
;     ...
;     for (int t = 0; t < nt - 2; t += 2) {
;       LDB(B0, 0, 0); SCHED; LDA(At, 0, 0); STAGE(SA(1, 1), rA, brow + HALF, t + 1);
;       WAIT_V(10); WAIT_L(8); BAR; WAIT_L(0); MMA(0, 0, At, B0); BAR; SCHED;
;       LDB(B1, 0, 1); STAGE(SB(0, 0), rB, bcol, t + 2);
;       WAIT_V(10); BAR; WAIT_L(0); MMA(0, 1, At, B1); BAR;
;       LDA(At, 0, 1); STAGE(SA(0, 0), rA, brow, t + 2);
;       BAR; WAIT_L(0); MMA(1, 0, At, B0); BAR; SCHED;
;       STAGE(SB(0, 1), rB, bcol + HALF, t + 2);
;       WAIT_V(10); BAR; MMA(1, 1, At, B1); BAR;
.LBB0_172:
	ds_read_b128 v[142:145], v133
	ds_read_b128 v[146:149], v133 offset:1024
	ds_read_b128 v[150:153], v133 offset:2048
	ds_read_b128 v[154:157], v133 offset:3072
	s_add_i32 s73, s67, s72
	s_mov_b32 m0, s57
	s_add_i32 s6, s73, 0x4000
	ds_read_b128 v[162:165], v134
	ds_read_b128 v[166:169], v134 offset:1024
	ds_read_b128 v[170:173], v135
	ds_read_b128 v[176:179], v135 offset:1024
	ds_read_b128 v[180:183], v136
	ds_read_b128 v[184:187], v136 offset:1024
	ds_read_b128 v[188:191], v137
	ds_read_b128 v[192:195], v137 offset:1024
	buffer_load_dwordx4 v130, s[0:3], s6 offen lds
	s_add_i32 s6, s73, 0x6000
	s_mov_b32 m0, s58
	s_nop 0
	buffer_load_dwordx4 v130, s[0:3], s6 offen lds
	s_waitcnt vmcnt(10)
	s_waitcnt lgkmcnt(8)
	s_barrier
	s_waitcnt lgkmcnt(0)
	v_mfma_f32_16x16x32_bf16 v[124:127], v[142:145], v[162:165], v[124:127]
	v_mfma_f32_16x16x32_bf16 v[120:123], v[150:153], v[162:165], v[120:123]
	v_mfma_f32_16x16x32_bf16 v[116:119], v[142:145], v[170:173], v[116:119]
	v_mfma_f32_16x16x32_bf16 v[112:115], v[150:153], v[170:173], v[112:115]
	v_mfma_f32_16x16x32_bf16 v[108:111], v[142:145], v[180:183], v[108:111]
	v_mfma_f32_16x16x32_bf16 v[104:107], v[150:153], v[180:183], v[104:107]
	v_mfma_f32_16x16x32_bf16 v[100:103], v[142:145], v[188:191], v[100:103]
	v_mfma_f32_16x16x32_bf16 v[96:99], v[150:153], v[188:191], v[96:99]
	v_mfma_f32_16x16x32_bf16 v[124:127], v[146:149], v[166:169], v[124:127]
	v_mfma_f32_16x16x32_bf16 v[120:123], v[154:157], v[166:169], v[120:123]
	v_mfma_f32_16x16x32_bf16 v[116:119], v[146:149], v[176:179], v[116:119]
	v_mfma_f32_16x16x32_bf16 v[112:115], v[154:157], v[176:179], v[112:115]
	v_mfma_f32_16x16x32_bf16 v[108:111], v[146:149], v[184:187], v[108:111]
	v_mfma_f32_16x16x32_bf16 v[104:107], v[154:157], v[184:187], v[104:107]
	v_mfma_f32_16x16x32_bf16 v[100:103], v[146:149], v[192:195], v[100:103]
	v_mfma_f32_16x16x32_bf16 v[96:99], v[154:157], v[192:195], v[96:99]
	s_barrier
	s_add_i32 s74, s70, s72
	s_mov_b32 m0, s34
	s_add_i32 s75, s74, 0x8000
	s_mov_b32 s6, s2
	s_mov_b32 s7, s3
	ds_read_b128 v[196:199], v138
	ds_read_b128 v[200:203], v138 offset:1024
	ds_read_b128 v[204:207], v138 offset:2048
	ds_read_b128 v[208:211], v138 offset:3072
	buffer_load_dwordx4 v130, s[4:7], s75 offen lds
	s_add_i32 s75, s74, 0xa000
	s_mov_b32 m0, s35
	s_nop 0
	buffer_load_dwordx4 v130, s[4:7], s75 offen lds
	s_waitcnt vmcnt(10)
	s_barrier
	s_waitcnt lgkmcnt(0)
	v_mfma_f32_16x16x32_bf16 v[92:95], v[196:199], v[162:165], v[92:95]
	v_mfma_f32_16x16x32_bf16 v[88:91], v[204:207], v[162:165], v[88:91]
	v_mfma_f32_16x16x32_bf16 v[84:87], v[196:199], v[170:173], v[84:87]
	v_mfma_f32_16x16x32_bf16 v[80:83], v[204:207], v[170:173], v[80:83]
	v_mfma_f32_16x16x32_bf16 v[76:79], v[196:199], v[180:183], v[76:79]
	v_mfma_f32_16x16x32_bf16 v[72:75], v[204:207], v[180:183], v[72:75]
	v_mfma_f32_16x16x32_bf16 v[68:71], v[196:199], v[188:191], v[68:71]
	v_mfma_f32_16x16x32_bf16 v[64:67], v[204:207], v[188:191], v[64:67]
	v_mfma_f32_16x16x32_bf16 v[92:95], v[200:203], v[166:169], v[92:95]
	v_mfma_f32_16x16x32_bf16 v[88:91], v[208:211], v[166:169], v[88:91]
	v_mfma_f32_16x16x32_bf16 v[84:87], v[200:203], v[176:179], v[84:87]
	v_mfma_f32_16x16x32_bf16 v[80:83], v[208:211], v[176:179], v[80:83]
	v_mfma_f32_16x16x32_bf16 v[76:79], v[200:203], v[184:187], v[76:79]
	v_mfma_f32_16x16x32_bf16 v[72:75], v[208:211], v[184:187], v[72:75]
	v_mfma_f32_16x16x32_bf16 v[68:71], v[200:203], v[192:195], v[68:71]
	v_mfma_f32_16x16x32_bf16 v[64:67], v[208:211], v[192:195], v[64:67]
	s_add_i32 s75, s69, s72
	s_mov_b32 m0, s38
	s_add_i32 s78, s75, 0x8000
	s_barrier
	ds_read_b128 v[162:165], v134 offset:16384
	ds_read_b128 v[166:169], v134 offset:17408
	ds_read_b128 v[170:173], v135 offset:16384
	ds_read_b128 v[176:179], v135 offset:17408
	ds_read_b128 v[180:183], v136 offset:16384
	ds_read_b128 v[184:187], v136 offset:17408
	ds_read_b128 v[188:191], v137 offset:16384
	ds_read_b128 v[192:195], v137 offset:17408
	buffer_load_dwordx4 v130, s[0:3], s78 offen lds
	s_add_i32 s78, s75, 0xa000
	s_mov_b32 m0, s39
	s_nop 0
	buffer_load_dwordx4 v130, s[0:3], s78 offen lds
	s_barrier
	s_waitcnt lgkmcnt(0)
	v_mfma_f32_16x16x32_bf16 v[60:63], v[142:145], v[162:165], v[60:63]
	v_mfma_f32_16x16x32_bf16 v[56:59], v[150:153], v[162:165], v[56:59]
	v_mfma_f32_16x16x32_bf16 v[52:55], v[142:145], v[170:173], v[52:55]
	v_mfma_f32_16x16x32_bf16 v[48:51], v[150:153], v[170:173], v[48:51]
	v_mfma_f32_16x16x32_bf16 v[44:47], v[142:145], v[180:183], v[44:47]
	v_mfma_f32_16x16x32_bf16 v[40:43], v[150:153], v[180:183], v[40:43]
	v_mfma_f32_16x16x32_bf16 v[36:39], v[142:145], v[188:191], v[36:39]
	v_mfma_f32_16x16x32_bf16 v[32:35], v[150:153], v[188:191], v[32:35]
	v_mfma_f32_16x16x32_bf16 v[60:63], v[146:149], v[166:169], v[60:63]
	v_mfma_f32_16x16x32_bf16 v[56:59], v[154:157], v[166:169], v[56:59]
	v_mfma_f32_16x16x32_bf16 v[52:55], v[146:149], v[176:179], v[52:55]
	v_mfma_f32_16x16x32_bf16 v[48:51], v[154:157], v[176:179], v[48:51]
	v_mfma_f32_16x16x32_bf16 v[44:47], v[146:149], v[184:187], v[44:47]
	v_mfma_f32_16x16x32_bf16 v[40:43], v[154:157], v[184:187], v[40:43]
	v_mfma_f32_16x16x32_bf16 v[36:39], v[146:149], v[192:195], v[36:39]
	v_mfma_f32_16x16x32_bf16 v[32:35], v[154:157], v[192:195], v[32:35]
	s_barrier
	s_add_i32 s78, s68, s72
	s_mov_b32 m0, s40
	s_add_i32 s79, s78, 0x8000
	buffer_load_dwordx4 v130, s[4:7], s79 offen lds
	s_add_i32 s79, s78, 0xa000
	s_mov_b32 m0, s41
	s_nop 0
	buffer_load_dwordx4 v130, s[4:7], s79 offen lds
	s_waitcnt vmcnt(10)
	s_barrier
; #define LDA(dst, b, h)                                                                                               \
;   _Pragma("unroll") for (int m = 0; m < 4; ++m) _Pragma("unroll") for (int k = 0; k < 2; ++k) dst[m][k] =            \
;       *reinterpret_cast<const bf16x8*>(SA(b, h) + lds_byte(wr * 64 + m * 16 + fr, k * 32 + fq * 8))
; #define LDB(dst, b, h)                                                                                               \
;   _Pragma("unroll") for (int n = 0; n < 2; ++n) _Pragma("unroll") for (int k = 0; k < 2; ++k) dst[n][k] =            \
;       *reinterpret_cast<const bf16x8*>(SB(b, h) + lds_byte(wc * 32 + n * 16 + fr, k * 32 + fq * 8))
; #define WAIT_V(n) asm volatile("s_waitcnt vmcnt(" #n ")" ::: "memory")
; #define WAIT_L(n) asm volatile("s_waitcnt lgkmcnt(" #n ")" ::: "memory")
; #define BAR __builtin_amdgcn_s_barrier()
; #define SCHED __builtin_amdgcn_sched_barrier(0)
; template <int EPI>
; __device__ __forceinline__ void gemm_phase(const u16* __restrict__ A, const u16* __restrict__ Bt, const int K,
;                                            const int nN, char* shm, const EpiArgs& ea) {
;     ...
;       WAIT_V(10); BAR; MMA(1, 1, At, B1); BAR;
;       LDB(B0, 1, 0); SCHED; LDA(At, 1, 0); STAGE(SA(0, 1), rA, brow + HALF, t + 2);
;       WAIT_V(10); WAIT_L(8); BAR; WAIT_L(0); MMA(0, 0, At, B0); BAR; SCHED;
;       LDB(B1, 1, 1); STAGE(SB(1, 0), rB, bcol, t + 3);
;       WAIT_V(10); BAR; WAIT_L(0); MMA(0, 1, At, B1); BAR;
	v_mfma_f32_16x16x32_bf16 v[28:31], v[196:199], v[162:165], v[28:31]
	v_mfma_f32_16x16x32_bf16 v[24:27], v[204:207], v[162:165], v[24:27]
	v_mfma_f32_16x16x32_bf16 v[20:23], v[196:199], v[170:173], v[20:23]
	v_mfma_f32_16x16x32_bf16 v[16:19], v[204:207], v[170:173], v[16:19]
	v_mfma_f32_16x16x32_bf16 v[12:15], v[196:199], v[180:183], v[12:15]
	v_mfma_f32_16x16x32_bf16 v[8:11], v[204:207], v[180:183], v[8:11]
	v_mfma_f32_16x16x32_bf16 v[4:7], v[196:199], v[188:191], v[4:7]
	v_mfma_f32_16x16x32_bf16 v[0:3], v[204:207], v[188:191], v[0:3]
	v_mfma_f32_16x16x32_bf16 v[28:31], v[200:203], v[166:169], v[28:31]
	v_mfma_f32_16x16x32_bf16 v[24:27], v[208:211], v[166:169], v[24:27]
	v_mfma_f32_16x16x32_bf16 v[20:23], v[200:203], v[176:179], v[20:23]
	v_mfma_f32_16x16x32_bf16 v[16:19], v[208:211], v[176:179], v[16:19]
	v_mfma_f32_16x16x32_bf16 v[12:15], v[200:203], v[184:187], v[12:15]
	v_mfma_f32_16x16x32_bf16 v[8:11], v[208:211], v[184:187], v[8:11]
	v_mfma_f32_16x16x32_bf16 v[4:7], v[200:203], v[192:195], v[4:7]
	v_mfma_f32_16x16x32_bf16 v[0:3], v[208:211], v[192:195], v[0:3]
	s_barrier
	ds_read_b128 v[142:145], v139
	ds_read_b128 v[146:149], v139 offset:1024
	ds_read_b128 v[150:153], v139 offset:2048
	ds_read_b128 v[154:157], v139 offset:3072
	s_mov_b32 m0, s42
	s_add_i32 s79, s73, 0x8000
	ds_read_b128 v[162:165], v134 offset:32768
	ds_read_b128 v[166:169], v134 offset:33792
	ds_read_b128 v[170:173], v135 offset:32768
	ds_read_b128 v[176:179], v135 offset:33792
	ds_read_b128 v[180:183], v136 offset:32768
	ds_read_b128 v[184:187], v136 offset:33792
	ds_read_b128 v[188:191], v137 offset:32768
	ds_read_b128 v[192:195], v137 offset:33792
	buffer_load_dwordx4 v130, s[0:3], s79 offen lds
	s_add_i32 s73, s73, 0xa000
	s_mov_b32 m0, s43
	s_nop 0
	buffer_load_dwordx4 v130, s[0:3], s73 offen lds
	s_waitcnt vmcnt(10)
	s_waitcnt lgkmcnt(8)
	s_barrier
	s_waitcnt lgkmcnt(0)
	v_mfma_f32_16x16x32_bf16 v[124:127], v[142:145], v[162:165], v[124:127]
	v_mfma_f32_16x16x32_bf16 v[120:123], v[150:153], v[162:165], v[120:123]
	v_mfma_f32_16x16x32_bf16 v[116:119], v[142:145], v[170:173], v[116:119]
	v_mfma_f32_16x16x32_bf16 v[112:115], v[150:153], v[170:173], v[112:115]
	v_mfma_f32_16x16x32_bf16 v[108:111], v[142:145], v[180:183], v[108:111]
	v_mfma_f32_16x16x32_bf16 v[104:107], v[150:153], v[180:183], v[104:107]
	v_mfma_f32_16x16x32_bf16 v[100:103], v[142:145], v[188:191], v[100:103]
	v_mfma_f32_16x16x32_bf16 v[96:99], v[150:153], v[188:191], v[96:99]
	v_mfma_f32_16x16x32_bf16 v[124:127], v[146:149], v[166:169], v[124:127]
	v_mfma_f32_16x16x32_bf16 v[120:123], v[154:157], v[166:169], v[120:123]
	v_mfma_f32_16x16x32_bf16 v[116:119], v[146:149], v[176:179], v[116:119]
	v_mfma_f32_16x16x32_bf16 v[112:115], v[154:157], v[176:179], v[112:115]
	v_mfma_f32_16x16x32_bf16 v[108:111], v[146:149], v[184:187], v[108:111]
	v_mfma_f32_16x16x32_bf16 v[104:107], v[154:157], v[184:187], v[104:107]
	v_mfma_f32_16x16x32_bf16 v[100:103], v[146:149], v[192:195], v[100:103]
	v_mfma_f32_16x16x32_bf16 v[96:99], v[154:157], v[192:195], v[96:99]
	s_barrier
	s_mov_b32 m0, s48
	s_add_i32 s73, s74, 0xc000
	ds_read_b128 v[196:199], v140
	ds_read_b128 v[200:203], v140 offset:1024
	ds_read_b128 v[204:207], v140 offset:2048
	ds_read_b128 v[208:211], v140 offset:3072
	buffer_load_dwordx4 v130, s[4:7], s73 offen lds
	s_add_i32 s74, s74, 0xe000
	s_mov_b32 m0, s49
	s_nop 0
	buffer_load_dwordx4 v130, s[4:7], s74 offen lds
	s_waitcnt vmcnt(10)
	s_barrier
	s_waitcnt lgkmcnt(0)
	v_mfma_f32_16x16x32_bf16 v[92:95], v[196:199], v[162:165], v[92:95]
	v_mfma_f32_16x16x32_bf16 v[88:91], v[204:207], v[162:165], v[88:91]
	v_mfma_f32_16x16x32_bf16 v[84:87], v[196:199], v[170:173], v[84:87]
	v_mfma_f32_16x16x32_bf16 v[80:83], v[204:207], v[170:173], v[80:83]
	v_mfma_f32_16x16x32_bf16 v[76:79], v[196:199], v[180:183], v[76:79]
	v_mfma_f32_16x16x32_bf16 v[72:75], v[204:207], v[180:183], v[72:75]
	v_mfma_f32_16x16x32_bf16 v[68:71], v[196:199], v[188:191], v[68:71]
	v_mfma_f32_16x16x32_bf16 v[64:67], v[204:207], v[188:191], v[64:67]
	v_mfma_f32_16x16x32_bf16 v[92:95], v[200:203], v[166:169], v[92:95]
	v_mfma_f32_16x16x32_bf16 v[88:91], v[208:211], v[166:169], v[88:91]
	v_mfma_f32_16x16x32_bf16 v[84:87], v[200:203], v[176:179], v[84:87]
	v_mfma_f32_16x16x32_bf16 v[80:83], v[208:211], v[176:179], v[80:83]
	v_mfma_f32_16x16x32_bf16 v[76:79], v[200:203], v[184:187], v[76:79]
	v_mfma_f32_16x16x32_bf16 v[72:75], v[208:211], v[184:187], v[72:75]
	v_mfma_f32_16x16x32_bf16 v[68:71], v[200:203], v[192:195], v[68:71]
	v_mfma_f32_16x16x32_bf16 v[64:67], v[208:211], v[192:195], v[64:67]
	s_mov_b32 m0, s52
	s_add_i32 s73, s75, 0xc000
	s_barrier
	ds_read_b128 v[162:165], v134 offset:49152
	ds_read_b128 v[166:169], v134 offset:50176
	ds_read_b128 v[170:173], v135 offset:49152
	ds_read_b128 v[176:179], v135 offset:50176
	ds_read_b128 v[180:183], v136 offset:49152
	ds_read_b128 v[184:187], v136 offset:50176
	ds_read_b128 v[188:191], v137 offset:49152
	ds_read_b128 v[192:195], v137 offset:50176
	buffer_load_dwordx4 v130, s[0:3], s73 offen lds
	s_add_i32 s75, s75, 0xe000
	s_mov_b32 m0, s53
	s_nop 0
	buffer_load_dwordx4 v130, s[0:3], s75 offen lds
	s_barrier
; #define LDA(dst, b, h)                                                                                               \
;   _Pragma("unroll") for (int m = 0; m < 4; ++m) _Pragma("unroll") for (int k = 0; k < 2; ++k) dst[m][k] =            \
;       *reinterpret_cast<const bf16x8*>(SA(b, h) + lds_byte(wr * 64 + m * 16 + fr, k * 32 + fq * 8))
; #define LDB(dst, b, h)                                                                                               \
;   _Pragma("unroll") for (int n = 0; n < 2; ++n) _Pragma("unroll") for (int k = 0; k < 2; ++k) dst[n][k] =            \
;       *reinterpret_cast<const bf16x8*>(SB(b, h) + lds_byte(wc * 32 + n * 16 + fr, k * 32 + fq * 8))
; #define WAIT_V(n) asm volatile("s_waitcnt vmcnt(" #n ")" ::: "memory")
; #define WAIT_L(n) asm volatile("s_waitcnt lgkmcnt(" #n ")" ::: "memory")
; #define BAR __builtin_amdgcn_s_barrier()
; #define SCHED __builtin_amdgcn_sched_barrier(0)
; template <int EPI>
; __device__ __forceinline__ void gemm_phase(const u16* __restrict__ A, const u16* __restrict__ Bt, const int K,
;                                            const int nN, char* shm, const EpiArgs& ea) {
;     ...
;       LDA(At, 1, 1); STAGE(SA(1, 0), rA, brow, t + 3);
;       BAR; WAIT_L(0); MMA(1, 0, At, B0); BAR; SCHED;
;       STAGE(SB(1, 1), rB, bcol + HALF, t + 3);
;       WAIT_V(10); BAR; MMA(1, 1, At, B1); BAR;
;     }
;     float eC = 0.f, eB = 0.f;
;     float2 eS = make_float2(0.f, 0.f);
;     if (EPI == EPI_IN || EPI == EPI_SWIGLU_LN) {
;       if (wr == 0) {
;         eC = ea.c1[bcol + tid];
;         eS = *(const float2*)(ea.st_in + (size_t)(brow + tid) * 2);
;       } else {
;         eC = ea.c2[bcol + tid - 256];
;         if (EPI == EPI_IN) eB = ea.bias[bcol + tid - 256];
;       }
;     }
;     {
;       LDB(B0, 0, 0); LDA(At, 0, 0); STAGE(SA(1, 1), rA, brow + HALF, nt - 1);
;       WAIT_V(10); BAR; WAIT_L(0); MMA(0, 0, At, B0); BAR;
;       LDB(B1, 0, 1); WAIT_V(8); BAR; WAIT_L(0); MMA(0, 1, At, B1); BAR;
;       LDA(At, 0, 1); WAIT_V(4); BAR; WAIT_L(0); MMA(1, 0, At, B0); MMA(1, 1, At, B1); BAR;
	s_waitcnt lgkmcnt(0)
	v_mfma_f32_16x16x32_bf16 v[60:63], v[142:145], v[162:165], v[60:63]
	v_mfma_f32_16x16x32_bf16 v[56:59], v[150:153], v[162:165], v[56:59]
	v_mfma_f32_16x16x32_bf16 v[52:55], v[142:145], v[170:173], v[52:55]
	v_mfma_f32_16x16x32_bf16 v[48:51], v[150:153], v[170:173], v[48:51]
	v_mfma_f32_16x16x32_bf16 v[44:47], v[142:145], v[180:183], v[44:47]
	v_mfma_f32_16x16x32_bf16 v[40:43], v[150:153], v[180:183], v[40:43]
	v_mfma_f32_16x16x32_bf16 v[36:39], v[142:145], v[188:191], v[36:39]
	v_mfma_f32_16x16x32_bf16 v[32:35], v[150:153], v[188:191], v[32:35]
	v_mfma_f32_16x16x32_bf16 v[60:63], v[146:149], v[166:169], v[60:63]
	v_mfma_f32_16x16x32_bf16 v[56:59], v[154:157], v[166:169], v[56:59]
	v_mfma_f32_16x16x32_bf16 v[52:55], v[146:149], v[176:179], v[52:55]
	v_mfma_f32_16x16x32_bf16 v[48:51], v[154:157], v[176:179], v[48:51]
	v_mfma_f32_16x16x32_bf16 v[44:47], v[146:149], v[184:187], v[44:47]
	v_mfma_f32_16x16x32_bf16 v[40:43], v[154:157], v[184:187], v[40:43]
	v_mfma_f32_16x16x32_bf16 v[36:39], v[146:149], v[192:195], v[36:39]
	v_mfma_f32_16x16x32_bf16 v[32:35], v[154:157], v[192:195], v[32:35]
	s_barrier
	s_mov_b32 m0, s54
	s_add_i32 s73, s78, 0xc000
	buffer_load_dwordx4 v130, s[4:7], s73 offen lds
	s_add_i32 s78, s78, 0xe000
	s_mov_b32 m0, s55
	s_nop 0
	buffer_load_dwordx4 v130, s[4:7], s78 offen lds
	s_waitcnt vmcnt(10)
	s_barrier
	v_mfma_f32_16x16x32_bf16 v[28:31], v[196:199], v[162:165], v[28:31]
	v_mfma_f32_16x16x32_bf16 v[24:27], v[204:207], v[162:165], v[24:27]
	v_mfma_f32_16x16x32_bf16 v[20:23], v[196:199], v[170:173], v[20:23]
	v_mfma_f32_16x16x32_bf16 v[16:19], v[204:207], v[170:173], v[16:19]
	v_mfma_f32_16x16x32_bf16 v[12:15], v[196:199], v[180:183], v[12:15]
	v_mfma_f32_16x16x32_bf16 v[8:11], v[204:207], v[180:183], v[8:11]
	v_mfma_f32_16x16x32_bf16 v[4:7], v[196:199], v[188:191], v[4:7]
	v_mfma_f32_16x16x32_bf16 v[0:3], v[204:207], v[188:191], v[0:3]
	v_mfma_f32_16x16x32_bf16 v[28:31], v[200:203], v[166:169], v[28:31]
	v_mfma_f32_16x16x32_bf16 v[24:27], v[208:211], v[166:169], v[24:27]
	v_mfma_f32_16x16x32_bf16 v[20:23], v[200:203], v[176:179], v[20:23]
	v_mfma_f32_16x16x32_bf16 v[16:19], v[208:211], v[176:179], v[16:19]
	v_mfma_f32_16x16x32_bf16 v[12:15], v[200:203], v[184:187], v[12:15]
	v_mfma_f32_16x16x32_bf16 v[8:11], v[208:211], v[184:187], v[8:11]
	v_mfma_f32_16x16x32_bf16 v[4:7], v[200:203], v[192:195], v[4:7]
	v_mfma_f32_16x16x32_bf16 v[0:3], v[208:211], v[192:195], v[0:3]
	s_add_i32 s71, s71, 2
	s_add_i32 s72, s72, 0x8000
	s_cmp_lt_u32 s71, 28
	s_barrier
	s_cbranch_scc1 .LBB0_172
	s_mov_b32 m0, s57
	s_add_i32 s6, s67, 0x7c000
	ds_read_b128 v[142:145], v133
	ds_read_b128 v[146:149], v133 offset:1024
	ds_read_b128 v[150:153], v133 offset:2048
	ds_read_b128 v[154:157], v133 offset:3072
	ds_read_b128 v[162:165], v134
	ds_read_b128 v[166:169], v134 offset:1024
	ds_read_b128 v[170:173], v135
	ds_read_b128 v[176:179], v135 offset:1024
	ds_read_b128 v[180:183], v136
	ds_read_b128 v[184:187], v136 offset:1024
	ds_read_b128 v[188:191], v137
	ds_read_b128 v[192:195], v137 offset:1024
	buffer_load_dwordx4 v130, s[0:3], s6 offen lds
	s_add_i32 s67, s67, 0x7e000
	s_mov_b32 m0, s58
	s_nop 0
	buffer_load_dwordx4 v130, s[0:3], s67 offen lds
	s_waitcnt vmcnt(10)
	s_barrier
	s_waitcnt lgkmcnt(0)
	v_mfma_f32_16x16x32_bf16 v[124:127], v[142:145], v[162:165], v[124:127]
	v_mfma_f32_16x16x32_bf16 v[120:123], v[150:153], v[162:165], v[120:123]
	v_mfma_f32_16x16x32_bf16 v[116:119], v[142:145], v[170:173], v[116:119]
	v_mfma_f32_16x16x32_bf16 v[112:115], v[150:153], v[170:173], v[112:115]
	v_mfma_f32_16x16x32_bf16 v[108:111], v[142:145], v[180:183], v[108:111]
	v_mfma_f32_16x16x32_bf16 v[104:107], v[150:153], v[180:183], v[104:107]
	v_mfma_f32_16x16x32_bf16 v[100:103], v[142:145], v[188:191], v[100:103]
	v_mfma_f32_16x16x32_bf16 v[96:99], v[150:153], v[188:191], v[96:99]
	v_mfma_f32_16x16x32_bf16 v[124:127], v[146:149], v[166:169], v[124:127]
	v_mfma_f32_16x16x32_bf16 v[120:123], v[154:157], v[166:169], v[120:123]
	v_mfma_f32_16x16x32_bf16 v[116:119], v[146:149], v[176:179], v[116:119]
	v_mfma_f32_16x16x32_bf16 v[112:115], v[154:157], v[176:179], v[112:115]
	v_mfma_f32_16x16x32_bf16 v[108:111], v[146:149], v[184:187], v[108:111]
	v_mfma_f32_16x16x32_bf16 v[104:107], v[154:157], v[184:187], v[104:107]
	v_mfma_f32_16x16x32_bf16 v[100:103], v[146:149], v[192:195], v[100:103]
	v_mfma_f32_16x16x32_bf16 v[96:99], v[154:157], v[192:195], v[96:99]
	s_barrier
	ds_read_b128 v[196:199], v138
	ds_read_b128 v[200:203], v138 offset:1024
	ds_read_b128 v[204:207], v138 offset:2048
	ds_read_b128 v[208:211], v138 offset:3072
	s_waitcnt vmcnt(8)
	s_barrier
	s_waitcnt lgkmcnt(0)
	v_mfma_f32_16x16x32_bf16 v[76:79], v[196:199], v[180:183], v[76:79]
	v_mfma_f32_16x16x32_bf16 v[72:75], v[204:207], v[180:183], v[72:75]
	v_mfma_f32_16x16x32_bf16 v[68:71], v[196:199], v[188:191], v[68:71]
	v_mfma_f32_16x16x32_bf16 v[64:67], v[204:207], v[188:191], v[64:67]
	v_mfma_f32_16x16x32_bf16 v[92:95], v[196:199], v[162:165], v[92:95]
	v_mfma_f32_16x16x32_bf16 v[88:91], v[204:207], v[162:165], v[88:91]
	v_mfma_f32_16x16x32_bf16 v[84:87], v[196:199], v[170:173], v[84:87]
	v_mfma_f32_16x16x32_bf16 v[80:83], v[204:207], v[170:173], v[80:83]
	v_mfma_f32_16x16x32_bf16 v[76:79], v[200:203], v[184:187], v[76:79]
	v_mfma_f32_16x16x32_bf16 v[72:75], v[208:211], v[184:187], v[72:75]
	v_mfma_f32_16x16x32_bf16 v[68:71], v[200:203], v[192:195], v[68:71]
	v_mfma_f32_16x16x32_bf16 v[64:67], v[208:211], v[192:195], v[64:67]
	v_mfma_f32_16x16x32_bf16 v[212:215], v[200:203], v[166:169], v[92:95]
	v_mfma_f32_16x16x32_bf16 v[162:165], v[208:211], v[166:169], v[88:91]
	v_mfma_f32_16x16x32_bf16 v[166:169], v[200:203], v[176:179], v[84:87]
	v_mfma_f32_16x16x32_bf16 v[170:173], v[208:211], v[176:179], v[80:83]
	s_barrier
; #define LDA(dst, b, h)                                                                                               \
;   _Pragma("unroll") for (int m = 0; m < 4; ++m) _Pragma("unroll") for (int k = 0; k < 2; ++k) dst[m][k] =            \
;       *reinterpret_cast<const bf16x8*>(SA(b, h) + lds_byte(wr * 64 + m * 16 + fr, k * 32 + fq * 8))
; #define LDB(dst, b, h)                                                                                               \
;   _Pragma("unroll") for (int n = 0; n < 2; ++n) _Pragma("unroll") for (int k = 0; k < 2; ++k) dst[n][k] =            \
;       *reinterpret_cast<const bf16x8*>(SB(b, h) + lds_byte(wc * 32 + n * 16 + fr, k * 32 + fq * 8))
; #define WAIT_V(n) asm volatile("s_waitcnt vmcnt(" #n ")" ::: "memory")
; #define WAIT_L(n) asm volatile("s_waitcnt lgkmcnt(" #n ")" ::: "memory")
; #define BAR __builtin_amdgcn_s_barrier()
; template <int EPI>
; __device__ __forceinline__ void gemm_phase(const u16* __restrict__ A, const u16* __restrict__ Bt, const int K,
;                                            const int nN, char* shm, const EpiArgs& ea) {
;     ...
;       LDB(B1, 0, 1); WAIT_V(8); BAR; WAIT_L(0); MMA(0, 1, At, B1); BAR;
;       LDA(At, 0, 1); WAIT_V(4); BAR; WAIT_L(0); MMA(1, 0, At, B0); MMA(1, 1, At, B1); BAR;
;     }
;     {
;       LDB(B0, 1, 0); LDA(At, 1, 0); WAIT_V(2); BAR; WAIT_L(0); MMA(0, 0, At, B0); BAR;
;       LDB(B1, 1, 1); WAIT_V(0); BAR; WAIT_L(0); MMA(0, 1, At, B1); BAR;
	s_nop 0
	ds_read_b128 v[80:83], v134 offset:16384
	ds_read_b128 v[84:87], v134 offset:17408
	ds_read_b128 v[88:91], v135 offset:16384
	ds_read_b128 v[92:95], v135 offset:17408
	ds_read_b128 v[176:179], v136 offset:16384
	ds_read_b128 v[180:183], v136 offset:17408
	ds_read_b128 v[184:187], v137 offset:16384
	ds_read_b128 v[188:191], v137 offset:17408
	s_waitcnt vmcnt(4)
	s_barrier
	s_waitcnt lgkmcnt(0)
	v_mfma_f32_16x16x32_bf16 v[60:63], v[142:145], v[80:83], v[60:63]
	v_mfma_f32_16x16x32_bf16 v[56:59], v[150:153], v[80:83], v[56:59]
	v_mfma_f32_16x16x32_bf16 v[52:55], v[142:145], v[88:91], v[52:55]
	v_mfma_f32_16x16x32_bf16 v[48:51], v[150:153], v[88:91], v[48:51]
	v_mfma_f32_16x16x32_bf16 v[44:47], v[142:145], v[176:179], v[44:47]
	v_mfma_f32_16x16x32_bf16 v[40:43], v[150:153], v[176:179], v[40:43]
	v_mfma_f32_16x16x32_bf16 v[36:39], v[142:145], v[184:187], v[36:39]
	v_mfma_f32_16x16x32_bf16 v[32:35], v[150:153], v[184:187], v[32:35]
	v_mfma_f32_16x16x32_bf16 v[60:63], v[146:149], v[84:87], v[60:63]
	v_mfma_f32_16x16x32_bf16 v[56:59], v[154:157], v[84:87], v[56:59]
	v_mfma_f32_16x16x32_bf16 v[52:55], v[146:149], v[92:95], v[52:55]
	v_mfma_f32_16x16x32_bf16 v[48:51], v[154:157], v[92:95], v[48:51]
	v_mfma_f32_16x16x32_bf16 v[44:47], v[146:149], v[180:183], v[44:47]
	v_mfma_f32_16x16x32_bf16 v[40:43], v[154:157], v[180:183], v[40:43]
	v_mfma_f32_16x16x32_bf16 v[36:39], v[146:149], v[188:191], v[36:39]
	v_mfma_f32_16x16x32_bf16 v[32:35], v[154:157], v[188:191], v[32:35]
	v_mfma_f32_16x16x32_bf16 v[12:15], v[196:199], v[176:179], v[12:15]
	v_mfma_f32_16x16x32_bf16 v[8:11], v[204:207], v[176:179], v[8:11]
	v_mfma_f32_16x16x32_bf16 v[4:7], v[196:199], v[184:187], v[4:7]
	v_mfma_f32_16x16x32_bf16 v[0:3], v[204:207], v[184:187], v[0:3]
	v_mfma_f32_16x16x32_bf16 v[28:31], v[196:199], v[80:83], v[28:31]
	v_mfma_f32_16x16x32_bf16 v[24:27], v[204:207], v[80:83], v[24:27]
	v_mfma_f32_16x16x32_bf16 v[20:23], v[196:199], v[88:91], v[20:23]
	v_mfma_f32_16x16x32_bf16 v[16:19], v[204:207], v[88:91], v[16:19]
	v_mfma_f32_16x16x32_bf16 v[12:15], v[200:203], v[180:183], v[12:15]
	v_mfma_f32_16x16x32_bf16 v[8:11], v[208:211], v[180:183], v[8:11]
	v_mfma_f32_16x16x32_bf16 v[4:7], v[200:203], v[188:191], v[4:7]
	v_mfma_f32_16x16x32_bf16 v[0:3], v[208:211], v[188:191], v[0:3]
	v_mfma_f32_16x16x32_bf16 v[142:145], v[200:203], v[84:87], v[28:31]
	v_mfma_f32_16x16x32_bf16 v[146:149], v[208:211], v[84:87], v[24:27]
	v_mfma_f32_16x16x32_bf16 v[150:153], v[200:203], v[92:95], v[20:23]
	v_mfma_f32_16x16x32_bf16 v[154:157], v[208:211], v[92:95], v[16:19]
	s_barrier
	s_nop 0
	ds_read_b128 v[16:19], v139
	ds_read_b128 v[20:23], v139 offset:1024
	ds_read_b128 v[176:179], v139 offset:2048
	ds_read_b128 v[180:183], v139 offset:3072
	ds_read_b128 v[24:27], v134 offset:32768
	ds_read_b128 v[28:31], v134 offset:33792
	ds_read_b128 v[184:187], v135 offset:32768
	ds_read_b128 v[188:191], v135 offset:33792
	ds_read_b128 v[192:195], v136 offset:32768
	ds_read_b128 v[196:199], v136 offset:33792
	ds_read_b128 v[200:203], v137 offset:32768
	ds_read_b128 v[204:207], v137 offset:33792
	s_waitcnt vmcnt(2)
	s_barrier
	s_waitcnt lgkmcnt(0)
	v_mfma_f32_16x16x32_bf16 v[80:83], v[16:19], v[24:27], v[124:127]
	v_mfma_f32_16x16x32_bf16 v[124:127], v[20:23], v[28:31], v[80:83]
	v_mfma_f32_16x16x32_bf16 v[80:83], v[176:179], v[24:27], v[120:123]
	v_mfma_f32_16x16x32_bf16 v[120:123], v[180:183], v[28:31], v[80:83]
	v_mfma_f32_16x16x32_bf16 v[80:83], v[16:19], v[184:187], v[116:119]
	v_mfma_f32_16x16x32_bf16 v[116:119], v[20:23], v[188:191], v[80:83]
	v_mfma_f32_16x16x32_bf16 v[80:83], v[176:179], v[184:187], v[112:115]
	v_mfma_f32_16x16x32_bf16 v[112:115], v[180:183], v[188:191], v[80:83]
	v_mfma_f32_16x16x32_bf16 v[80:83], v[16:19], v[192:195], v[108:111]
	v_mfma_f32_16x16x32_bf16 v[92:95], v[20:23], v[196:199], v[80:83]
	v_mfma_f32_16x16x32_bf16 v[80:83], v[176:179], v[192:195], v[104:107]
	v_mfma_f32_16x16x32_bf16 v[88:91], v[180:183], v[196:199], v[80:83]
	v_mfma_f32_16x16x32_bf16 v[80:83], v[16:19], v[200:203], v[100:103]
	v_mfma_f32_16x16x32_bf16 v[84:87], v[20:23], v[204:207], v[80:83]
	v_mfma_f32_16x16x32_bf16 v[80:83], v[176:179], v[200:203], v[96:99]
	v_mfma_f32_16x16x32_bf16 v[80:83], v[180:183], v[204:207], v[80:83]
	s_barrier
; #define LDA(dst, b, h)                                                                                               \
;   _Pragma("unroll") for (int m = 0; m < 4; ++m) _Pragma("unroll") for (int k = 0; k < 2; ++k) dst[m][k] =            \
;       *reinterpret_cast<const bf16x8*>(SA(b, h) + lds_byte(wr * 64 + m * 16 + fr, k * 32 + fq * 8))
; #define LDB(dst, b, h)                                                                                               \
;   _Pragma("unroll") for (int n = 0; n < 2; ++n) _Pragma("unroll") for (int k = 0; k < 2; ++k) dst[n][k] =            \
;       *reinterpret_cast<const bf16x8*>(SB(b, h) + lds_byte(wc * 32 + n * 16 + fr, k * 32 + fq * 8))
; #define WAIT_V(n) asm volatile("s_waitcnt vmcnt(" #n ")" ::: "memory")
; #define WAIT_L(n) asm volatile("s_waitcnt lgkmcnt(" #n ")" ::: "memory")
; #define BAR __builtin_amdgcn_s_barrier()
; template <int EPI>
; __device__ __forceinline__ void gemm_phase(const u16* __restrict__ A, const u16* __restrict__ Bt, const int K,
;                                            const int nN, char* shm, const EpiArgs& ea) {
;     ...
;       LDB(B0, 1, 0); LDA(At, 1, 0); WAIT_V(2); BAR; WAIT_L(0); MMA(0, 0, At, B0); BAR;
;       LDB(B1, 1, 1); WAIT_V(0); BAR; WAIT_L(0); MMA(0, 1, At, B1); BAR;
;       LDA(At, 1, 1); BAR; WAIT_L(0); MMA(1, 0, At, B0); MMA(1, 1, At, B1); BAR;
;     }
;     if (wr == 0) BAR;
	ds_read_b128 v[208:211], v140
	ds_read_b128 v[216:219], v140 offset:1024
	ds_read_b128 v[220:223], v140 offset:2048
	ds_read_b128 v[224:227], v140 offset:3072
	s_waitcnt vmcnt(0)
	s_barrier
	s_waitcnt lgkmcnt(0)
	v_mfma_f32_16x16x32_bf16 v[96:99], v[208:211], v[24:27], v[212:215]
	v_mfma_f32_16x16x32_bf16 v[24:27], v[220:223], v[24:27], v[162:165]
	v_mfma_f32_16x16x32_bf16 v[104:107], v[224:227], v[28:31], v[24:27]
	v_mfma_f32_16x16x32_bf16 v[24:27], v[208:211], v[184:187], v[166:169]
	v_mfma_f32_16x16x32_bf16 v[100:103], v[216:219], v[188:191], v[24:27]
	v_mfma_f32_16x16x32_bf16 v[24:27], v[220:223], v[184:187], v[170:173]
	v_mfma_f32_16x16x32_bf16 v[108:111], v[216:219], v[28:31], v[96:99]
	v_mfma_f32_16x16x32_bf16 v[96:99], v[224:227], v[188:191], v[24:27]
	v_mfma_f32_16x16x32_bf16 v[24:27], v[208:211], v[192:195], v[76:79]
	v_mfma_f32_16x16x32_bf16 v[76:79], v[216:219], v[196:199], v[24:27]
	v_mfma_f32_16x16x32_bf16 v[24:27], v[220:223], v[192:195], v[72:75]
	v_mfma_f32_16x16x32_bf16 v[72:75], v[224:227], v[196:199], v[24:27]
	v_mfma_f32_16x16x32_bf16 v[24:27], v[208:211], v[200:203], v[68:71]
	v_mfma_f32_16x16x32_bf16 v[68:71], v[216:219], v[204:207], v[24:27]
	v_mfma_f32_16x16x32_bf16 v[24:27], v[220:223], v[200:203], v[64:67]
	v_mfma_f32_16x16x32_bf16 v[64:67], v[224:227], v[204:207], v[24:27]
	s_barrier
	ds_read_b128 v[162:165], v134 offset:49152
	ds_read_b128 v[166:169], v134 offset:50176
	ds_read_b128 v[170:173], v135 offset:49152
	ds_read_b128 v[184:187], v135 offset:50176
	ds_read_b128 v[188:191], v136 offset:49152
	ds_read_b128 v[192:195], v136 offset:50176
	ds_read_b128 v[196:199], v137 offset:49152
	ds_read_b128 v[200:203], v137 offset:50176
	s_barrier
	s_waitcnt lgkmcnt(0)
	v_mfma_f32_16x16x32_bf16 v[24:27], v[16:19], v[162:165], v[60:63]
	v_mfma_f32_16x16x32_bf16 v[60:63], v[20:23], v[166:169], v[24:27]
	v_mfma_f32_16x16x32_bf16 v[24:27], v[176:179], v[162:165], v[56:59]
	v_mfma_f32_16x16x32_bf16 v[56:59], v[180:183], v[166:169], v[24:27]
	v_mfma_f32_16x16x32_bf16 v[24:27], v[16:19], v[170:173], v[52:55]
	v_mfma_f32_16x16x32_bf16 v[52:55], v[20:23], v[184:187], v[24:27]
	v_mfma_f32_16x16x32_bf16 v[24:27], v[176:179], v[170:173], v[48:51]
	v_mfma_f32_16x16x32_bf16 v[48:51], v[180:183], v[184:187], v[24:27]
	v_mfma_f32_16x16x32_bf16 v[24:27], v[16:19], v[188:191], v[44:47]
	v_mfma_f32_16x16x32_bf16 v[16:19], v[16:19], v[196:199], v[36:39]
	v_mfma_f32_16x16x32_bf16 v[28:31], v[20:23], v[192:195], v[24:27]
	v_mfma_f32_16x16x32_bf16 v[24:27], v[176:179], v[188:191], v[40:43]
	v_mfma_f32_16x16x32_bf16 v[20:23], v[20:23], v[200:203], v[16:19]
	v_mfma_f32_16x16x32_bf16 v[16:19], v[176:179], v[196:199], v[32:35]
	v_mfma_f32_16x16x32_bf16 v[24:27], v[180:183], v[192:195], v[24:27]
	v_mfma_f32_16x16x32_bf16 v[16:19], v[180:183], v[200:203], v[16:19]
	v_mfma_f32_16x16x32_bf16 v[32:35], v[208:211], v[162:165], v[142:145]
	v_mfma_f32_16x16x32_bf16 v[44:47], v[216:219], v[166:169], v[32:35]
	v_mfma_f32_16x16x32_bf16 v[32:35], v[220:223], v[162:165], v[146:149]
	v_mfma_f32_16x16x32_bf16 v[40:43], v[224:227], v[166:169], v[32:35]
	v_mfma_f32_16x16x32_bf16 v[32:35], v[208:211], v[170:173], v[150:153]
	v_mfma_f32_16x16x32_bf16 v[36:39], v[216:219], v[184:187], v[32:35]
	v_mfma_f32_16x16x32_bf16 v[32:35], v[220:223], v[170:173], v[154:157]
	v_mfma_f32_16x16x32_bf16 v[12:15], v[208:211], v[188:191], v[12:15]
	v_mfma_f32_16x16x32_bf16 v[8:11], v[220:223], v[188:191], v[8:11]
	v_mfma_f32_16x16x32_bf16 v[4:7], v[208:211], v[196:199], v[4:7]
	v_mfma_f32_16x16x32_bf16 v[0:3], v[220:223], v[196:199], v[0:3]
	v_mfma_f32_16x16x32_bf16 v[32:35], v[224:227], v[184:187], v[32:35]
	v_mfma_f32_16x16x32_bf16 v[12:15], v[216:219], v[192:195], v[12:15]
	v_mfma_f32_16x16x32_bf16 v[8:11], v[224:227], v[192:195], v[8:11]
	v_mfma_f32_16x16x32_bf16 v[4:7], v[216:219], v[200:203], v[4:7]
	v_mfma_f32_16x16x32_bf16 v[0:3], v[224:227], v[200:203], v[0:3]
	s_andn2_b64 vcc, exec, s[26:27]
	s_barrier
	s_cbranch_vccnz .LBB0_175
	s_barrier

; #define LDA(dst, b, h)                                                                                               \
;   _Pragma("unroll") for (int m = 0; m < 4; ++m) _Pragma("unroll") for (int k = 0; k < 2; ++k) dst[m][k] =            \
;       *reinterpret_cast<const bf16x8*>(SA(b, h) + lds_byte(wr * 64 + m * 16 + fr, k * 32 + fq * 8))
; #define LDB(dst, b, h)                                                                                               \
;   _Pragma("unroll") for (int n = 0; n < 2; ++n) _Pragma("unroll") for (int k = 0; k < 2; ++k) dst[n][k] =            \
;       *reinterpret_cast<const bf16x8*>(SB(b, h) + lds_byte(wc * 32 + n * 16 + fr, k * 32 + fq * 8))
; #define WAIT_V(n) asm volatile("s_waitcnt vmcnt(" #n ")" ::: "memory")
; #define WAIT_L(n) asm volatile("s_waitcnt lgkmcnt(" #n ")" ::: "memory")
; #define BAR __builtin_amdgcn_s_barrier()
; #define SCHED __builtin_amdgcn_sched_barrier(0)
; template <int EPI>
; __device__ __forceinline__ void gemm_phase(const u16* __restrict__ A, const u16* __restrict__ Bt, const int K,
;                                            const int nN, char* shm, const EpiArgs& ea) {
;     ...
;       LDB(B0, 0, 0); SCHED; LDA(At, 0, 0); STAGE(SA(1, 1), rA, brow + HALF, t + 1);
;       WAIT_V(10); WAIT_L(8); BAR; WAIT_L(0); MMA(0, 0, At, B0); BAR; SCHED;
;       LDB(B1, 0, 1); STAGE(SB(0, 0), rB, bcol, t + 2);
;       WAIT_V(10); BAR; WAIT_L(0); MMA(0, 1, At, B1); BAR;
;       LDA(At, 0, 1); STAGE(SA(0, 0), rA, brow, t + 2);
;       BAR; WAIT_L(0); MMA(1, 0, At, B0); BAR; SCHED;
;       STAGE(SB(0, 1), rB, bcol + HALF, t + 2);
;       WAIT_V(10); BAR; MMA(1, 1, At, B1); BAR;
.LBB0_231:
	ds_read_b128 v[130:133], v138
	ds_read_b128 v[146:149], v138 offset:1024
	ds_read_b128 v[150:153], v138 offset:2048
	ds_read_b128 v[154:157], v138 offset:3072
	s_add_i32 s78, s70, s75
	s_mov_b32 m0, s48
	s_add_i32 s26, s78, 0x4000
	ds_read_b128 v[162:165], v139
	ds_read_b128 v[166:169], v139 offset:1024
	ds_read_b128 v[170:173], v140
	ds_read_b128 v[176:179], v140 offset:1024
	ds_read_b128 v[180:183], v141
	ds_read_b128 v[184:187], v141 offset:1024
	ds_read_b128 v[188:191], v142
	ds_read_b128 v[192:195], v142 offset:1024
	buffer_load_dwordx4 v134, s[0:3], s26 offen lds
	s_add_i32 s26, s78, 0x6000
	s_mov_b32 m0, s49
	s_nop 0
	buffer_load_dwordx4 v134, s[0:3], s26 offen lds
	s_waitcnt vmcnt(10)
	s_waitcnt lgkmcnt(8)
	s_barrier
	s_waitcnt lgkmcnt(0)
	v_mfma_f32_16x16x32_bf16 v[124:127], v[130:133], v[162:165], v[124:127]
	v_mfma_f32_16x16x32_bf16 v[120:123], v[150:153], v[162:165], v[120:123]
	v_mfma_f32_16x16x32_bf16 v[116:119], v[130:133], v[170:173], v[116:119]
	v_mfma_f32_16x16x32_bf16 v[112:115], v[150:153], v[170:173], v[112:115]
	v_mfma_f32_16x16x32_bf16 v[108:111], v[130:133], v[180:183], v[108:111]
	v_mfma_f32_16x16x32_bf16 v[104:107], v[150:153], v[180:183], v[104:107]
	v_mfma_f32_16x16x32_bf16 v[100:103], v[130:133], v[188:191], v[100:103]
	v_mfma_f32_16x16x32_bf16 v[96:99], v[150:153], v[188:191], v[96:99]
	v_mfma_f32_16x16x32_bf16 v[124:127], v[146:149], v[166:169], v[124:127]
	v_mfma_f32_16x16x32_bf16 v[120:123], v[154:157], v[166:169], v[120:123]
	v_mfma_f32_16x16x32_bf16 v[116:119], v[146:149], v[176:179], v[116:119]
	v_mfma_f32_16x16x32_bf16 v[112:115], v[154:157], v[176:179], v[112:115]
	v_mfma_f32_16x16x32_bf16 v[108:111], v[146:149], v[184:187], v[108:111]
	v_mfma_f32_16x16x32_bf16 v[104:107], v[154:157], v[184:187], v[104:107]
	v_mfma_f32_16x16x32_bf16 v[100:103], v[146:149], v[192:195], v[100:103]
	v_mfma_f32_16x16x32_bf16 v[96:99], v[154:157], v[192:195], v[96:99]
	s_barrier
	s_add_i32 s79, s73, s75
	s_mov_b32 m0, s52
	s_add_i32 s80, s79, 0x8000
	s_mov_b32 s26, s2
	s_mov_b32 s27, s3
	ds_read_b128 v[196:199], v143
	ds_read_b128 v[200:203], v143 offset:1024
	ds_read_b128 v[204:207], v143 offset:2048
	ds_read_b128 v[208:211], v143 offset:3072
	buffer_load_dwordx4 v134, s[24:27], s80 offen lds
	s_add_i32 s80, s79, 0xa000
	s_mov_b32 m0, s53
	s_nop 0
	buffer_load_dwordx4 v134, s[24:27], s80 offen lds
	s_waitcnt vmcnt(10)
	s_barrier
	s_waitcnt lgkmcnt(0)
	v_mfma_f32_16x16x32_bf16 v[92:95], v[196:199], v[162:165], v[92:95]
	v_mfma_f32_16x16x32_bf16 v[88:91], v[204:207], v[162:165], v[88:91]
	v_mfma_f32_16x16x32_bf16 v[84:87], v[196:199], v[170:173], v[84:87]
	v_mfma_f32_16x16x32_bf16 v[80:83], v[204:207], v[170:173], v[80:83]
	v_mfma_f32_16x16x32_bf16 v[76:79], v[196:199], v[180:183], v[76:79]
	v_mfma_f32_16x16x32_bf16 v[72:75], v[204:207], v[180:183], v[72:75]
	v_mfma_f32_16x16x32_bf16 v[68:71], v[196:199], v[188:191], v[68:71]
	v_mfma_f32_16x16x32_bf16 v[64:67], v[204:207], v[188:191], v[64:67]
	v_mfma_f32_16x16x32_bf16 v[92:95], v[200:203], v[166:169], v[92:95]
	v_mfma_f32_16x16x32_bf16 v[88:91], v[208:211], v[166:169], v[88:91]
	v_mfma_f32_16x16x32_bf16 v[84:87], v[200:203], v[176:179], v[84:87]
	v_mfma_f32_16x16x32_bf16 v[80:83], v[208:211], v[176:179], v[80:83]
	v_mfma_f32_16x16x32_bf16 v[76:79], v[200:203], v[184:187], v[76:79]
	v_mfma_f32_16x16x32_bf16 v[72:75], v[208:211], v[184:187], v[72:75]
	v_mfma_f32_16x16x32_bf16 v[68:71], v[200:203], v[192:195], v[68:71]
	v_mfma_f32_16x16x32_bf16 v[64:67], v[208:211], v[192:195], v[64:67]
	s_add_i32 s80, s72, s75
	s_mov_b32 m0, s43
	s_add_i32 s81, s80, 0x8000
	s_barrier
	ds_read_b128 v[162:165], v139 offset:16384
	ds_read_b128 v[166:169], v139 offset:17408
	ds_read_b128 v[170:173], v140 offset:16384
	ds_read_b128 v[176:179], v140 offset:17408
	ds_read_b128 v[180:183], v141 offset:16384
	ds_read_b128 v[184:187], v141 offset:17408
	ds_read_b128 v[188:191], v142 offset:16384
	ds_read_b128 v[192:195], v142 offset:17408
	buffer_load_dwordx4 v134, s[0:3], s81 offen lds
	s_add_i32 s81, s80, 0xa000
	s_mov_b32 m0, s54
	s_nop 0
	buffer_load_dwordx4 v134, s[0:3], s81 offen lds
	s_barrier
	s_waitcnt lgkmcnt(0)
	v_mfma_f32_16x16x32_bf16 v[60:63], v[130:133], v[162:165], v[60:63]
	v_mfma_f32_16x16x32_bf16 v[56:59], v[150:153], v[162:165], v[56:59]
	v_mfma_f32_16x16x32_bf16 v[52:55], v[130:133], v[170:173], v[52:55]
	v_mfma_f32_16x16x32_bf16 v[48:51], v[150:153], v[170:173], v[48:51]
	v_mfma_f32_16x16x32_bf16 v[44:47], v[130:133], v[180:183], v[44:47]
	v_mfma_f32_16x16x32_bf16 v[40:43], v[150:153], v[180:183], v[40:43]
	v_mfma_f32_16x16x32_bf16 v[36:39], v[130:133], v[188:191], v[36:39]
	v_mfma_f32_16x16x32_bf16 v[32:35], v[150:153], v[188:191], v[32:35]
	v_mfma_f32_16x16x32_bf16 v[60:63], v[146:149], v[166:169], v[60:63]
	v_mfma_f32_16x16x32_bf16 v[56:59], v[154:157], v[166:169], v[56:59]
	v_mfma_f32_16x16x32_bf16 v[52:55], v[146:149], v[176:179], v[52:55]
	v_mfma_f32_16x16x32_bf16 v[48:51], v[154:157], v[176:179], v[48:51]
	v_mfma_f32_16x16x32_bf16 v[44:47], v[146:149], v[184:187], v[44:47]
	v_mfma_f32_16x16x32_bf16 v[40:43], v[154:157], v[184:187], v[40:43]
	v_mfma_f32_16x16x32_bf16 v[36:39], v[146:149], v[192:195], v[36:39]
	v_mfma_f32_16x16x32_bf16 v[32:35], v[154:157], v[192:195], v[32:35]
	s_barrier
	s_add_i32 s81, s71, s75
	s_mov_b32 m0, s55
	s_add_i32 s82, s81, 0x8000
	buffer_load_dwordx4 v134, s[24:27], s82 offen lds
	s_add_i32 s82, s81, 0xa000
	s_mov_b32 m0, s56
	s_nop 0
	buffer_load_dwordx4 v134, s[24:27], s82 offen lds
	s_waitcnt vmcnt(10)
	s_barrier
; #define LDA(dst, b, h)                                                                                               \
;   _Pragma("unroll") for (int m = 0; m < 4; ++m) _Pragma("unroll") for (int k = 0; k < 2; ++k) dst[m][k] =            \
;       *reinterpret_cast<const bf16x8*>(SA(b, h) + lds_byte(wr * 64 + m * 16 + fr, k * 32 + fq * 8))
; #define LDB(dst, b, h)                                                                                               \
;   _Pragma("unroll") for (int n = 0; n < 2; ++n) _Pragma("unroll") for (int k = 0; k < 2; ++k) dst[n][k] =            \
;       *reinterpret_cast<const bf16x8*>(SB(b, h) + lds_byte(wc * 32 + n * 16 + fr, k * 32 + fq * 8))
; #define WAIT_V(n) asm volatile("s_waitcnt vmcnt(" #n ")" ::: "memory")
; #define WAIT_L(n) asm volatile("s_waitcnt lgkmcnt(" #n ")" ::: "memory")
; #define BAR __builtin_amdgcn_s_barrier()
; #define SCHED __builtin_amdgcn_sched_barrier(0)
; template <int EPI>
; __device__ __forceinline__ void gemm_phase(const u16* __restrict__ A, const u16* __restrict__ Bt, const int K,
;                                            const int nN, char* shm, const EpiArgs& ea) {
;     ...
;       WAIT_V(10); BAR; MMA(1, 1, At, B1); BAR;
;       LDB(B0, 1, 0); SCHED; LDA(At, 1, 0); STAGE(SA(0, 1), rA, brow + HALF, t + 2);
;       WAIT_V(10); WAIT_L(8); BAR; WAIT_L(0); MMA(0, 0, At, B0); BAR; SCHED;
;       LDB(B1, 1, 1); STAGE(SB(1, 0), rB, bcol, t + 3);
;       WAIT_V(10); BAR; WAIT_L(0); MMA(0, 1, At, B1); BAR;
;       LDA(At, 1, 1); STAGE(SA(1, 0), rA, brow, t + 3);
;       BAR; WAIT_L(0); MMA(1, 0, At, B0); BAR; SCHED;
;       STAGE(SB(1, 1), rB, bcol + HALF, t + 3);
	v_mfma_f32_16x16x32_bf16 v[28:31], v[196:199], v[162:165], v[28:31]
	v_mfma_f32_16x16x32_bf16 v[24:27], v[204:207], v[162:165], v[24:27]
	v_mfma_f32_16x16x32_bf16 v[20:23], v[196:199], v[170:173], v[20:23]
	v_mfma_f32_16x16x32_bf16 v[16:19], v[204:207], v[170:173], v[16:19]
	v_mfma_f32_16x16x32_bf16 v[12:15], v[196:199], v[180:183], v[12:15]
	v_mfma_f32_16x16x32_bf16 v[8:11], v[204:207], v[180:183], v[8:11]
	v_mfma_f32_16x16x32_bf16 v[4:7], v[196:199], v[188:191], v[4:7]
	v_mfma_f32_16x16x32_bf16 v[0:3], v[204:207], v[188:191], v[0:3]
	v_mfma_f32_16x16x32_bf16 v[28:31], v[200:203], v[166:169], v[28:31]
	v_mfma_f32_16x16x32_bf16 v[24:27], v[208:211], v[166:169], v[24:27]
	v_mfma_f32_16x16x32_bf16 v[20:23], v[200:203], v[176:179], v[20:23]
	v_mfma_f32_16x16x32_bf16 v[16:19], v[208:211], v[176:179], v[16:19]
	v_mfma_f32_16x16x32_bf16 v[12:15], v[200:203], v[184:187], v[12:15]
	v_mfma_f32_16x16x32_bf16 v[8:11], v[208:211], v[184:187], v[8:11]
	v_mfma_f32_16x16x32_bf16 v[4:7], v[200:203], v[192:195], v[4:7]
	v_mfma_f32_16x16x32_bf16 v[0:3], v[208:211], v[192:195], v[0:3]
	s_barrier
	ds_read_b128 v[130:133], v144
	ds_read_b128 v[146:149], v144 offset:1024
	ds_read_b128 v[150:153], v144 offset:2048
	ds_read_b128 v[154:157], v144 offset:3072
	s_mov_b32 m0, s57
	s_add_i32 s82, s78, 0x8000
	ds_read_b128 v[162:165], v139 offset:32768
	ds_read_b128 v[166:169], v139 offset:33792
	ds_read_b128 v[170:173], v140 offset:32768
	ds_read_b128 v[176:179], v140 offset:33792
	ds_read_b128 v[180:183], v141 offset:32768
	ds_read_b128 v[184:187], v141 offset:33792
	ds_read_b128 v[188:191], v142 offset:32768
	ds_read_b128 v[192:195], v142 offset:33792
	buffer_load_dwordx4 v134, s[0:3], s82 offen lds
	s_add_i32 s78, s78, 0xa000
	s_mov_b32 m0, s58
	s_nop 0
	buffer_load_dwordx4 v134, s[0:3], s78 offen lds
	s_waitcnt vmcnt(10)
	s_waitcnt lgkmcnt(8)
	s_barrier
	s_waitcnt lgkmcnt(0)
	v_mfma_f32_16x16x32_bf16 v[124:127], v[130:133], v[162:165], v[124:127]
	v_mfma_f32_16x16x32_bf16 v[120:123], v[150:153], v[162:165], v[120:123]
	v_mfma_f32_16x16x32_bf16 v[116:119], v[130:133], v[170:173], v[116:119]
	v_mfma_f32_16x16x32_bf16 v[112:115], v[150:153], v[170:173], v[112:115]
	v_mfma_f32_16x16x32_bf16 v[108:111], v[130:133], v[180:183], v[108:111]
	v_mfma_f32_16x16x32_bf16 v[104:107], v[150:153], v[180:183], v[104:107]
	v_mfma_f32_16x16x32_bf16 v[100:103], v[130:133], v[188:191], v[100:103]
	v_mfma_f32_16x16x32_bf16 v[96:99], v[150:153], v[188:191], v[96:99]
	v_mfma_f32_16x16x32_bf16 v[124:127], v[146:149], v[166:169], v[124:127]
	v_mfma_f32_16x16x32_bf16 v[120:123], v[154:157], v[166:169], v[120:123]
	v_mfma_f32_16x16x32_bf16 v[116:119], v[146:149], v[176:179], v[116:119]
	v_mfma_f32_16x16x32_bf16 v[112:115], v[154:157], v[176:179], v[112:115]
	v_mfma_f32_16x16x32_bf16 v[108:111], v[146:149], v[184:187], v[108:111]
	v_mfma_f32_16x16x32_bf16 v[104:107], v[154:157], v[184:187], v[104:107]
	v_mfma_f32_16x16x32_bf16 v[100:103], v[146:149], v[192:195], v[100:103]
	v_mfma_f32_16x16x32_bf16 v[96:99], v[154:157], v[192:195], v[96:99]
	s_barrier
	s_mov_b32 m0, s59
	s_add_i32 s78, s79, 0xc000
	ds_read_b128 v[196:199], v145
	ds_read_b128 v[200:203], v145 offset:1024
	ds_read_b128 v[204:207], v145 offset:2048
	ds_read_b128 v[208:211], v145 offset:3072
	buffer_load_dwordx4 v134, s[24:27], s78 offen lds
	s_add_i32 s79, s79, 0xe000
	s_mov_b32 m0, s60
	s_nop 0
	buffer_load_dwordx4 v134, s[24:27], s79 offen lds
	s_waitcnt vmcnt(10)
	s_barrier
	s_waitcnt lgkmcnt(0)
	v_mfma_f32_16x16x32_bf16 v[92:95], v[196:199], v[162:165], v[92:95]
	v_mfma_f32_16x16x32_bf16 v[88:91], v[204:207], v[162:165], v[88:91]
	v_mfma_f32_16x16x32_bf16 v[84:87], v[196:199], v[170:173], v[84:87]
	v_mfma_f32_16x16x32_bf16 v[80:83], v[204:207], v[170:173], v[80:83]
	v_mfma_f32_16x16x32_bf16 v[76:79], v[196:199], v[180:183], v[76:79]
	v_mfma_f32_16x16x32_bf16 v[72:75], v[204:207], v[180:183], v[72:75]
	v_mfma_f32_16x16x32_bf16 v[68:71], v[196:199], v[188:191], v[68:71]
	v_mfma_f32_16x16x32_bf16 v[64:67], v[204:207], v[188:191], v[64:67]
	v_mfma_f32_16x16x32_bf16 v[92:95], v[200:203], v[166:169], v[92:95]
	v_mfma_f32_16x16x32_bf16 v[88:91], v[208:211], v[166:169], v[88:91]
	v_mfma_f32_16x16x32_bf16 v[84:87], v[200:203], v[176:179], v[84:87]
	v_mfma_f32_16x16x32_bf16 v[80:83], v[208:211], v[176:179], v[80:83]
	v_mfma_f32_16x16x32_bf16 v[76:79], v[200:203], v[184:187], v[76:79]
	v_mfma_f32_16x16x32_bf16 v[72:75], v[208:211], v[184:187], v[72:75]
	v_mfma_f32_16x16x32_bf16 v[68:71], v[200:203], v[192:195], v[68:71]
	v_mfma_f32_16x16x32_bf16 v[64:67], v[208:211], v[192:195], v[64:67]
	s_mov_b32 m0, s61
	s_add_i32 s78, s80, 0xc000
	s_barrier
	ds_read_b128 v[162:165], v139 offset:49152
	ds_read_b128 v[166:169], v139 offset:50176
	ds_read_b128 v[170:173], v140 offset:49152
	ds_read_b128 v[176:179], v140 offset:50176
	ds_read_b128 v[180:183], v141 offset:49152
	ds_read_b128 v[184:187], v141 offset:50176
	ds_read_b128 v[188:191], v142 offset:49152
	ds_read_b128 v[192:195], v142 offset:50176
	buffer_load_dwordx4 v134, s[0:3], s78 offen lds
	s_add_i32 s80, s80, 0xe000
	s_mov_b32 m0, s62
	s_nop 0
	buffer_load_dwordx4 v134, s[0:3], s80 offen lds
	s_barrier
; #define LDA(dst, b, h)                                                                                               \
;   _Pragma("unroll") for (int m = 0; m < 4; ++m) _Pragma("unroll") for (int k = 0; k < 2; ++k) dst[m][k] =            \
;       *reinterpret_cast<const bf16x8*>(SA(b, h) + lds_byte(wr * 64 + m * 16 + fr, k * 32 + fq * 8))
; #define LDB(dst, b, h)                                                                                               \
;   _Pragma("unroll") for (int n = 0; n < 2; ++n) _Pragma("unroll") for (int k = 0; k < 2; ++k) dst[n][k] =            \
;       *reinterpret_cast<const bf16x8*>(SB(b, h) + lds_byte(wc * 32 + n * 16 + fr, k * 32 + fq * 8))
; #define WAIT_V(n) asm volatile("s_waitcnt vmcnt(" #n ")" ::: "memory")
; #define WAIT_L(n) asm volatile("s_waitcnt lgkmcnt(" #n ")" ::: "memory")
; #define BAR __builtin_amdgcn_s_barrier()
; #define SCHED __builtin_amdgcn_sched_barrier(0)
; template <int EPI>
; __device__ __forceinline__ void gemm_phase(const u16* __restrict__ A, const u16* __restrict__ Bt, const int K,
;                                            const int nN, char* shm, const EpiArgs& ea) {
;     ...
;       WAIT_V(10); BAR; WAIT_L(0); MMA(0, 1, At, B1); BAR;
;       LDA(At, 1, 1); STAGE(SA(1, 0), rA, brow, t + 3);
;       BAR; WAIT_L(0); MMA(1, 0, At, B0); BAR; SCHED;
;       STAGE(SB(1, 1), rB, bcol + HALF, t + 3);
;       WAIT_V(10); BAR; MMA(1, 1, At, B1); BAR;
;     }
;     ...
;       LDB(B0, 0, 0); LDA(At, 0, 0); STAGE(SA(1, 1), rA, brow + HALF, nt - 1);
;       WAIT_V(10); BAR; WAIT_L(0); MMA(0, 0, At, B0); BAR;
;       LDB(B1, 0, 1); WAIT_V(8); BAR; WAIT_L(0); MMA(0, 1, At, B1); BAR;
;       LDA(At, 0, 1); WAIT_V(4); BAR; WAIT_L(0); MMA(1, 0, At, B0); MMA(1, 1, At, B1); BAR;
	s_waitcnt lgkmcnt(0)
	v_mfma_f32_16x16x32_bf16 v[60:63], v[130:133], v[162:165], v[60:63]
	v_mfma_f32_16x16x32_bf16 v[56:59], v[150:153], v[162:165], v[56:59]
	v_mfma_f32_16x16x32_bf16 v[52:55], v[130:133], v[170:173], v[52:55]
	v_mfma_f32_16x16x32_bf16 v[48:51], v[150:153], v[170:173], v[48:51]
	v_mfma_f32_16x16x32_bf16 v[44:47], v[130:133], v[180:183], v[44:47]
	v_mfma_f32_16x16x32_bf16 v[40:43], v[150:153], v[180:183], v[40:43]
	v_mfma_f32_16x16x32_bf16 v[36:39], v[130:133], v[188:191], v[36:39]
	v_mfma_f32_16x16x32_bf16 v[32:35], v[150:153], v[188:191], v[32:35]
	v_mfma_f32_16x16x32_bf16 v[60:63], v[146:149], v[166:169], v[60:63]
	v_mfma_f32_16x16x32_bf16 v[56:59], v[154:157], v[166:169], v[56:59]
	v_mfma_f32_16x16x32_bf16 v[52:55], v[146:149], v[176:179], v[52:55]
	v_mfma_f32_16x16x32_bf16 v[48:51], v[154:157], v[176:179], v[48:51]
	v_mfma_f32_16x16x32_bf16 v[44:47], v[146:149], v[184:187], v[44:47]
	v_mfma_f32_16x16x32_bf16 v[40:43], v[154:157], v[184:187], v[40:43]
	v_mfma_f32_16x16x32_bf16 v[36:39], v[146:149], v[192:195], v[36:39]
	v_mfma_f32_16x16x32_bf16 v[32:35], v[154:157], v[192:195], v[32:35]
	s_barrier
	s_mov_b32 m0, s63
	s_add_i32 s78, s81, 0xc000
	buffer_load_dwordx4 v134, s[24:27], s78 offen lds
	s_add_i32 s81, s81, 0xe000
	s_mov_b32 m0, s64
	s_nop 0
	buffer_load_dwordx4 v134, s[24:27], s81 offen lds
	s_waitcnt vmcnt(10)
	s_barrier
	v_mfma_f32_16x16x32_bf16 v[28:31], v[196:199], v[162:165], v[28:31]
	v_mfma_f32_16x16x32_bf16 v[24:27], v[204:207], v[162:165], v[24:27]
	v_mfma_f32_16x16x32_bf16 v[20:23], v[196:199], v[170:173], v[20:23]
	v_mfma_f32_16x16x32_bf16 v[16:19], v[204:207], v[170:173], v[16:19]
	v_mfma_f32_16x16x32_bf16 v[12:15], v[196:199], v[180:183], v[12:15]
	v_mfma_f32_16x16x32_bf16 v[8:11], v[204:207], v[180:183], v[8:11]
	v_mfma_f32_16x16x32_bf16 v[4:7], v[196:199], v[188:191], v[4:7]
	v_mfma_f32_16x16x32_bf16 v[0:3], v[204:207], v[188:191], v[0:3]
	v_mfma_f32_16x16x32_bf16 v[28:31], v[200:203], v[166:169], v[28:31]
	v_mfma_f32_16x16x32_bf16 v[24:27], v[208:211], v[166:169], v[24:27]
	v_mfma_f32_16x16x32_bf16 v[20:23], v[200:203], v[176:179], v[20:23]
	v_mfma_f32_16x16x32_bf16 v[16:19], v[208:211], v[176:179], v[16:19]
	v_mfma_f32_16x16x32_bf16 v[12:15], v[200:203], v[184:187], v[12:15]
	v_mfma_f32_16x16x32_bf16 v[8:11], v[208:211], v[184:187], v[8:11]
	v_mfma_f32_16x16x32_bf16 v[4:7], v[200:203], v[192:195], v[4:7]
	v_mfma_f32_16x16x32_bf16 v[0:3], v[208:211], v[192:195], v[0:3]
	s_add_i32 s74, s74, 2
	s_add_i32 s75, s75, 0x8000
	s_cmpk_lt_u32 s74, 0x54
	s_barrier
	s_cbranch_scc1 .LBB0_231
	s_mov_b32 m0, s48
	s_add_i32 s26, s70, 0x15c000
	ds_read_b128 v[130:133], v138
	ds_read_b128 v[146:149], v138 offset:1024
	ds_read_b128 v[150:153], v138 offset:2048
	ds_read_b128 v[154:157], v138 offset:3072
	ds_read_b128 v[162:165], v139
	ds_read_b128 v[166:169], v139 offset:1024
	ds_read_b128 v[170:173], v140
	ds_read_b128 v[176:179], v140 offset:1024
	ds_read_b128 v[180:183], v141
	ds_read_b128 v[184:187], v141 offset:1024
	ds_read_b128 v[188:191], v142
	ds_read_b128 v[192:195], v142 offset:1024
	buffer_load_dwordx4 v134, s[0:3], s26 offen lds
	s_add_i32 s70, s70, 0x15e000
	s_mov_b32 m0, s49
	s_nop 0
	buffer_load_dwordx4 v134, s[0:3], s70 offen lds
	s_waitcnt vmcnt(10)
	s_barrier
	s_waitcnt lgkmcnt(0)
	v_mfma_f32_16x16x32_bf16 v[124:127], v[130:133], v[162:165], v[124:127]
	v_mfma_f32_16x16x32_bf16 v[116:119], v[130:133], v[170:173], v[116:119]
	v_mfma_f32_16x16x32_bf16 v[112:115], v[150:153], v[170:173], v[112:115]
	v_mfma_f32_16x16x32_bf16 v[100:103], v[130:133], v[188:191], v[100:103]
	v_mfma_f32_16x16x32_bf16 v[96:99], v[150:153], v[188:191], v[96:99]
	v_mfma_f32_16x16x32_bf16 v[124:127], v[146:149], v[166:169], v[124:127]
	v_mfma_f32_16x16x32_bf16 v[120:123], v[150:153], v[162:165], v[120:123]
	v_mfma_f32_16x16x32_bf16 v[116:119], v[146:149], v[176:179], v[116:119]
	v_mfma_f32_16x16x32_bf16 v[112:115], v[154:157], v[176:179], v[112:115]
	v_mfma_f32_16x16x32_bf16 v[108:111], v[130:133], v[180:183], v[108:111]
	v_mfma_f32_16x16x32_bf16 v[104:107], v[150:153], v[180:183], v[104:107]
	v_mfma_f32_16x16x32_bf16 v[100:103], v[146:149], v[192:195], v[100:103]
	v_mfma_f32_16x16x32_bf16 v[96:99], v[154:157], v[192:195], v[96:99]
	v_mfma_f32_16x16x32_bf16 v[196:199], v[154:157], v[166:169], v[120:123]
	v_mfma_f32_16x16x32_bf16 v[200:203], v[146:149], v[184:187], v[108:111]
	v_mfma_f32_16x16x32_bf16 v[204:207], v[154:157], v[184:187], v[104:107]
	s_barrier
	s_nop 0
	ds_read_b128 v[104:107], v143
	ds_read_b128 v[108:111], v143 offset:1024
	ds_read_b128 v[120:123], v143 offset:2048
	ds_read_b128 v[208:211], v143 offset:3072
	s_waitcnt vmcnt(8)
	s_barrier
	s_waitcnt lgkmcnt(0)
	v_mfma_f32_16x16x32_bf16 v[84:87], v[104:107], v[170:173], v[84:87]
	v_mfma_f32_16x16x32_bf16 v[80:83], v[120:123], v[170:173], v[80:83]
	v_mfma_f32_16x16x32_bf16 v[68:71], v[104:107], v[188:191], v[68:71]
	v_mfma_f32_16x16x32_bf16 v[92:95], v[104:107], v[162:165], v[92:95]
	v_mfma_f32_16x16x32_bf16 v[88:91], v[120:123], v[162:165], v[88:91]
	v_mfma_f32_16x16x32_bf16 v[84:87], v[108:111], v[176:179], v[84:87]
	v_mfma_f32_16x16x32_bf16 v[80:83], v[208:211], v[176:179], v[80:83]
	v_mfma_f32_16x16x32_bf16 v[76:79], v[104:107], v[180:183], v[76:79]
	v_mfma_f32_16x16x32_bf16 v[72:75], v[120:123], v[180:183], v[72:75]
	v_mfma_f32_16x16x32_bf16 v[68:71], v[108:111], v[192:195], v[68:71]
	v_mfma_f32_16x16x32_bf16 v[64:67], v[120:123], v[188:191], v[64:67]
	v_mfma_f32_16x16x32_bf16 v[212:215], v[108:111], v[166:169], v[92:95]
	v_mfma_f32_16x16x32_bf16 v[162:165], v[208:211], v[166:169], v[88:91]
	v_mfma_f32_16x16x32_bf16 v[166:169], v[108:111], v[184:187], v[76:79]
	v_mfma_f32_16x16x32_bf16 v[170:173], v[208:211], v[184:187], v[72:75]
	v_mfma_f32_16x16x32_bf16 v[176:179], v[208:211], v[192:195], v[64:67]
	s_barrier
; #define LDA(dst, b, h)                                                                                               \
;   _Pragma("unroll") for (int m = 0; m < 4; ++m) _Pragma("unroll") for (int k = 0; k < 2; ++k) dst[m][k] =            \
;       *reinterpret_cast<const bf16x8*>(SA(b, h) + lds_byte(wr * 64 + m * 16 + fr, k * 32 + fq * 8))
; #define LDB(dst, b, h)                                                                                               \
;   _Pragma("unroll") for (int n = 0; n < 2; ++n) _Pragma("unroll") for (int k = 0; k < 2; ++k) dst[n][k] =            \
;       *reinterpret_cast<const bf16x8*>(SB(b, h) + lds_byte(wc * 32 + n * 16 + fr, k * 32 + fq * 8))
; #define WAIT_V(n) asm volatile("s_waitcnt vmcnt(" #n ")" ::: "memory")
; #define WAIT_L(n) asm volatile("s_waitcnt lgkmcnt(" #n ")" ::: "memory")
; #define BAR __builtin_amdgcn_s_barrier()
; template <int EPI>
; __device__ __forceinline__ void gemm_phase(const u16* __restrict__ A, const u16* __restrict__ Bt, const int K,
;                                            const int nN, char* shm, const EpiArgs& ea) {
;     ...
;       LDB(B1, 0, 1); WAIT_V(8); BAR; WAIT_L(0); MMA(0, 1, At, B1); BAR;
;       LDA(At, 0, 1); WAIT_V(4); BAR; WAIT_L(0); MMA(1, 0, At, B0); MMA(1, 1, At, B1); BAR;
;     }
;     {
;       LDB(B0, 1, 0); LDA(At, 1, 0); WAIT_V(2); BAR; WAIT_L(0); MMA(0, 0, At, B0); BAR;
	s_nop 0
	ds_read_b128 v[64:67], v139 offset:16384
	ds_read_b128 v[72:75], v139 offset:17408
	ds_read_b128 v[76:79], v140 offset:16384
	ds_read_b128 v[88:91], v140 offset:17408
	ds_read_b128 v[92:95], v141 offset:16384
	ds_read_b128 v[180:183], v141 offset:17408
	ds_read_b128 v[184:187], v142 offset:16384
	ds_read_b128 v[188:191], v142 offset:17408
	s_waitcnt vmcnt(4)
	s_barrier
	s_waitcnt lgkmcnt(0)
	v_mfma_f32_16x16x32_bf16 v[60:63], v[130:133], v[64:67], v[60:63]
	v_mfma_f32_16x16x32_bf16 v[52:55], v[130:133], v[76:79], v[52:55]
	v_mfma_f32_16x16x32_bf16 v[48:51], v[150:153], v[76:79], v[48:51]
	v_mfma_f32_16x16x32_bf16 v[36:39], v[130:133], v[184:187], v[36:39]
	v_mfma_f32_16x16x32_bf16 v[32:35], v[150:153], v[184:187], v[32:35]
	v_mfma_f32_16x16x32_bf16 v[60:63], v[146:149], v[72:75], v[60:63]
	v_mfma_f32_16x16x32_bf16 v[56:59], v[150:153], v[64:67], v[56:59]
	v_mfma_f32_16x16x32_bf16 v[52:55], v[146:149], v[88:91], v[52:55]
	v_mfma_f32_16x16x32_bf16 v[48:51], v[154:157], v[88:91], v[48:51]
	v_mfma_f32_16x16x32_bf16 v[44:47], v[130:133], v[92:95], v[44:47]
	v_mfma_f32_16x16x32_bf16 v[40:43], v[150:153], v[92:95], v[40:43]
	v_mfma_f32_16x16x32_bf16 v[36:39], v[146:149], v[188:191], v[36:39]
	v_mfma_f32_16x16x32_bf16 v[32:35], v[154:157], v[188:191], v[32:35]
	v_mfma_f32_16x16x32_bf16 v[192:195], v[154:157], v[72:75], v[56:59]
	v_mfma_f32_16x16x32_bf16 v[216:219], v[146:149], v[180:183], v[44:47]
	v_mfma_f32_16x16x32_bf16 v[220:223], v[154:157], v[180:183], v[40:43]
	v_mfma_f32_16x16x32_bf16 v[20:23], v[104:107], v[76:79], v[20:23]
	v_mfma_f32_16x16x32_bf16 v[16:19], v[120:123], v[76:79], v[16:19]
	v_mfma_f32_16x16x32_bf16 v[4:7], v[104:107], v[184:187], v[4:7]
	v_mfma_f32_16x16x32_bf16 v[28:31], v[104:107], v[64:67], v[28:31]
	v_mfma_f32_16x16x32_bf16 v[24:27], v[120:123], v[64:67], v[24:27]
	v_mfma_f32_16x16x32_bf16 v[20:23], v[108:111], v[88:91], v[20:23]
	v_mfma_f32_16x16x32_bf16 v[16:19], v[208:211], v[88:91], v[16:19]
	v_mfma_f32_16x16x32_bf16 v[12:15], v[104:107], v[92:95], v[12:15]
	v_mfma_f32_16x16x32_bf16 v[8:11], v[120:123], v[92:95], v[8:11]
	v_mfma_f32_16x16x32_bf16 v[4:7], v[108:111], v[188:191], v[4:7]
	v_mfma_f32_16x16x32_bf16 v[0:3], v[120:123], v[184:187], v[0:3]
	v_mfma_f32_16x16x32_bf16 v[130:133], v[108:111], v[72:75], v[28:31]
	v_mfma_f32_16x16x32_bf16 v[146:149], v[208:211], v[72:75], v[24:27]
	v_mfma_f32_16x16x32_bf16 v[150:153], v[108:111], v[180:183], v[12:15]
	v_mfma_f32_16x16x32_bf16 v[154:157], v[208:211], v[180:183], v[8:11]
	v_mfma_f32_16x16x32_bf16 v[180:183], v[208:211], v[188:191], v[0:3]
	s_barrier
	s_nop 0
	ds_read_b128 v[0:3], v144
	ds_read_b128 v[8:11], v144 offset:1024
	ds_read_b128 v[12:15], v144 offset:2048
	ds_read_b128 v[184:187], v144 offset:3072
	ds_read_b128 v[24:27], v139 offset:32768
	ds_read_b128 v[28:31], v139 offset:33792
	ds_read_b128 v[40:43], v140 offset:32768
	ds_read_b128 v[44:47], v140 offset:33792
	ds_read_b128 v[56:59], v141 offset:32768
	ds_read_b128 v[64:67], v141 offset:33792
	ds_read_b128 v[188:191], v142 offset:32768
	ds_read_b128 v[208:211], v142 offset:33792
	s_waitcnt vmcnt(2)
	s_barrier
	s_waitcnt lgkmcnt(0)
	v_mfma_f32_16x16x32_bf16 v[72:75], v[0:3], v[24:27], v[124:127]
	v_mfma_f32_16x16x32_bf16 v[120:123], v[8:11], v[28:31], v[72:75]
	v_mfma_f32_16x16x32_bf16 v[72:75], v[12:15], v[24:27], v[196:199]
	v_mfma_f32_16x16x32_bf16 v[124:127], v[184:187], v[28:31], v[72:75]
	v_mfma_f32_16x16x32_bf16 v[72:75], v[0:3], v[40:43], v[116:119]
	v_mfma_f32_16x16x32_bf16 v[104:107], v[8:11], v[44:47], v[72:75]
	v_mfma_f32_16x16x32_bf16 v[72:75], v[12:15], v[40:43], v[112:115]
	v_mfma_f32_16x16x32_bf16 v[108:111], v[184:187], v[44:47], v[72:75]
	v_mfma_f32_16x16x32_bf16 v[72:75], v[0:3], v[56:59], v[200:203]
	v_mfma_f32_16x16x32_bf16 v[88:91], v[8:11], v[64:67], v[72:75]
	v_mfma_f32_16x16x32_bf16 v[72:75], v[12:15], v[56:59], v[204:207]
	v_mfma_f32_16x16x32_bf16 v[92:95], v[184:187], v[64:67], v[72:75]
	v_mfma_f32_16x16x32_bf16 v[72:75], v[0:3], v[188:191], v[100:103]
	v_mfma_f32_16x16x32_bf16 v[76:79], v[12:15], v[188:191], v[96:99]
	v_mfma_f32_16x16x32_bf16 v[72:75], v[8:11], v[208:211], v[72:75]
	v_mfma_f32_16x16x32_bf16 v[76:79], v[184:187], v[208:211], v[76:79]
	s_barrier
; #define LDA(dst, b, h)                                                                                               \
;   _Pragma("unroll") for (int m = 0; m < 4; ++m) _Pragma("unroll") for (int k = 0; k < 2; ++k) dst[m][k] =            \
;       *reinterpret_cast<const bf16x8*>(SA(b, h) + lds_byte(wr * 64 + m * 16 + fr, k * 32 + fq * 8))
; #define LDB(dst, b, h)                                                                                               \
;   _Pragma("unroll") for (int n = 0; n < 2; ++n) _Pragma("unroll") for (int k = 0; k < 2; ++k) dst[n][k] =            \
;       *reinterpret_cast<const bf16x8*>(SB(b, h) + lds_byte(wc * 32 + n * 16 + fr, k * 32 + fq * 8))
; #define WAIT_V(n) asm volatile("s_waitcnt vmcnt(" #n ")" ::: "memory")
; #define WAIT_L(n) asm volatile("s_waitcnt lgkmcnt(" #n ")" ::: "memory")
; #define BAR __builtin_amdgcn_s_barrier()
; template <int EPI>
; __device__ __forceinline__ void gemm_phase(const u16* __restrict__ A, const u16* __restrict__ Bt, const int K,
;                                            const int nN, char* shm, const EpiArgs& ea) {
;     ...
;       LDB(B0, 1, 0); LDA(At, 1, 0); WAIT_V(2); BAR; WAIT_L(0); MMA(0, 0, At, B0); BAR;
;       LDB(B1, 1, 1); WAIT_V(0); BAR; WAIT_L(0); MMA(0, 1, At, B1); BAR;
;       LDA(At, 1, 1); BAR; WAIT_L(0); MMA(1, 0, At, B0); MMA(1, 1, At, B1); BAR;
;     }
;     if (wr == 0) BAR;
	ds_read_b128 v[196:199], v145
	ds_read_b128 v[200:203], v145 offset:1024
	ds_read_b128 v[204:207], v145 offset:2048
	ds_read_b128 v[224:227], v145 offset:3072
	s_waitcnt vmcnt(0)
	s_barrier
	s_waitcnt lgkmcnt(0)
	v_mfma_f32_16x16x32_bf16 v[96:99], v[196:199], v[24:27], v[212:215]
	v_mfma_f32_16x16x32_bf16 v[24:27], v[204:207], v[24:27], v[162:165]
	v_mfma_f32_16x16x32_bf16 v[116:119], v[224:227], v[28:31], v[24:27]
	v_mfma_f32_16x16x32_bf16 v[24:27], v[196:199], v[40:43], v[84:87]
	v_mfma_f32_16x16x32_bf16 v[112:115], v[200:203], v[28:31], v[96:99]
	v_mfma_f32_16x16x32_bf16 v[96:99], v[200:203], v[44:47], v[24:27]
	v_mfma_f32_16x16x32_bf16 v[24:27], v[204:207], v[40:43], v[80:83]
	v_mfma_f32_16x16x32_bf16 v[100:103], v[224:227], v[44:47], v[24:27]
	v_mfma_f32_16x16x32_bf16 v[24:27], v[196:199], v[56:59], v[166:169]
	v_mfma_f32_16x16x32_bf16 v[80:83], v[200:203], v[64:67], v[24:27]
	v_mfma_f32_16x16x32_bf16 v[24:27], v[204:207], v[56:59], v[170:173]
	v_mfma_f32_16x16x32_bf16 v[84:87], v[224:227], v[64:67], v[24:27]
	v_mfma_f32_16x16x32_bf16 v[24:27], v[196:199], v[188:191], v[68:71]
	v_mfma_f32_16x16x32_bf16 v[64:67], v[200:203], v[208:211], v[24:27]
	v_mfma_f32_16x16x32_bf16 v[24:27], v[204:207], v[188:191], v[176:179]
	v_mfma_f32_16x16x32_bf16 v[68:71], v[224:227], v[208:211], v[24:27]
	s_barrier
	ds_read_b128 v[162:165], v139 offset:49152
	ds_read_b128 v[166:169], v139 offset:50176
	ds_read_b128 v[170:173], v140 offset:49152
	ds_read_b128 v[176:179], v140 offset:50176
	ds_read_b128 v[188:191], v141 offset:49152
	ds_read_b128 v[208:211], v141 offset:50176
	ds_read_b128 v[212:215], v142 offset:49152
	ds_read_b128 v[228:231], v142 offset:50176
	s_barrier
	s_waitcnt lgkmcnt(0)
	v_mfma_f32_16x16x32_bf16 v[24:27], v[0:3], v[162:165], v[60:63]
	v_mfma_f32_16x16x32_bf16 v[56:59], v[8:11], v[166:169], v[24:27]
	v_mfma_f32_16x16x32_bf16 v[24:27], v[12:15], v[162:165], v[192:195]
	v_mfma_f32_16x16x32_bf16 v[60:63], v[184:187], v[166:169], v[24:27]
	v_mfma_f32_16x16x32_bf16 v[24:27], v[0:3], v[170:173], v[52:55]
	v_mfma_f32_16x16x32_bf16 v[40:43], v[8:11], v[176:179], v[24:27]
	v_mfma_f32_16x16x32_bf16 v[24:27], v[12:15], v[170:173], v[48:51]
	v_mfma_f32_16x16x32_bf16 v[44:47], v[184:187], v[176:179], v[24:27]
	v_mfma_f32_16x16x32_bf16 v[24:27], v[0:3], v[188:191], v[216:219]
	v_mfma_f32_16x16x32_bf16 v[0:3], v[0:3], v[212:215], v[36:39]
	v_mfma_f32_16x16x32_bf16 v[24:27], v[8:11], v[208:211], v[24:27]
	v_mfma_f32_16x16x32_bf16 v[28:31], v[12:15], v[188:191], v[220:223]
	v_mfma_f32_16x16x32_bf16 v[8:11], v[8:11], v[228:231], v[0:3]
	v_mfma_f32_16x16x32_bf16 v[0:3], v[12:15], v[212:215], v[32:35]
	v_mfma_f32_16x16x32_bf16 v[28:31], v[184:187], v[208:211], v[28:31]
	v_mfma_f32_16x16x32_bf16 v[12:15], v[184:187], v[228:231], v[0:3]
	v_mfma_f32_16x16x32_bf16 v[0:3], v[196:199], v[162:165], v[130:133]
	v_mfma_f32_16x16x32_bf16 v[48:51], v[200:203], v[166:169], v[0:3]
	v_mfma_f32_16x16x32_bf16 v[0:3], v[204:207], v[162:165], v[146:149]
	v_mfma_f32_16x16x32_bf16 v[52:55], v[224:227], v[166:169], v[0:3]
	v_mfma_f32_16x16x32_bf16 v[0:3], v[196:199], v[170:173], v[20:23]
	v_mfma_f32_16x16x32_bf16 v[32:35], v[200:203], v[176:179], v[0:3]
	v_mfma_f32_16x16x32_bf16 v[0:3], v[204:207], v[170:173], v[16:19]
	v_mfma_f32_16x16x32_bf16 v[36:39], v[224:227], v[176:179], v[0:3]
	v_mfma_f32_16x16x32_bf16 v[0:3], v[196:199], v[188:191], v[150:153]
	v_mfma_f32_16x16x32_bf16 v[16:19], v[200:203], v[208:211], v[0:3]
	v_mfma_f32_16x16x32_bf16 v[0:3], v[204:207], v[188:191], v[154:157]
	v_mfma_f32_16x16x32_bf16 v[20:23], v[224:227], v[208:211], v[0:3]
	v_mfma_f32_16x16x32_bf16 v[0:3], v[196:199], v[212:215], v[4:7]
	v_mfma_f32_16x16x32_bf16 v[4:7], v[204:207], v[212:215], v[180:183]
	v_mfma_f32_16x16x32_bf16 v[0:3], v[200:203], v[228:231], v[0:3]
	v_mfma_f32_16x16x32_bf16 v[4:7], v[224:227], v[228:231], v[4:7]
	s_andn2_b64 vcc, exec, s[30:31]
	s_barrier
	s_cbranch_vccnz .LBB0_234
	s_barrier

; #define LDA(dst, b, h)                                                                                               \
;   _Pragma("unroll") for (int m = 0; m < 4; ++m) _Pragma("unroll") for (int k = 0; k < 2; ++k) dst[m][k] =            \
;       *reinterpret_cast<const bf16x8*>(SA(b, h) + lds_byte(wr * 64 + m * 16 + fr, k * 32 + fq * 8))
; #define LDB(dst, b, h)                                                                                               \
;   _Pragma("unroll") for (int n = 0; n < 2; ++n) _Pragma("unroll") for (int k = 0; k < 2; ++k) dst[n][k] =            \
;       *reinterpret_cast<const bf16x8*>(SB(b, h) + lds_byte(wc * 32 + n * 16 + fr, k * 32 + fq * 8))
; #define WAIT_V(n) asm volatile("s_waitcnt vmcnt(" #n ")" ::: "memory")
; #define WAIT_L(n) asm volatile("s_waitcnt lgkmcnt(" #n ")" ::: "memory")
; #define BAR __builtin_amdgcn_s_barrier()
; #define SCHED __builtin_amdgcn_sched_barrier(0)
; template <int EPI>
; __device__ __forceinline__ void gemm_phase(const u16* __restrict__ A, const u16* __restrict__ Bt, const int K,
;                                            const int nN, char* shm, const EpiArgs& ea) {
;     ...
;       LDB(B0, 0, 0); SCHED; LDA(At, 0, 0); STAGE(SA(1, 1), rA, brow + HALF, t + 1);
;       WAIT_V(10); WAIT_L(8); BAR; WAIT_L(0); MMA(0, 0, At, B0); BAR; SCHED;
;       LDB(B1, 0, 1); STAGE(SB(0, 0), rB, bcol, t + 2);
;       WAIT_V(10); BAR; WAIT_L(0); MMA(0, 1, At, B1); BAR;
;       LDA(At, 0, 1); STAGE(SA(0, 0), rA, brow, t + 2);
;       BAR; WAIT_L(0); MMA(1, 0, At, B0); BAR; SCHED;
;       STAGE(SB(0, 1), rB, bcol + HALF, t + 2);
;       WAIT_V(10); BAR; MMA(1, 1, At, B1); BAR;
.LBB0_306:
	ds_read_b128 v[128:131], v168
	ds_read_b128 v[132:135], v168 offset:1024
	ds_read_b128 v[136:139], v168 offset:2048
	ds_read_b128 v[140:143], v168 offset:3072
	s_add_i32 s79, s72, s78
	s_mov_b32 m0, s52
	s_add_i32 s26, s79, 0x4000
	ds_read_b128 v[144:147], v169
	ds_read_b128 v[148:151], v169 offset:1024
	ds_read_b128 v[152:155], v170
	ds_read_b128 v[156:159], v170 offset:1024
	ds_read_b128 v[180:183], v171
	ds_read_b128 v[184:187], v171 offset:1024
	ds_read_b128 v[188:191], v172
	ds_read_b128 v[192:195], v172 offset:1024
	buffer_load_dwordx4 v161, s[0:3], s26 offen lds
	s_add_i32 s26, s79, 0x6000
	s_mov_b32 m0, s53
	s_nop 0
	buffer_load_dwordx4 v161, s[0:3], s26 offen lds
	s_waitcnt vmcnt(10)
	s_waitcnt lgkmcnt(8)
	s_barrier
	s_waitcnt lgkmcnt(0)
	v_mfma_f32_16x16x32_bf16 v[124:127], v[128:131], v[144:147], v[124:127]
	v_mfma_f32_16x16x32_bf16 v[120:123], v[136:139], v[144:147], v[120:123]
	v_mfma_f32_16x16x32_bf16 v[116:119], v[128:131], v[152:155], v[116:119]
	v_mfma_f32_16x16x32_bf16 v[112:115], v[136:139], v[152:155], v[112:115]
	v_mfma_f32_16x16x32_bf16 v[108:111], v[128:131], v[180:183], v[108:111]
	v_mfma_f32_16x16x32_bf16 v[104:107], v[136:139], v[180:183], v[104:107]
	v_mfma_f32_16x16x32_bf16 v[100:103], v[128:131], v[188:191], v[100:103]
	v_mfma_f32_16x16x32_bf16 v[96:99], v[136:139], v[188:191], v[96:99]
	v_mfma_f32_16x16x32_bf16 v[124:127], v[132:135], v[148:151], v[124:127]
	v_mfma_f32_16x16x32_bf16 v[120:123], v[140:143], v[148:151], v[120:123]
	v_mfma_f32_16x16x32_bf16 v[116:119], v[132:135], v[156:159], v[116:119]
	v_mfma_f32_16x16x32_bf16 v[112:115], v[140:143], v[156:159], v[112:115]
	v_mfma_f32_16x16x32_bf16 v[108:111], v[132:135], v[184:187], v[108:111]
	v_mfma_f32_16x16x32_bf16 v[104:107], v[140:143], v[184:187], v[104:107]
	v_mfma_f32_16x16x32_bf16 v[100:103], v[132:135], v[192:195], v[100:103]
	v_mfma_f32_16x16x32_bf16 v[96:99], v[140:143], v[192:195], v[96:99]
	s_barrier
	s_add_i32 s80, s74, s78
	s_mov_b32 m0, s54
	s_add_i32 s81, s80, 0x8000
	s_mov_b32 s26, s2
	s_mov_b32 s27, s3
	ds_read_b128 v[196:199], v173
	ds_read_b128 v[200:203], v173 offset:1024
	ds_read_b128 v[204:207], v173 offset:2048
	ds_read_b128 v[208:211], v173 offset:3072
	buffer_load_dwordx4 v161, s[24:27], s81 offen lds
	s_add_i32 s81, s80, 0xa000
	s_mov_b32 m0, s55
	s_nop 0
	buffer_load_dwordx4 v161, s[24:27], s81 offen lds
	s_waitcnt vmcnt(10)
	s_barrier
	s_waitcnt lgkmcnt(0)
	v_mfma_f32_16x16x32_bf16 v[92:95], v[196:199], v[144:147], v[92:95]
	v_mfma_f32_16x16x32_bf16 v[88:91], v[204:207], v[144:147], v[88:91]
	v_mfma_f32_16x16x32_bf16 v[84:87], v[196:199], v[152:155], v[84:87]
	v_mfma_f32_16x16x32_bf16 v[80:83], v[204:207], v[152:155], v[80:83]
	v_mfma_f32_16x16x32_bf16 v[76:79], v[196:199], v[180:183], v[76:79]
	v_mfma_f32_16x16x32_bf16 v[72:75], v[204:207], v[180:183], v[72:75]
	v_mfma_f32_16x16x32_bf16 v[68:71], v[196:199], v[188:191], v[68:71]
	v_mfma_f32_16x16x32_bf16 v[64:67], v[204:207], v[188:191], v[64:67]
	v_mfma_f32_16x16x32_bf16 v[92:95], v[200:203], v[148:151], v[92:95]
	v_mfma_f32_16x16x32_bf16 v[88:91], v[208:211], v[148:151], v[88:91]
	v_mfma_f32_16x16x32_bf16 v[84:87], v[200:203], v[156:159], v[84:87]
	v_mfma_f32_16x16x32_bf16 v[80:83], v[208:211], v[156:159], v[80:83]
	v_mfma_f32_16x16x32_bf16 v[76:79], v[200:203], v[184:187], v[76:79]
	v_mfma_f32_16x16x32_bf16 v[72:75], v[208:211], v[184:187], v[72:75]
	v_mfma_f32_16x16x32_bf16 v[68:71], v[200:203], v[192:195], v[68:71]
	v_mfma_f32_16x16x32_bf16 v[64:67], v[208:211], v[192:195], v[64:67]
	s_add_i32 s81, s73, s78
	s_mov_b32 m0, s49
	s_add_i32 s82, s81, 0x8000
	s_barrier
	ds_read_b128 v[144:147], v169 offset:16384
	ds_read_b128 v[148:151], v169 offset:17408
	ds_read_b128 v[152:155], v170 offset:16384
	ds_read_b128 v[156:159], v170 offset:17408
	ds_read_b128 v[180:183], v171 offset:16384
	ds_read_b128 v[184:187], v171 offset:17408
	ds_read_b128 v[188:191], v172 offset:16384
	ds_read_b128 v[192:195], v172 offset:17408
	buffer_load_dwordx4 v161, s[0:3], s82 offen lds
	s_add_i32 s82, s81, 0xa000
	s_mov_b32 m0, s56
	s_nop 0
	buffer_load_dwordx4 v161, s[0:3], s82 offen lds
	s_barrier
	s_waitcnt lgkmcnt(0)
	v_mfma_f32_16x16x32_bf16 v[60:63], v[128:131], v[144:147], v[60:63]
	v_mfma_f32_16x16x32_bf16 v[56:59], v[136:139], v[144:147], v[56:59]
	v_mfma_f32_16x16x32_bf16 v[52:55], v[128:131], v[152:155], v[52:55]
	v_mfma_f32_16x16x32_bf16 v[48:51], v[136:139], v[152:155], v[48:51]
	v_mfma_f32_16x16x32_bf16 v[44:47], v[128:131], v[180:183], v[44:47]
	v_mfma_f32_16x16x32_bf16 v[40:43], v[136:139], v[180:183], v[40:43]
	v_mfma_f32_16x16x32_bf16 v[36:39], v[128:131], v[188:191], v[36:39]
	v_mfma_f32_16x16x32_bf16 v[32:35], v[136:139], v[188:191], v[32:35]
	v_mfma_f32_16x16x32_bf16 v[60:63], v[132:135], v[148:151], v[60:63]
	v_mfma_f32_16x16x32_bf16 v[56:59], v[140:143], v[148:151], v[56:59]
	v_mfma_f32_16x16x32_bf16 v[52:55], v[132:135], v[156:159], v[52:55]
	v_mfma_f32_16x16x32_bf16 v[48:51], v[140:143], v[156:159], v[48:51]
	v_mfma_f32_16x16x32_bf16 v[44:47], v[132:135], v[184:187], v[44:47]
	v_mfma_f32_16x16x32_bf16 v[40:43], v[140:143], v[184:187], v[40:43]
	v_mfma_f32_16x16x32_bf16 v[36:39], v[132:135], v[192:195], v[36:39]
	v_mfma_f32_16x16x32_bf16 v[32:35], v[140:143], v[192:195], v[32:35]
	s_barrier
	s_add_i32 s82, s43, s78
	s_mov_b32 m0, s57
	s_add_i32 s83, s82, 0x8000
	buffer_load_dwordx4 v161, s[24:27], s83 offen lds
	s_add_i32 s83, s82, 0xa000
	s_mov_b32 m0, s58
	s_nop 0
	buffer_load_dwordx4 v161, s[24:27], s83 offen lds
	s_waitcnt vmcnt(10)
	s_barrier
; #define LDA(dst, b, h)                                                                                               \
;   _Pragma("unroll") for (int m = 0; m < 4; ++m) _Pragma("unroll") for (int k = 0; k < 2; ++k) dst[m][k] =            \
;       *reinterpret_cast<const bf16x8*>(SA(b, h) + lds_byte(wr * 64 + m * 16 + fr, k * 32 + fq * 8))
; #define LDB(dst, b, h)                                                                                               \
;   _Pragma("unroll") for (int n = 0; n < 2; ++n) _Pragma("unroll") for (int k = 0; k < 2; ++k) dst[n][k] =            \
;       *reinterpret_cast<const bf16x8*>(SB(b, h) + lds_byte(wc * 32 + n * 16 + fr, k * 32 + fq * 8))
; #define WAIT_V(n) asm volatile("s_waitcnt vmcnt(" #n ")" ::: "memory")
; #define WAIT_L(n) asm volatile("s_waitcnt lgkmcnt(" #n ")" ::: "memory")
; #define BAR __builtin_amdgcn_s_barrier()
; #define SCHED __builtin_amdgcn_sched_barrier(0)
; template <int EPI>
; __device__ __forceinline__ void gemm_phase(const u16* __restrict__ A, const u16* __restrict__ Bt, const int K,
;                                            const int nN, char* shm, const EpiArgs& ea) {
;     ...
;       WAIT_V(10); BAR; MMA(1, 1, At, B1); BAR;
;       LDB(B0, 1, 0); SCHED; LDA(At, 1, 0); STAGE(SA(0, 1), rA, brow + HALF, t + 2);
;       WAIT_V(10); WAIT_L(8); BAR; WAIT_L(0); MMA(0, 0, At, B0); BAR; SCHED;
;       LDB(B1, 1, 1); STAGE(SB(1, 0), rB, bcol, t + 3);
;       WAIT_V(10); BAR; WAIT_L(0); MMA(0, 1, At, B1); BAR;
;       LDA(At, 1, 1); STAGE(SA(1, 0), rA, brow, t + 3);
	v_mfma_f32_16x16x32_bf16 v[28:31], v[196:199], v[144:147], v[28:31]
	v_mfma_f32_16x16x32_bf16 v[24:27], v[204:207], v[144:147], v[24:27]
	v_mfma_f32_16x16x32_bf16 v[20:23], v[196:199], v[152:155], v[20:23]
	v_mfma_f32_16x16x32_bf16 v[16:19], v[204:207], v[152:155], v[16:19]
	v_mfma_f32_16x16x32_bf16 v[12:15], v[196:199], v[180:183], v[12:15]
	v_mfma_f32_16x16x32_bf16 v[8:11], v[204:207], v[180:183], v[8:11]
	v_mfma_f32_16x16x32_bf16 v[4:7], v[196:199], v[188:191], v[4:7]
	v_mfma_f32_16x16x32_bf16 v[0:3], v[204:207], v[188:191], v[0:3]
	v_mfma_f32_16x16x32_bf16 v[28:31], v[200:203], v[148:151], v[28:31]
	v_mfma_f32_16x16x32_bf16 v[24:27], v[208:211], v[148:151], v[24:27]
	v_mfma_f32_16x16x32_bf16 v[20:23], v[200:203], v[156:159], v[20:23]
	v_mfma_f32_16x16x32_bf16 v[16:19], v[208:211], v[156:159], v[16:19]
	v_mfma_f32_16x16x32_bf16 v[12:15], v[200:203], v[184:187], v[12:15]
	v_mfma_f32_16x16x32_bf16 v[8:11], v[208:211], v[184:187], v[8:11]
	v_mfma_f32_16x16x32_bf16 v[4:7], v[200:203], v[192:195], v[4:7]
	v_mfma_f32_16x16x32_bf16 v[0:3], v[208:211], v[192:195], v[0:3]
	s_barrier
	ds_read_b128 v[128:131], v176
	ds_read_b128 v[132:135], v176 offset:1024
	ds_read_b128 v[136:139], v176 offset:2048
	ds_read_b128 v[140:143], v176 offset:3072
	s_mov_b32 m0, s59
	s_add_i32 s83, s79, 0x8000
	ds_read_b128 v[144:147], v169 offset:32768
	ds_read_b128 v[148:151], v169 offset:33792
	ds_read_b128 v[152:155], v170 offset:32768
	ds_read_b128 v[156:159], v170 offset:33792
	ds_read_b128 v[180:183], v171 offset:32768
	ds_read_b128 v[184:187], v171 offset:33792
	ds_read_b128 v[188:191], v172 offset:32768
	ds_read_b128 v[192:195], v172 offset:33792
	buffer_load_dwordx4 v161, s[0:3], s83 offen lds
	s_add_i32 s79, s79, 0xa000
	s_mov_b32 m0, s60
	s_nop 0
	buffer_load_dwordx4 v161, s[0:3], s79 offen lds
	s_waitcnt vmcnt(10)
	s_waitcnt lgkmcnt(8)
	s_barrier
	s_waitcnt lgkmcnt(0)
	v_mfma_f32_16x16x32_bf16 v[124:127], v[128:131], v[144:147], v[124:127]
	v_mfma_f32_16x16x32_bf16 v[120:123], v[136:139], v[144:147], v[120:123]
	v_mfma_f32_16x16x32_bf16 v[116:119], v[128:131], v[152:155], v[116:119]
	v_mfma_f32_16x16x32_bf16 v[112:115], v[136:139], v[152:155], v[112:115]
	v_mfma_f32_16x16x32_bf16 v[108:111], v[128:131], v[180:183], v[108:111]
	v_mfma_f32_16x16x32_bf16 v[104:107], v[136:139], v[180:183], v[104:107]
	v_mfma_f32_16x16x32_bf16 v[100:103], v[128:131], v[188:191], v[100:103]
	v_mfma_f32_16x16x32_bf16 v[96:99], v[136:139], v[188:191], v[96:99]
	v_mfma_f32_16x16x32_bf16 v[124:127], v[132:135], v[148:151], v[124:127]
	v_mfma_f32_16x16x32_bf16 v[120:123], v[140:143], v[148:151], v[120:123]
	v_mfma_f32_16x16x32_bf16 v[116:119], v[132:135], v[156:159], v[116:119]
	v_mfma_f32_16x16x32_bf16 v[112:115], v[140:143], v[156:159], v[112:115]
	v_mfma_f32_16x16x32_bf16 v[108:111], v[132:135], v[184:187], v[108:111]
	v_mfma_f32_16x16x32_bf16 v[104:107], v[140:143], v[184:187], v[104:107]
	v_mfma_f32_16x16x32_bf16 v[100:103], v[132:135], v[192:195], v[100:103]
	v_mfma_f32_16x16x32_bf16 v[96:99], v[140:143], v[192:195], v[96:99]
	s_barrier
	s_mov_b32 m0, s61
	s_add_i32 s79, s80, 0xc000
	ds_read_b128 v[196:199], v177
	ds_read_b128 v[200:203], v177 offset:1024
	ds_read_b128 v[204:207], v177 offset:2048
	ds_read_b128 v[208:211], v177 offset:3072
	buffer_load_dwordx4 v161, s[24:27], s79 offen lds
	s_add_i32 s80, s80, 0xe000
	s_mov_b32 m0, s62
	s_nop 0
	buffer_load_dwordx4 v161, s[24:27], s80 offen lds
	s_waitcnt vmcnt(10)
	s_barrier
	s_waitcnt lgkmcnt(0)
	v_mfma_f32_16x16x32_bf16 v[92:95], v[196:199], v[144:147], v[92:95]
	v_mfma_f32_16x16x32_bf16 v[88:91], v[204:207], v[144:147], v[88:91]
	v_mfma_f32_16x16x32_bf16 v[84:87], v[196:199], v[152:155], v[84:87]
	v_mfma_f32_16x16x32_bf16 v[80:83], v[204:207], v[152:155], v[80:83]
	v_mfma_f32_16x16x32_bf16 v[76:79], v[196:199], v[180:183], v[76:79]
	v_mfma_f32_16x16x32_bf16 v[72:75], v[204:207], v[180:183], v[72:75]
	v_mfma_f32_16x16x32_bf16 v[68:71], v[196:199], v[188:191], v[68:71]
	v_mfma_f32_16x16x32_bf16 v[64:67], v[204:207], v[188:191], v[64:67]
	v_mfma_f32_16x16x32_bf16 v[92:95], v[200:203], v[148:151], v[92:95]
	v_mfma_f32_16x16x32_bf16 v[88:91], v[208:211], v[148:151], v[88:91]
	v_mfma_f32_16x16x32_bf16 v[84:87], v[200:203], v[156:159], v[84:87]
	v_mfma_f32_16x16x32_bf16 v[80:83], v[208:211], v[156:159], v[80:83]
	v_mfma_f32_16x16x32_bf16 v[76:79], v[200:203], v[184:187], v[76:79]
	v_mfma_f32_16x16x32_bf16 v[72:75], v[208:211], v[184:187], v[72:75]
	v_mfma_f32_16x16x32_bf16 v[68:71], v[200:203], v[192:195], v[68:71]
	v_mfma_f32_16x16x32_bf16 v[64:67], v[208:211], v[192:195], v[64:67]
	s_mov_b32 m0, s63
	s_add_i32 s79, s81, 0xc000
	s_barrier
; #define LDA(dst, b, h)                                                                                               \
;   _Pragma("unroll") for (int m = 0; m < 4; ++m) _Pragma("unroll") for (int k = 0; k < 2; ++k) dst[m][k] =            \
;       *reinterpret_cast<const bf16x8*>(SA(b, h) + lds_byte(wr * 64 + m * 16 + fr, k * 32 + fq * 8))
; #define LDB(dst, b, h)                                                                                               \
;   _Pragma("unroll") for (int n = 0; n < 2; ++n) _Pragma("unroll") for (int k = 0; k < 2; ++k) dst[n][k] =            \
;       *reinterpret_cast<const bf16x8*>(SB(b, h) + lds_byte(wc * 32 + n * 16 + fr, k * 32 + fq * 8))
; #define WAIT_V(n) asm volatile("s_waitcnt vmcnt(" #n ")" ::: "memory")
; #define WAIT_L(n) asm volatile("s_waitcnt lgkmcnt(" #n ")" ::: "memory")
; #define BAR __builtin_amdgcn_s_barrier()
; #define SCHED __builtin_amdgcn_sched_barrier(0)
; template <int EPI>
; __device__ __forceinline__ void gemm_phase(const u16* __restrict__ A, const u16* __restrict__ Bt, const int K,
;                                            const int nN, char* shm, const EpiArgs& ea) {
;     ...
;       LDB(B1, 1, 1); STAGE(SB(1, 0), rB, bcol, t + 3);
;       WAIT_V(10); BAR; WAIT_L(0); MMA(0, 1, At, B1); BAR;
;       LDA(At, 1, 1); STAGE(SA(1, 0), rA, brow, t + 3);
;       BAR; WAIT_L(0); MMA(1, 0, At, B0); BAR; SCHED;
;       STAGE(SB(1, 1), rB, bcol + HALF, t + 3);
;       WAIT_V(10); BAR; MMA(1, 1, At, B1); BAR;
;     }
;     float eC = 0.f, eB = 0.f;
;     float2 eS = make_float2(0.f, 0.f);
;     if (EPI == EPI_IN || EPI == EPI_SWIGLU_LN) {
;       if (wr == 0) {
;         eC = ea.c1[bcol + tid];
;         eS = *(const float2*)(ea.st_in + (size_t)(brow + tid) * 2);
;       } else {
;         eC = ea.c2[bcol + tid - 256];
;         if (EPI == EPI_IN) eB = ea.bias[bcol + tid - 256];
;       }
;     }
	ds_read_b128 v[144:147], v169 offset:49152
	ds_read_b128 v[148:151], v169 offset:50176
	ds_read_b128 v[152:155], v170 offset:49152
	ds_read_b128 v[156:159], v170 offset:50176
	ds_read_b128 v[180:183], v171 offset:49152
	ds_read_b128 v[184:187], v171 offset:50176
	ds_read_b128 v[188:191], v172 offset:49152
	ds_read_b128 v[192:195], v172 offset:50176
	buffer_load_dwordx4 v161, s[0:3], s79 offen lds
	s_add_i32 s81, s81, 0xe000
	s_mov_b32 m0, s64
	s_nop 0
	buffer_load_dwordx4 v161, s[0:3], s81 offen lds
	s_barrier
	s_waitcnt lgkmcnt(0)
	v_mfma_f32_16x16x32_bf16 v[60:63], v[128:131], v[144:147], v[60:63]
	v_mfma_f32_16x16x32_bf16 v[56:59], v[136:139], v[144:147], v[56:59]
	v_mfma_f32_16x16x32_bf16 v[52:55], v[128:131], v[152:155], v[52:55]
	v_mfma_f32_16x16x32_bf16 v[48:51], v[136:139], v[152:155], v[48:51]
	v_mfma_f32_16x16x32_bf16 v[44:47], v[128:131], v[180:183], v[44:47]
	v_mfma_f32_16x16x32_bf16 v[40:43], v[136:139], v[180:183], v[40:43]
	v_mfma_f32_16x16x32_bf16 v[36:39], v[128:131], v[188:191], v[36:39]
	v_mfma_f32_16x16x32_bf16 v[32:35], v[136:139], v[188:191], v[32:35]
	v_mfma_f32_16x16x32_bf16 v[60:63], v[132:135], v[148:151], v[60:63]
	v_mfma_f32_16x16x32_bf16 v[56:59], v[140:143], v[148:151], v[56:59]
	v_mfma_f32_16x16x32_bf16 v[52:55], v[132:135], v[156:159], v[52:55]
	v_mfma_f32_16x16x32_bf16 v[48:51], v[140:143], v[156:159], v[48:51]
	v_mfma_f32_16x16x32_bf16 v[44:47], v[132:135], v[184:187], v[44:47]
	v_mfma_f32_16x16x32_bf16 v[40:43], v[140:143], v[184:187], v[40:43]
	v_mfma_f32_16x16x32_bf16 v[36:39], v[132:135], v[192:195], v[36:39]
	v_mfma_f32_16x16x32_bf16 v[32:35], v[140:143], v[192:195], v[32:35]
	s_barrier
	s_mov_b32 m0, s65
	s_add_i32 s79, s82, 0xc000
	buffer_load_dwordx4 v161, s[24:27], s79 offen lds
	s_add_i32 s82, s82, 0xe000
	s_mov_b32 m0, s66
	s_nop 0
	buffer_load_dwordx4 v161, s[24:27], s82 offen lds
	s_waitcnt vmcnt(10)
	s_barrier
	v_mfma_f32_16x16x32_bf16 v[28:31], v[196:199], v[144:147], v[28:31]
	v_mfma_f32_16x16x32_bf16 v[24:27], v[204:207], v[144:147], v[24:27]
	v_mfma_f32_16x16x32_bf16 v[20:23], v[196:199], v[152:155], v[20:23]
	v_mfma_f32_16x16x32_bf16 v[16:19], v[204:207], v[152:155], v[16:19]
	v_mfma_f32_16x16x32_bf16 v[12:15], v[196:199], v[180:183], v[12:15]
	v_mfma_f32_16x16x32_bf16 v[8:11], v[204:207], v[180:183], v[8:11]
	v_mfma_f32_16x16x32_bf16 v[4:7], v[196:199], v[188:191], v[4:7]
	v_mfma_f32_16x16x32_bf16 v[0:3], v[204:207], v[188:191], v[0:3]
	v_mfma_f32_16x16x32_bf16 v[28:31], v[200:203], v[148:151], v[28:31]
	v_mfma_f32_16x16x32_bf16 v[24:27], v[208:211], v[148:151], v[24:27]
	v_mfma_f32_16x16x32_bf16 v[20:23], v[200:203], v[156:159], v[20:23]
	v_mfma_f32_16x16x32_bf16 v[16:19], v[208:211], v[156:159], v[16:19]
	v_mfma_f32_16x16x32_bf16 v[12:15], v[200:203], v[184:187], v[12:15]
	v_mfma_f32_16x16x32_bf16 v[8:11], v[208:211], v[184:187], v[8:11]
	v_mfma_f32_16x16x32_bf16 v[4:7], v[200:203], v[192:195], v[4:7]
	v_mfma_f32_16x16x32_bf16 v[0:3], v[208:211], v[192:195], v[0:3]
	s_add_i32 s75, s75, 2
	s_add_i32 s78, s78, 0x8000
	s_cmp_lt_u32 s75, 28
	s_barrier
	s_cbranch_scc1 .LBB0_306
	s_mov_b64 s[26:27], -1
	s_and_b64 vcc, exec, s[38:39]
	s_cbranch_vccz .LBB0_309
	s_ashr_i32 s43, s42, 31
	v_lshl_add_u64 v[128:129], v[174:175], 0, s[42:43]
	v_lshl_add_u64 v[128:129], v[128:129], 2, s[50:51]
	global_load_dword v150, v[128:129], off offset:-1024
	v_add_u32_e32 v128, s42, v163
	v_ashrrev_i32_e32 v129, 31, v128
	v_lshl_add_u64 v[128:129], v[128:129], 2, s[18:19]
	s_mov_b64 s[26:27], 0

; #define LDA(dst, b, h)                                                                                               \
;   _Pragma("unroll") for (int m = 0; m < 4; ++m) _Pragma("unroll") for (int k = 0; k < 2; ++k) dst[m][k] =            \
;       *reinterpret_cast<const bf16x8*>(SA(b, h) + lds_byte(wr * 64 + m * 16 + fr, k * 32 + fq * 8))
; #define LDB(dst, b, h)                                                                                               \
;   _Pragma("unroll") for (int n = 0; n < 2; ++n) _Pragma("unroll") for (int k = 0; k < 2; ++k) dst[n][k] =            \
;       *reinterpret_cast<const bf16x8*>(SB(b, h) + lds_byte(wc * 32 + n * 16 + fr, k * 32 + fq * 8))
; #define WAIT_V(n) asm volatile("s_waitcnt vmcnt(" #n ")" ::: "memory")
; #define WAIT_L(n) asm volatile("s_waitcnt lgkmcnt(" #n ")" ::: "memory")
; #define BAR __builtin_amdgcn_s_barrier()
; template <int EPI>
; __device__ __forceinline__ void gemm_phase(const u16* __restrict__ A, const u16* __restrict__ Bt, const int K,
;                                            const int nN, char* shm, const EpiArgs& ea) {
;     ...
;         eS = *(const float2*)(ea.st_in + (size_t)(brow + tid) * 2);
;       } else {
;         eC = ea.c2[bcol + tid - 256];
;         if (EPI == EPI_IN) eB = ea.bias[bcol + tid - 256];
;       }
;     }
;     {
;       LDB(B0, 0, 0); LDA(At, 0, 0); STAGE(SA(1, 1), rA, brow + HALF, nt - 1);
;       WAIT_V(10); BAR; WAIT_L(0); MMA(0, 0, At, B0); BAR;
;       LDB(B1, 0, 1); WAIT_V(8); BAR; WAIT_L(0); MMA(0, 1, At, B1); BAR;
;       LDA(At, 0, 1); WAIT_V(4); BAR; WAIT_L(0); MMA(1, 0, At, B0); MMA(1, 1, At, B1); BAR;
;     }
.LBB0_311:
	s_mov_b32 m0, s52
	s_add_i32 s26, s72, 0x7c000
	global_load_dword v151, v[128:129], off
	ds_read_b128 v[128:131], v168
	ds_read_b128 v[132:135], v168 offset:1024
	ds_read_b128 v[136:139], v168 offset:2048
	ds_read_b128 v[140:143], v168 offset:3072
	ds_read_b128 v[144:147], v169
	ds_read_b128 v[152:155], v169 offset:1024
	ds_read_b128 v[156:159], v170
	ds_read_b128 v[180:183], v170 offset:1024
	ds_read_b128 v[184:187], v171
	ds_read_b128 v[188:191], v171 offset:1024
	ds_read_b128 v[192:195], v172
	ds_read_b128 v[196:199], v172 offset:1024
	buffer_load_dwordx4 v161, s[0:3], s26 offen lds
	s_add_i32 s72, s72, 0x7e000
	s_mov_b32 m0, s53
	s_nop 0
	buffer_load_dwordx4 v161, s[0:3], s72 offen lds
	s_waitcnt vmcnt(10)
	s_barrier
	s_waitcnt lgkmcnt(0)
	v_mfma_f32_16x16x32_bf16 v[124:127], v[128:131], v[144:147], v[124:127]
	v_mfma_f32_16x16x32_bf16 v[120:123], v[136:139], v[144:147], v[120:123]
	v_mfma_f32_16x16x32_bf16 v[116:119], v[128:131], v[156:159], v[116:119]
	v_mfma_f32_16x16x32_bf16 v[112:115], v[136:139], v[156:159], v[112:115]
	v_mfma_f32_16x16x32_bf16 v[108:111], v[128:131], v[184:187], v[108:111]
	v_mfma_f32_16x16x32_bf16 v[104:107], v[136:139], v[184:187], v[104:107]
	v_mfma_f32_16x16x32_bf16 v[100:103], v[128:131], v[192:195], v[100:103]
	v_mfma_f32_16x16x32_bf16 v[96:99], v[136:139], v[192:195], v[96:99]
	v_mfma_f32_16x16x32_bf16 v[124:127], v[132:135], v[152:155], v[124:127]
	v_mfma_f32_16x16x32_bf16 v[120:123], v[140:143], v[152:155], v[120:123]
	v_mfma_f32_16x16x32_bf16 v[116:119], v[132:135], v[180:183], v[116:119]
	v_mfma_f32_16x16x32_bf16 v[112:115], v[140:143], v[180:183], v[112:115]
	v_mfma_f32_16x16x32_bf16 v[108:111], v[132:135], v[188:191], v[108:111]
	v_mfma_f32_16x16x32_bf16 v[104:107], v[140:143], v[188:191], v[104:107]
	v_mfma_f32_16x16x32_bf16 v[100:103], v[132:135], v[196:199], v[100:103]
	v_mfma_f32_16x16x32_bf16 v[96:99], v[140:143], v[196:199], v[96:99]
	s_barrier
	ds_read_b128 v[200:203], v173
	ds_read_b128 v[204:207], v173 offset:1024
	ds_read_b128 v[208:211], v173 offset:2048
	ds_read_b128 v[212:215], v173 offset:3072
	s_waitcnt vmcnt(8)
	s_barrier
	s_waitcnt lgkmcnt(0)
	v_mfma_f32_16x16x32_bf16 v[92:95], v[200:203], v[144:147], v[92:95]
	v_mfma_f32_16x16x32_bf16 v[88:91], v[208:211], v[144:147], v[88:91]
	v_mfma_f32_16x16x32_bf16 v[84:87], v[200:203], v[156:159], v[84:87]
	v_mfma_f32_16x16x32_bf16 v[80:83], v[208:211], v[156:159], v[80:83]
	v_mfma_f32_16x16x32_bf16 v[76:79], v[200:203], v[184:187], v[76:79]
	v_mfma_f32_16x16x32_bf16 v[72:75], v[208:211], v[184:187], v[72:75]
	v_mfma_f32_16x16x32_bf16 v[68:71], v[200:203], v[192:195], v[68:71]
	v_mfma_f32_16x16x32_bf16 v[64:67], v[208:211], v[192:195], v[64:67]
	v_mfma_f32_16x16x32_bf16 v[92:95], v[204:207], v[152:155], v[92:95]
	v_mfma_f32_16x16x32_bf16 v[88:91], v[212:215], v[152:155], v[88:91]
	v_mfma_f32_16x16x32_bf16 v[84:87], v[204:207], v[180:183], v[84:87]
	v_mfma_f32_16x16x32_bf16 v[80:83], v[212:215], v[180:183], v[80:83]
	v_mfma_f32_16x16x32_bf16 v[76:79], v[204:207], v[188:191], v[76:79]
	v_mfma_f32_16x16x32_bf16 v[72:75], v[212:215], v[188:191], v[72:75]
	v_mfma_f32_16x16x32_bf16 v[68:71], v[204:207], v[196:199], v[68:71]
	v_mfma_f32_16x16x32_bf16 v[64:67], v[212:215], v[196:199], v[64:67]
	s_barrier
	ds_read_b128 v[144:147], v169 offset:16384
	ds_read_b128 v[152:155], v169 offset:17408
	ds_read_b128 v[156:159], v170 offset:16384
	ds_read_b128 v[180:183], v170 offset:17408
	ds_read_b128 v[184:187], v171 offset:16384
	ds_read_b128 v[188:191], v171 offset:17408
	ds_read_b128 v[192:195], v172 offset:16384
	ds_read_b128 v[196:199], v172 offset:17408
	s_waitcnt vmcnt(4)
	s_barrier
	s_waitcnt lgkmcnt(0)
	v_mfma_f32_16x16x32_bf16 v[60:63], v[128:131], v[144:147], v[60:63]
	v_mfma_f32_16x16x32_bf16 v[56:59], v[136:139], v[144:147], v[56:59]
	v_mfma_f32_16x16x32_bf16 v[40:43], v[136:139], v[184:187], v[40:43]
	v_mfma_f32_16x16x32_bf16 v[60:63], v[132:135], v[152:155], v[60:63]
	v_mfma_f32_16x16x32_bf16 v[56:59], v[140:143], v[152:155], v[56:59]
	v_mfma_f32_16x16x32_bf16 v[52:55], v[128:131], v[156:159], v[52:55]
	v_mfma_f32_16x16x32_bf16 v[48:51], v[136:139], v[156:159], v[48:51]
	v_mfma_f32_16x16x32_bf16 v[44:47], v[128:131], v[184:187], v[44:47]
	v_mfma_f32_16x16x32_bf16 v[40:43], v[140:143], v[188:191], v[40:43]
	v_mfma_f32_16x16x32_bf16 v[36:39], v[128:131], v[192:195], v[36:39]
	v_mfma_f32_16x16x32_bf16 v[32:35], v[136:139], v[192:195], v[32:35]
	v_mfma_f32_16x16x32_bf16 v[52:55], v[132:135], v[180:183], v[52:55]
	v_mfma_f32_16x16x32_bf16 v[216:219], v[140:143], v[180:183], v[48:51]
	v_mfma_f32_16x16x32_bf16 v[44:47], v[132:135], v[188:191], v[44:47]
	v_mfma_f32_16x16x32_bf16 v[220:223], v[132:135], v[196:199], v[36:39]
	v_mfma_f32_16x16x32_bf16 v[32:35], v[140:143], v[196:199], v[32:35]
	v_mfma_f32_16x16x32_bf16 v[16:19], v[208:211], v[156:159], v[16:19]
	v_mfma_f32_16x16x32_bf16 v[4:7], v[200:203], v[192:195], v[4:7]
	v_mfma_f32_16x16x32_bf16 v[0:3], v[208:211], v[192:195], v[0:3]
	v_mfma_f32_16x16x32_bf16 v[28:31], v[200:203], v[144:147], v[28:31]
	v_mfma_f32_16x16x32_bf16 v[24:27], v[208:211], v[144:147], v[24:27]
	v_mfma_f32_16x16x32_bf16 v[20:23], v[200:203], v[156:159], v[20:23]
	v_mfma_f32_16x16x32_bf16 v[16:19], v[212:215], v[180:183], v[16:19]
	v_mfma_f32_16x16x32_bf16 v[12:15], v[200:203], v[184:187], v[12:15]
	v_mfma_f32_16x16x32_bf16 v[8:11], v[208:211], v[184:187], v[8:11]
	v_mfma_f32_16x16x32_bf16 v[4:7], v[204:207], v[196:199], v[4:7]
	v_mfma_f32_16x16x32_bf16 v[0:3], v[212:215], v[196:199], v[0:3]
	v_mfma_f32_16x16x32_bf16 v[224:227], v[204:207], v[152:155], v[28:31]
	v_mfma_f32_16x16x32_bf16 v[24:27], v[212:215], v[152:155], v[24:27]
	v_mfma_f32_16x16x32_bf16 v[20:23], v[204:207], v[180:183], v[20:23]
	v_mfma_f32_16x16x32_bf16 v[152:155], v[204:207], v[188:191], v[12:15]
	v_mfma_f32_16x16x32_bf16 v[156:159], v[212:215], v[188:191], v[8:11]
	s_barrier
; #define LDA(dst, b, h)                                                                                               \
;   _Pragma("unroll") for (int m = 0; m < 4; ++m) _Pragma("unroll") for (int k = 0; k < 2; ++k) dst[m][k] =            \
;       *reinterpret_cast<const bf16x8*>(SA(b, h) + lds_byte(wr * 64 + m * 16 + fr, k * 32 + fq * 8))
; #define LDB(dst, b, h)                                                                                               \
;   _Pragma("unroll") for (int n = 0; n < 2; ++n) _Pragma("unroll") for (int k = 0; k < 2; ++k) dst[n][k] =            \
;       *reinterpret_cast<const bf16x8*>(SB(b, h) + lds_byte(wc * 32 + n * 16 + fr, k * 32 + fq * 8))
; #define WAIT_V(n) asm volatile("s_waitcnt vmcnt(" #n ")" ::: "memory")
; #define WAIT_L(n) asm volatile("s_waitcnt lgkmcnt(" #n ")" ::: "memory")
; #define BAR __builtin_amdgcn_s_barrier()
; template <int EPI>
; __device__ __forceinline__ void gemm_phase(const u16* __restrict__ A, const u16* __restrict__ Bt, const int K,
;                                            const int nN, char* shm, const EpiArgs& ea) {
;     ...
;       LDA(At, 0, 1); WAIT_V(4); BAR; WAIT_L(0); MMA(1, 0, At, B0); MMA(1, 1, At, B1); BAR;
;     }
;     {
;       LDB(B0, 1, 0); LDA(At, 1, 0); WAIT_V(2); BAR; WAIT_L(0); MMA(0, 0, At, B0); BAR;
;       LDB(B1, 1, 1); WAIT_V(0); BAR; WAIT_L(0); MMA(0, 1, At, B1); BAR;
;       LDA(At, 1, 1); BAR; WAIT_L(0); MMA(1, 0, At, B0); MMA(1, 1, At, B1); BAR;
;     }
;     if (wr == 0) BAR;
	s_nop 0
	ds_read_b128 v[8:11], v176
	ds_read_b128 v[12:15], v176 offset:1024
	ds_read_b128 v[180:183], v176 offset:2048
	ds_read_b128 v[184:187], v176 offset:3072
	ds_read_b128 v[128:131], v169 offset:32768
	ds_read_b128 v[132:135], v169 offset:33792
	ds_read_b128 v[188:191], v170 offset:32768
	ds_read_b128 v[192:195], v170 offset:33792
	ds_read_b128 v[196:199], v171 offset:32768
	ds_read_b128 v[200:203], v171 offset:33792
	ds_read_b128 v[204:207], v172 offset:32768
	ds_read_b128 v[208:211], v172 offset:33792
	s_waitcnt vmcnt(2)
	s_barrier
	s_waitcnt lgkmcnt(0)
	v_mfma_f32_16x16x32_bf16 v[48:51], v[8:11], v[188:191], v[116:119]
	v_mfma_f32_16x16x32_bf16 v[140:143], v[12:15], v[192:195], v[48:51]
	v_mfma_f32_16x16x32_bf16 v[48:51], v[180:183], v[188:191], v[112:115]
	v_mfma_f32_16x16x32_bf16 v[136:139], v[184:187], v[192:195], v[48:51]
	v_mfma_f32_16x16x32_bf16 v[48:51], v[8:11], v[196:199], v[108:111]
	v_mfma_f32_16x16x32_bf16 v[28:31], v[8:11], v[128:131], v[124:127]
	v_mfma_f32_16x16x32_bf16 v[124:127], v[12:15], v[200:203], v[48:51]
	v_mfma_f32_16x16x32_bf16 v[48:51], v[180:183], v[196:199], v[104:107]
	v_mfma_f32_16x16x32_bf16 v[36:39], v[180:183], v[128:131], v[120:123]
	v_mfma_f32_16x16x32_bf16 v[120:123], v[184:187], v[200:203], v[48:51]
	v_mfma_f32_16x16x32_bf16 v[48:51], v[8:11], v[204:207], v[100:103]
	v_mfma_f32_16x16x32_bf16 v[108:111], v[12:15], v[208:211], v[48:51]
	v_mfma_f32_16x16x32_bf16 v[48:51], v[180:183], v[204:207], v[96:99]
	v_mfma_f32_16x16x32_bf16 v[28:31], v[12:15], v[132:135], v[28:31]
	v_mfma_f32_16x16x32_bf16 v[36:39], v[184:187], v[132:135], v[36:39]
	v_mfma_f32_16x16x32_bf16 v[104:107], v[184:187], v[208:211], v[48:51]
	s_barrier
	ds_read_b128 v[212:215], v177
	ds_read_b128 v[228:231], v177 offset:1024
	ds_read_b128 v[232:235], v177 offset:2048
	ds_read_b128 v[236:239], v177 offset:3072
	s_waitcnt vmcnt(0)
	s_barrier
	s_waitcnt lgkmcnt(0)
	v_mfma_f32_16x16x32_bf16 v[48:51], v[212:215], v[128:131], v[92:95]
	v_mfma_f32_16x16x32_bf16 v[88:91], v[232:235], v[128:131], v[88:91]
	v_mfma_f32_16x16x32_bf16 v[84:87], v[212:215], v[188:191], v[84:87]
	v_mfma_f32_16x16x32_bf16 v[80:83], v[232:235], v[188:191], v[80:83]
	v_mfma_f32_16x16x32_bf16 v[76:79], v[212:215], v[196:199], v[76:79]
	v_mfma_f32_16x16x32_bf16 v[72:75], v[232:235], v[196:199], v[72:75]
	v_mfma_f32_16x16x32_bf16 v[68:71], v[212:215], v[204:207], v[68:71]
	v_mfma_f32_16x16x32_bf16 v[64:67], v[232:235], v[204:207], v[64:67]
	v_mfma_f32_16x16x32_bf16 v[48:51], v[228:231], v[132:135], v[48:51]
	v_mfma_f32_16x16x32_bf16 v[144:147], v[236:239], v[132:135], v[88:91]
	v_mfma_f32_16x16x32_bf16 v[132:135], v[228:231], v[192:195], v[84:87]
	v_mfma_f32_16x16x32_bf16 v[128:131], v[236:239], v[192:195], v[80:83]
	v_mfma_f32_16x16x32_bf16 v[116:119], v[228:231], v[200:203], v[76:79]
	v_mfma_f32_16x16x32_bf16 v[112:115], v[236:239], v[200:203], v[72:75]
	v_mfma_f32_16x16x32_bf16 v[100:103], v[228:231], v[208:211], v[68:71]
	v_mfma_f32_16x16x32_bf16 v[96:99], v[236:239], v[208:211], v[64:67]
	s_barrier
	s_nop 0
	ds_read_b128 v[64:67], v169 offset:49152
	ds_read_b128 v[68:71], v169 offset:50176
	ds_read_b128 v[188:191], v170 offset:49152
	ds_read_b128 v[192:195], v170 offset:50176
	ds_read_b128 v[196:199], v171 offset:49152
	ds_read_b128 v[200:203], v171 offset:50176
	ds_read_b128 v[204:207], v172 offset:49152
	ds_read_b128 v[208:211], v172 offset:50176
	s_barrier
	s_waitcnt lgkmcnt(0)
	v_mfma_f32_16x16x32_bf16 v[60:63], v[8:11], v[64:67], v[60:63]
	v_mfma_f32_16x16x32_bf16 v[52:55], v[8:11], v[188:191], v[52:55]
	v_mfma_f32_16x16x32_bf16 v[44:47], v[8:11], v[196:199], v[44:47]
	v_mfma_f32_16x16x32_bf16 v[8:11], v[8:11], v[204:207], v[220:223]
	v_mfma_f32_16x16x32_bf16 v[92:95], v[12:15], v[68:71], v[60:63]
	v_mfma_f32_16x16x32_bf16 v[56:59], v[180:183], v[64:67], v[56:59]
	v_mfma_f32_16x16x32_bf16 v[76:79], v[12:15], v[192:195], v[52:55]
	v_mfma_f32_16x16x32_bf16 v[52:55], v[180:183], v[188:191], v[216:219]
	v_mfma_f32_16x16x32_bf16 v[60:63], v[12:15], v[200:203], v[44:47]
	v_mfma_f32_16x16x32_bf16 v[40:43], v[180:183], v[196:199], v[40:43]
	v_mfma_f32_16x16x32_bf16 v[12:15], v[12:15], v[208:211], v[8:11]
	v_mfma_f32_16x16x32_bf16 v[8:11], v[180:183], v[204:207], v[32:35]
	v_mfma_f32_16x16x32_bf16 v[88:91], v[184:187], v[68:71], v[56:59]
	v_mfma_f32_16x16x32_bf16 v[72:75], v[184:187], v[192:195], v[52:55]
	v_mfma_f32_16x16x32_bf16 v[56:59], v[184:187], v[200:203], v[40:43]
	v_mfma_f32_16x16x32_bf16 v[8:11], v[184:187], v[208:211], v[8:11]
	v_mfma_f32_16x16x32_bf16 v[16:19], v[232:235], v[188:191], v[16:19]
	v_mfma_f32_16x16x32_bf16 v[32:35], v[212:215], v[64:67], v[224:227]
	v_mfma_f32_16x16x32_bf16 v[24:27], v[232:235], v[64:67], v[24:27]
	v_mfma_f32_16x16x32_bf16 v[64:67], v[236:239], v[192:195], v[16:19]
	v_mfma_f32_16x16x32_bf16 v[16:19], v[212:215], v[196:199], v[152:155]
	v_mfma_f32_16x16x32_bf16 v[20:23], v[212:215], v[188:191], v[20:23]
	v_mfma_f32_16x16x32_bf16 v[40:43], v[228:231], v[200:203], v[16:19]
	v_mfma_f32_16x16x32_bf16 v[16:19], v[232:235], v[196:199], v[156:159]
	v_mfma_f32_16x16x32_bf16 v[4:7], v[212:215], v[204:207], v[4:7]
	v_mfma_f32_16x16x32_bf16 v[0:3], v[232:235], v[204:207], v[0:3]
	v_mfma_f32_16x16x32_bf16 v[84:87], v[228:231], v[68:71], v[32:35]
	v_mfma_f32_16x16x32_bf16 v[80:83], v[236:239], v[68:71], v[24:27]
	v_mfma_f32_16x16x32_bf16 v[68:71], v[228:231], v[192:195], v[20:23]
	v_mfma_f32_16x16x32_bf16 v[16:19], v[236:239], v[200:203], v[16:19]
	v_mfma_f32_16x16x32_bf16 v[4:7], v[228:231], v[208:211], v[4:7]
	v_mfma_f32_16x16x32_bf16 v[0:3], v[236:239], v[208:211], v[0:3]
	s_andn2_b64 vcc, exec, s[36:37]
	s_barrier
	s_cbranch_vccz .LBB0_380
	s_andn2_b64 vcc, exec, s[4:5]
	s_cbranch_vccz .LBB0_381

; #define LDA(dst, b, h)                                                                                               \
;   _Pragma("unroll") for (int m = 0; m < 4; ++m) _Pragma("unroll") for (int k = 0; k < 2; ++k) dst[m][k] =            \
;       *reinterpret_cast<const bf16x8*>(SA(b, h) + lds_byte(wr * 64 + m * 16 + fr, k * 32 + fq * 8))
; #define LDB(dst, b, h)                                                                                               \
;   _Pragma("unroll") for (int n = 0; n < 2; ++n) _Pragma("unroll") for (int k = 0; k < 2; ++k) dst[n][k] =            \
;       *reinterpret_cast<const bf16x8*>(SB(b, h) + lds_byte(wc * 32 + n * 16 + fr, k * 32 + fq * 8))
; #define WAIT_V(n) asm volatile("s_waitcnt vmcnt(" #n ")" ::: "memory")
; #define WAIT_L(n) asm volatile("s_waitcnt lgkmcnt(" #n ")" ::: "memory")
; #define BAR __builtin_amdgcn_s_barrier()
; #define SCHED __builtin_amdgcn_sched_barrier(0)
; template <int EPI>
; __device__ __forceinline__ void gemm_phase(const u16* __restrict__ A, const u16* __restrict__ Bt, const int K,
;                                            const int nN, char* shm, const EpiArgs& ea) {
;     ...
;       LDB(B0, 0, 0); SCHED; LDA(At, 0, 0); STAGE(SA(1, 1), rA, brow + HALF, t + 1);
;       WAIT_V(10); WAIT_L(8); BAR; WAIT_L(0); MMA(0, 0, At, B0); BAR; SCHED;
;       LDB(B1, 0, 1); STAGE(SB(0, 0), rB, bcol, t + 2);
;       WAIT_V(10); BAR; WAIT_L(0); MMA(0, 1, At, B1); BAR;
;       LDA(At, 0, 1); STAGE(SA(0, 0), rA, brow, t + 2);
;       BAR; WAIT_L(0); MMA(1, 0, At, B0); BAR; SCHED;
;       STAGE(SB(0, 1), rB, bcol + HALF, t + 2);
;       WAIT_V(10); BAR; MMA(1, 1, At, B1); BAR;
.LBB0_492:
	ds_read_b128 v[130:133], v146
	ds_read_b128 v[134:137], v146 offset:1024
	ds_read_b128 v[138:141], v146 offset:2048
	ds_read_b128 v[154:157], v146 offset:3072
	s_add_i32 s65, s59, s64
	s_mov_b32 m0, s34
	s_add_i32 s10, s65, 0x4000
	ds_read_b128 v[158:161], v147
	ds_read_b128 v[162:165], v147 offset:1024
	ds_read_b128 v[166:169], v148
	ds_read_b128 v[170:173], v148 offset:1024
	ds_read_b128 v[176:179], v149
	ds_read_b128 v[180:183], v149 offset:1024
	ds_read_b128 v[184:187], v150
	ds_read_b128 v[188:191], v150 offset:1024
	buffer_load_dwordx4 v142, s[0:3], s10 offen lds
	s_add_i32 s10, s65, 0x6000
	s_mov_b32 m0, s35
	s_nop 0
	buffer_load_dwordx4 v142, s[0:3], s10 offen lds
	s_waitcnt vmcnt(10)
	s_waitcnt lgkmcnt(8)
	s_barrier
	s_waitcnt lgkmcnt(0)
	v_mfma_f32_16x16x32_bf16 v[124:127], v[130:133], v[158:161], v[124:127]
	v_mfma_f32_16x16x32_bf16 v[120:123], v[138:141], v[158:161], v[120:123]
	v_mfma_f32_16x16x32_bf16 v[116:119], v[130:133], v[166:169], v[116:119]
	v_mfma_f32_16x16x32_bf16 v[112:115], v[138:141], v[166:169], v[112:115]
	v_mfma_f32_16x16x32_bf16 v[108:111], v[130:133], v[176:179], v[108:111]
	v_mfma_f32_16x16x32_bf16 v[104:107], v[138:141], v[176:179], v[104:107]
	v_mfma_f32_16x16x32_bf16 v[100:103], v[130:133], v[184:187], v[100:103]
	v_mfma_f32_16x16x32_bf16 v[96:99], v[138:141], v[184:187], v[96:99]
	v_mfma_f32_16x16x32_bf16 v[124:127], v[134:137], v[162:165], v[124:127]
	v_mfma_f32_16x16x32_bf16 v[120:123], v[154:157], v[162:165], v[120:123]
	v_mfma_f32_16x16x32_bf16 v[116:119], v[134:137], v[170:173], v[116:119]
	v_mfma_f32_16x16x32_bf16 v[112:115], v[154:157], v[170:173], v[112:115]
	v_mfma_f32_16x16x32_bf16 v[108:111], v[134:137], v[180:183], v[108:111]
	v_mfma_f32_16x16x32_bf16 v[104:107], v[154:157], v[180:183], v[104:107]
	v_mfma_f32_16x16x32_bf16 v[100:103], v[134:137], v[188:191], v[100:103]
	v_mfma_f32_16x16x32_bf16 v[96:99], v[154:157], v[188:191], v[96:99]
	s_barrier
	s_add_i32 s66, s62, s64
	s_mov_b32 m0, s36
	s_add_i32 s67, s66, 0x8000
	s_mov_b32 s10, s2
	s_mov_b32 s11, s3
	ds_read_b128 v[192:195], v151
	ds_read_b128 v[196:199], v151 offset:1024
	ds_read_b128 v[200:203], v151 offset:2048
	ds_read_b128 v[204:207], v151 offset:3072
	buffer_load_dwordx4 v142, s[8:11], s67 offen lds
	s_add_i32 s67, s66, 0xa000
	s_mov_b32 m0, s37
	s_nop 0
	buffer_load_dwordx4 v142, s[8:11], s67 offen lds
	s_waitcnt vmcnt(10)
	s_barrier
	s_waitcnt lgkmcnt(0)
	v_mfma_f32_16x16x32_bf16 v[92:95], v[192:195], v[158:161], v[92:95]
	v_mfma_f32_16x16x32_bf16 v[88:91], v[200:203], v[158:161], v[88:91]
	v_mfma_f32_16x16x32_bf16 v[84:87], v[192:195], v[166:169], v[84:87]
	v_mfma_f32_16x16x32_bf16 v[80:83], v[200:203], v[166:169], v[80:83]
	v_mfma_f32_16x16x32_bf16 v[76:79], v[192:195], v[176:179], v[76:79]
	v_mfma_f32_16x16x32_bf16 v[72:75], v[200:203], v[176:179], v[72:75]
	v_mfma_f32_16x16x32_bf16 v[68:71], v[192:195], v[184:187], v[68:71]
	v_mfma_f32_16x16x32_bf16 v[64:67], v[200:203], v[184:187], v[64:67]
	v_mfma_f32_16x16x32_bf16 v[92:95], v[196:199], v[162:165], v[92:95]
	v_mfma_f32_16x16x32_bf16 v[88:91], v[204:207], v[162:165], v[88:91]
	v_mfma_f32_16x16x32_bf16 v[84:87], v[196:199], v[170:173], v[84:87]
	v_mfma_f32_16x16x32_bf16 v[80:83], v[204:207], v[170:173], v[80:83]
	v_mfma_f32_16x16x32_bf16 v[76:79], v[196:199], v[180:183], v[76:79]
	v_mfma_f32_16x16x32_bf16 v[72:75], v[204:207], v[180:183], v[72:75]
	v_mfma_f32_16x16x32_bf16 v[68:71], v[196:199], v[188:191], v[68:71]
	v_mfma_f32_16x16x32_bf16 v[64:67], v[204:207], v[188:191], v[64:67]
	s_add_i32 s67, s61, s64
	s_mov_b32 m0, s27
	s_add_i32 s68, s67, 0x8000
	s_barrier
	ds_read_b128 v[158:161], v147 offset:16384
	ds_read_b128 v[162:165], v147 offset:17408
	ds_read_b128 v[166:169], v148 offset:16384
	ds_read_b128 v[170:173], v148 offset:17408
	ds_read_b128 v[176:179], v149 offset:16384
	ds_read_b128 v[180:183], v149 offset:17408
	ds_read_b128 v[184:187], v150 offset:16384
	ds_read_b128 v[188:191], v150 offset:17408
	buffer_load_dwordx4 v142, s[0:3], s68 offen lds
	s_add_i32 s68, s67, 0xa000
	s_mov_b32 m0, s38
	s_nop 0
	buffer_load_dwordx4 v142, s[0:3], s68 offen lds
	s_barrier
	s_waitcnt lgkmcnt(0)
	v_mfma_f32_16x16x32_bf16 v[60:63], v[130:133], v[158:161], v[60:63]
	v_mfma_f32_16x16x32_bf16 v[56:59], v[138:141], v[158:161], v[56:59]
	v_mfma_f32_16x16x32_bf16 v[52:55], v[130:133], v[166:169], v[52:55]
	v_mfma_f32_16x16x32_bf16 v[48:51], v[138:141], v[166:169], v[48:51]
	v_mfma_f32_16x16x32_bf16 v[44:47], v[130:133], v[176:179], v[44:47]
	v_mfma_f32_16x16x32_bf16 v[40:43], v[138:141], v[176:179], v[40:43]
	v_mfma_f32_16x16x32_bf16 v[36:39], v[130:133], v[184:187], v[36:39]
	v_mfma_f32_16x16x32_bf16 v[32:35], v[138:141], v[184:187], v[32:35]
	v_mfma_f32_16x16x32_bf16 v[60:63], v[134:137], v[162:165], v[60:63]
	v_mfma_f32_16x16x32_bf16 v[56:59], v[154:157], v[162:165], v[56:59]
	v_mfma_f32_16x16x32_bf16 v[52:55], v[134:137], v[170:173], v[52:55]
	v_mfma_f32_16x16x32_bf16 v[48:51], v[154:157], v[170:173], v[48:51]
	v_mfma_f32_16x16x32_bf16 v[44:47], v[134:137], v[180:183], v[44:47]
	v_mfma_f32_16x16x32_bf16 v[40:43], v[154:157], v[180:183], v[40:43]
	v_mfma_f32_16x16x32_bf16 v[36:39], v[134:137], v[188:191], v[36:39]
	v_mfma_f32_16x16x32_bf16 v[32:35], v[154:157], v[188:191], v[32:35]
	s_barrier
	s_add_i32 s68, s60, s64
	s_mov_b32 m0, s39
	s_add_i32 s69, s68, 0x8000
	buffer_load_dwordx4 v142, s[8:11], s69 offen lds
	s_add_i32 s69, s68, 0xa000
	s_mov_b32 m0, s40
	s_nop 0
	buffer_load_dwordx4 v142, s[8:11], s69 offen lds
	s_waitcnt vmcnt(10)
	s_barrier
; #define LDA(dst, b, h)                                                                                               \
;   _Pragma("unroll") for (int m = 0; m < 4; ++m) _Pragma("unroll") for (int k = 0; k < 2; ++k) dst[m][k] =            \
;       *reinterpret_cast<const bf16x8*>(SA(b, h) + lds_byte(wr * 64 + m * 16 + fr, k * 32 + fq * 8))
; #define LDB(dst, b, h)                                                                                               \
;   _Pragma("unroll") for (int n = 0; n < 2; ++n) _Pragma("unroll") for (int k = 0; k < 2; ++k) dst[n][k] =            \
;       *reinterpret_cast<const bf16x8*>(SB(b, h) + lds_byte(wc * 32 + n * 16 + fr, k * 32 + fq * 8))
; #define WAIT_V(n) asm volatile("s_waitcnt vmcnt(" #n ")" ::: "memory")
; #define WAIT_L(n) asm volatile("s_waitcnt lgkmcnt(" #n ")" ::: "memory")
; #define BAR __builtin_amdgcn_s_barrier()
; #define SCHED __builtin_amdgcn_sched_barrier(0)
; template <int EPI>
; __device__ __forceinline__ void gemm_phase(const u16* __restrict__ A, const u16* __restrict__ Bt, const int K,
;                                            const int nN, char* shm, const EpiArgs& ea) {
;     ...
;       WAIT_V(10); BAR; MMA(1, 1, At, B1); BAR;
;       LDB(B0, 1, 0); SCHED; LDA(At, 1, 0); STAGE(SA(0, 1), rA, brow + HALF, t + 2);
;       WAIT_V(10); WAIT_L(8); BAR; WAIT_L(0); MMA(0, 0, At, B0); BAR; SCHED;
;       LDB(B1, 1, 1); STAGE(SB(1, 0), rB, bcol, t + 3);
;       WAIT_V(10); BAR; WAIT_L(0); MMA(0, 1, At, B1); BAR;
;       LDA(At, 1, 1); STAGE(SA(1, 0), rA, brow, t + 3);
;       BAR; WAIT_L(0); MMA(1, 0, At, B0); BAR; SCHED;
;       STAGE(SB(1, 1), rB, bcol + HALF, t + 3);
	v_mfma_f32_16x16x32_bf16 v[28:31], v[192:195], v[158:161], v[28:31]
	v_mfma_f32_16x16x32_bf16 v[24:27], v[200:203], v[158:161], v[24:27]
	v_mfma_f32_16x16x32_bf16 v[20:23], v[192:195], v[166:169], v[20:23]
	v_mfma_f32_16x16x32_bf16 v[16:19], v[200:203], v[166:169], v[16:19]
	v_mfma_f32_16x16x32_bf16 v[12:15], v[192:195], v[176:179], v[12:15]
	v_mfma_f32_16x16x32_bf16 v[8:11], v[200:203], v[176:179], v[8:11]
	v_mfma_f32_16x16x32_bf16 v[4:7], v[192:195], v[184:187], v[4:7]
	v_mfma_f32_16x16x32_bf16 v[0:3], v[200:203], v[184:187], v[0:3]
	v_mfma_f32_16x16x32_bf16 v[28:31], v[196:199], v[162:165], v[28:31]
	v_mfma_f32_16x16x32_bf16 v[24:27], v[204:207], v[162:165], v[24:27]
	v_mfma_f32_16x16x32_bf16 v[20:23], v[196:199], v[170:173], v[20:23]
	v_mfma_f32_16x16x32_bf16 v[16:19], v[204:207], v[170:173], v[16:19]
	v_mfma_f32_16x16x32_bf16 v[12:15], v[196:199], v[180:183], v[12:15]
	v_mfma_f32_16x16x32_bf16 v[8:11], v[204:207], v[180:183], v[8:11]
	v_mfma_f32_16x16x32_bf16 v[4:7], v[196:199], v[188:191], v[4:7]
	v_mfma_f32_16x16x32_bf16 v[0:3], v[204:207], v[188:191], v[0:3]
	s_barrier
	ds_read_b128 v[130:133], v152
	ds_read_b128 v[134:137], v152 offset:1024
	ds_read_b128 v[138:141], v152 offset:2048
	ds_read_b128 v[154:157], v152 offset:3072
	s_mov_b32 m0, s41
	s_add_i32 s69, s65, 0x8000
	ds_read_b128 v[158:161], v147 offset:32768
	ds_read_b128 v[162:165], v147 offset:33792
	ds_read_b128 v[166:169], v148 offset:32768
	ds_read_b128 v[170:173], v148 offset:33792
	ds_read_b128 v[176:179], v149 offset:32768
	ds_read_b128 v[180:183], v149 offset:33792
	ds_read_b128 v[184:187], v150 offset:32768
	ds_read_b128 v[188:191], v150 offset:33792
	buffer_load_dwordx4 v142, s[0:3], s69 offen lds
	s_add_i32 s65, s65, 0xa000
	s_mov_b32 m0, s42
	s_nop 0
	buffer_load_dwordx4 v142, s[0:3], s65 offen lds
	s_waitcnt vmcnt(10)
	s_waitcnt lgkmcnt(8)
	s_barrier
	s_waitcnt lgkmcnt(0)
	v_mfma_f32_16x16x32_bf16 v[124:127], v[130:133], v[158:161], v[124:127]
	v_mfma_f32_16x16x32_bf16 v[120:123], v[138:141], v[158:161], v[120:123]
	v_mfma_f32_16x16x32_bf16 v[116:119], v[130:133], v[166:169], v[116:119]
	v_mfma_f32_16x16x32_bf16 v[112:115], v[138:141], v[166:169], v[112:115]
	v_mfma_f32_16x16x32_bf16 v[108:111], v[130:133], v[176:179], v[108:111]
	v_mfma_f32_16x16x32_bf16 v[104:107], v[138:141], v[176:179], v[104:107]
	v_mfma_f32_16x16x32_bf16 v[100:103], v[130:133], v[184:187], v[100:103]
	v_mfma_f32_16x16x32_bf16 v[96:99], v[138:141], v[184:187], v[96:99]
	v_mfma_f32_16x16x32_bf16 v[124:127], v[134:137], v[162:165], v[124:127]
	v_mfma_f32_16x16x32_bf16 v[120:123], v[154:157], v[162:165], v[120:123]
	v_mfma_f32_16x16x32_bf16 v[116:119], v[134:137], v[170:173], v[116:119]
	v_mfma_f32_16x16x32_bf16 v[112:115], v[154:157], v[170:173], v[112:115]
	v_mfma_f32_16x16x32_bf16 v[108:111], v[134:137], v[180:183], v[108:111]
	v_mfma_f32_16x16x32_bf16 v[104:107], v[154:157], v[180:183], v[104:107]
	v_mfma_f32_16x16x32_bf16 v[100:103], v[134:137], v[188:191], v[100:103]
	v_mfma_f32_16x16x32_bf16 v[96:99], v[154:157], v[188:191], v[96:99]
	s_barrier
	s_mov_b32 m0, s43
	s_add_i32 s65, s66, 0xc000
	ds_read_b128 v[192:195], v153
	ds_read_b128 v[196:199], v153 offset:1024
	ds_read_b128 v[200:203], v153 offset:2048
	ds_read_b128 v[204:207], v153 offset:3072
	buffer_load_dwordx4 v142, s[8:11], s65 offen lds
	s_add_i32 s66, s66, 0xe000
	s_mov_b32 m0, s48
	s_nop 0
	buffer_load_dwordx4 v142, s[8:11], s66 offen lds
	s_waitcnt vmcnt(10)
	s_barrier
	s_waitcnt lgkmcnt(0)
	v_mfma_f32_16x16x32_bf16 v[92:95], v[192:195], v[158:161], v[92:95]
	v_mfma_f32_16x16x32_bf16 v[88:91], v[200:203], v[158:161], v[88:91]
	v_mfma_f32_16x16x32_bf16 v[84:87], v[192:195], v[166:169], v[84:87]
	v_mfma_f32_16x16x32_bf16 v[80:83], v[200:203], v[166:169], v[80:83]
	v_mfma_f32_16x16x32_bf16 v[76:79], v[192:195], v[176:179], v[76:79]
	v_mfma_f32_16x16x32_bf16 v[72:75], v[200:203], v[176:179], v[72:75]
	v_mfma_f32_16x16x32_bf16 v[68:71], v[192:195], v[184:187], v[68:71]
	v_mfma_f32_16x16x32_bf16 v[64:67], v[200:203], v[184:187], v[64:67]
	v_mfma_f32_16x16x32_bf16 v[92:95], v[196:199], v[162:165], v[92:95]
	v_mfma_f32_16x16x32_bf16 v[88:91], v[204:207], v[162:165], v[88:91]
	v_mfma_f32_16x16x32_bf16 v[84:87], v[196:199], v[170:173], v[84:87]
	v_mfma_f32_16x16x32_bf16 v[80:83], v[204:207], v[170:173], v[80:83]
	v_mfma_f32_16x16x32_bf16 v[76:79], v[196:199], v[180:183], v[76:79]
	v_mfma_f32_16x16x32_bf16 v[72:75], v[204:207], v[180:183], v[72:75]
	v_mfma_f32_16x16x32_bf16 v[68:71], v[196:199], v[188:191], v[68:71]
	v_mfma_f32_16x16x32_bf16 v[64:67], v[204:207], v[188:191], v[64:67]
	s_mov_b32 m0, s49
	s_add_i32 s65, s67, 0xc000
	s_barrier
	ds_read_b128 v[158:161], v147 offset:49152
	ds_read_b128 v[162:165], v147 offset:50176
	ds_read_b128 v[166:169], v148 offset:49152
	ds_read_b128 v[170:173], v148 offset:50176
	ds_read_b128 v[176:179], v149 offset:49152
	ds_read_b128 v[180:183], v149 offset:50176
	ds_read_b128 v[184:187], v150 offset:49152
	ds_read_b128 v[188:191], v150 offset:50176
	buffer_load_dwordx4 v142, s[0:3], s65 offen lds
	s_add_i32 s67, s67, 0xe000
	s_mov_b32 m0, s50
	s_nop 0
	buffer_load_dwordx4 v142, s[0:3], s67 offen lds
	s_barrier
; #define LDA(dst, b, h)                                                                                               \
;   _Pragma("unroll") for (int m = 0; m < 4; ++m) _Pragma("unroll") for (int k = 0; k < 2; ++k) dst[m][k] =            \
;       *reinterpret_cast<const bf16x8*>(SA(b, h) + lds_byte(wr * 64 + m * 16 + fr, k * 32 + fq * 8))
; #define LDB(dst, b, h)                                                                                               \
;   _Pragma("unroll") for (int n = 0; n < 2; ++n) _Pragma("unroll") for (int k = 0; k < 2; ++k) dst[n][k] =            \
;       *reinterpret_cast<const bf16x8*>(SB(b, h) + lds_byte(wc * 32 + n * 16 + fr, k * 32 + fq * 8))
; #define WAIT_V(n) asm volatile("s_waitcnt vmcnt(" #n ")" ::: "memory")
; #define WAIT_L(n) asm volatile("s_waitcnt lgkmcnt(" #n ")" ::: "memory")
; #define BAR __builtin_amdgcn_s_barrier()
; #define SCHED __builtin_amdgcn_sched_barrier(0)
; template <int EPI>
; __device__ __forceinline__ void gemm_phase(const u16* __restrict__ A, const u16* __restrict__ Bt, const int K,
;                                            const int nN, char* shm, const EpiArgs& ea) {
;     ...
;       WAIT_V(10); BAR; WAIT_L(0); MMA(0, 1, At, B1); BAR;
;       LDA(At, 1, 1); STAGE(SA(1, 0), rA, brow, t + 3);
;       BAR; WAIT_L(0); MMA(1, 0, At, B0); BAR; SCHED;
;       STAGE(SB(1, 1), rB, bcol + HALF, t + 3);
;       WAIT_V(10); BAR; MMA(1, 1, At, B1); BAR;
;     }
;     ...
;       LDB(B0, 0, 0); LDA(At, 0, 0); STAGE(SA(1, 1), rA, brow + HALF, nt - 1);
;       WAIT_V(10); BAR; WAIT_L(0); MMA(0, 0, At, B0); BAR;
;       LDB(B1, 0, 1); WAIT_V(8); BAR; WAIT_L(0); MMA(0, 1, At, B1); BAR;
;       LDA(At, 0, 1); WAIT_V(4); BAR; WAIT_L(0); MMA(1, 0, At, B0); MMA(1, 1, At, B1); BAR;
	s_waitcnt lgkmcnt(0)
	v_mfma_f32_16x16x32_bf16 v[60:63], v[130:133], v[158:161], v[60:63]
	v_mfma_f32_16x16x32_bf16 v[56:59], v[138:141], v[158:161], v[56:59]
	v_mfma_f32_16x16x32_bf16 v[52:55], v[130:133], v[166:169], v[52:55]
	v_mfma_f32_16x16x32_bf16 v[48:51], v[138:141], v[166:169], v[48:51]
	v_mfma_f32_16x16x32_bf16 v[44:47], v[130:133], v[176:179], v[44:47]
	v_mfma_f32_16x16x32_bf16 v[40:43], v[138:141], v[176:179], v[40:43]
	v_mfma_f32_16x16x32_bf16 v[36:39], v[130:133], v[184:187], v[36:39]
	v_mfma_f32_16x16x32_bf16 v[32:35], v[138:141], v[184:187], v[32:35]
	v_mfma_f32_16x16x32_bf16 v[60:63], v[134:137], v[162:165], v[60:63]
	v_mfma_f32_16x16x32_bf16 v[56:59], v[154:157], v[162:165], v[56:59]
	v_mfma_f32_16x16x32_bf16 v[52:55], v[134:137], v[170:173], v[52:55]
	v_mfma_f32_16x16x32_bf16 v[48:51], v[154:157], v[170:173], v[48:51]
	v_mfma_f32_16x16x32_bf16 v[44:47], v[134:137], v[180:183], v[44:47]
	v_mfma_f32_16x16x32_bf16 v[40:43], v[154:157], v[180:183], v[40:43]
	v_mfma_f32_16x16x32_bf16 v[36:39], v[134:137], v[188:191], v[36:39]
	v_mfma_f32_16x16x32_bf16 v[32:35], v[154:157], v[188:191], v[32:35]
	s_barrier
	s_mov_b32 m0, s51
	s_add_i32 s65, s68, 0xc000
	buffer_load_dwordx4 v142, s[8:11], s65 offen lds
	s_add_i32 s68, s68, 0xe000
	s_mov_b32 m0, s52
	s_nop 0
	buffer_load_dwordx4 v142, s[8:11], s68 offen lds
	s_waitcnt vmcnt(10)
	s_barrier
	v_mfma_f32_16x16x32_bf16 v[28:31], v[192:195], v[158:161], v[28:31]
	v_mfma_f32_16x16x32_bf16 v[24:27], v[200:203], v[158:161], v[24:27]
	v_mfma_f32_16x16x32_bf16 v[20:23], v[192:195], v[166:169], v[20:23]
	v_mfma_f32_16x16x32_bf16 v[16:19], v[200:203], v[166:169], v[16:19]
	v_mfma_f32_16x16x32_bf16 v[12:15], v[192:195], v[176:179], v[12:15]
	v_mfma_f32_16x16x32_bf16 v[8:11], v[200:203], v[176:179], v[8:11]
	v_mfma_f32_16x16x32_bf16 v[4:7], v[192:195], v[184:187], v[4:7]
	v_mfma_f32_16x16x32_bf16 v[0:3], v[200:203], v[184:187], v[0:3]
	v_mfma_f32_16x16x32_bf16 v[28:31], v[196:199], v[162:165], v[28:31]
	v_mfma_f32_16x16x32_bf16 v[24:27], v[204:207], v[162:165], v[24:27]
	v_mfma_f32_16x16x32_bf16 v[20:23], v[196:199], v[170:173], v[20:23]
	v_mfma_f32_16x16x32_bf16 v[16:19], v[204:207], v[170:173], v[16:19]
	v_mfma_f32_16x16x32_bf16 v[12:15], v[196:199], v[180:183], v[12:15]
	v_mfma_f32_16x16x32_bf16 v[8:11], v[204:207], v[180:183], v[8:11]
	v_mfma_f32_16x16x32_bf16 v[4:7], v[196:199], v[188:191], v[4:7]
	v_mfma_f32_16x16x32_bf16 v[0:3], v[204:207], v[188:191], v[0:3]
	s_add_i32 s63, s63, 2
	s_add_i32 s64, s64, 0x8000
	s_cmp_lt_u32 s63, 28
	s_barrier
	s_cbranch_scc1 .LBB0_492
	s_mov_b32 m0, s34
	s_add_i32 s10, s59, 0x7c000
	ds_read_b128 v[130:133], v146
	ds_read_b128 v[134:137], v146 offset:1024
	ds_read_b128 v[138:141], v146 offset:2048
	ds_read_b128 v[154:157], v146 offset:3072
	ds_read_b128 v[158:161], v147
	ds_read_b128 v[162:165], v147 offset:1024
	ds_read_b128 v[166:169], v148
	ds_read_b128 v[170:173], v148 offset:1024
	ds_read_b128 v[176:179], v149
	ds_read_b128 v[180:183], v149 offset:1024
	ds_read_b128 v[184:187], v150
	ds_read_b128 v[188:191], v150 offset:1024
	buffer_load_dwordx4 v142, s[0:3], s10 offen lds
	s_add_i32 s59, s59, 0x7e000
	s_mov_b32 m0, s35
	s_nop 0
	buffer_load_dwordx4 v142, s[0:3], s59 offen lds
	s_waitcnt vmcnt(10)
	s_barrier
	s_waitcnt lgkmcnt(0)
	v_mfma_f32_16x16x32_bf16 v[124:127], v[130:133], v[158:161], v[124:127]
	v_mfma_f32_16x16x32_bf16 v[120:123], v[138:141], v[158:161], v[120:123]
	v_mfma_f32_16x16x32_bf16 v[116:119], v[130:133], v[166:169], v[116:119]
	v_mfma_f32_16x16x32_bf16 v[112:115], v[138:141], v[166:169], v[112:115]
	v_mfma_f32_16x16x32_bf16 v[100:103], v[130:133], v[184:187], v[100:103]
	v_mfma_f32_16x16x32_bf16 v[96:99], v[138:141], v[184:187], v[96:99]
	v_mfma_f32_16x16x32_bf16 v[124:127], v[134:137], v[162:165], v[124:127]
	v_mfma_f32_16x16x32_bf16 v[120:123], v[154:157], v[162:165], v[120:123]
	v_mfma_f32_16x16x32_bf16 v[116:119], v[134:137], v[170:173], v[116:119]
	v_mfma_f32_16x16x32_bf16 v[112:115], v[154:157], v[170:173], v[112:115]
	v_mfma_f32_16x16x32_bf16 v[108:111], v[130:133], v[176:179], v[108:111]
	v_mfma_f32_16x16x32_bf16 v[104:107], v[138:141], v[176:179], v[104:107]
	v_mfma_f32_16x16x32_bf16 v[100:103], v[134:137], v[188:191], v[100:103]
	v_mfma_f32_16x16x32_bf16 v[96:99], v[154:157], v[188:191], v[96:99]
	v_mfma_f32_16x16x32_bf16 v[192:195], v[134:137], v[180:183], v[108:111]
	v_mfma_f32_16x16x32_bf16 v[196:199], v[154:157], v[180:183], v[104:107]
	s_barrier
	s_nop 0
	ds_read_b128 v[104:107], v151
	ds_read_b128 v[108:111], v151 offset:1024
	ds_read_b128 v[200:203], v151 offset:2048
	ds_read_b128 v[204:207], v151 offset:3072
	s_waitcnt vmcnt(8)
	s_barrier
	s_waitcnt lgkmcnt(0)
	v_mfma_f32_16x16x32_bf16 v[84:87], v[104:107], v[166:169], v[84:87]
	v_mfma_f32_16x16x32_bf16 v[80:83], v[200:203], v[166:169], v[80:83]
	v_mfma_f32_16x16x32_bf16 v[68:71], v[104:107], v[184:187], v[68:71]
	v_mfma_f32_16x16x32_bf16 v[64:67], v[200:203], v[184:187], v[64:67]
	v_mfma_f32_16x16x32_bf16 v[92:95], v[104:107], v[158:161], v[92:95]
	v_mfma_f32_16x16x32_bf16 v[88:91], v[200:203], v[158:161], v[88:91]
	v_mfma_f32_16x16x32_bf16 v[84:87], v[108:111], v[170:173], v[84:87]
	v_mfma_f32_16x16x32_bf16 v[80:83], v[204:207], v[170:173], v[80:83]
	v_mfma_f32_16x16x32_bf16 v[76:79], v[104:107], v[176:179], v[76:79]
	v_mfma_f32_16x16x32_bf16 v[72:75], v[200:203], v[176:179], v[72:75]
	v_mfma_f32_16x16x32_bf16 v[68:71], v[108:111], v[188:191], v[68:71]
	v_mfma_f32_16x16x32_bf16 v[64:67], v[204:207], v[188:191], v[64:67]
	v_mfma_f32_16x16x32_bf16 v[208:211], v[108:111], v[162:165], v[92:95]
	v_mfma_f32_16x16x32_bf16 v[158:161], v[204:207], v[162:165], v[88:91]
	v_mfma_f32_16x16x32_bf16 v[162:165], v[108:111], v[180:183], v[76:79]
	v_mfma_f32_16x16x32_bf16 v[166:169], v[204:207], v[180:183], v[72:75]
	s_barrier
; #define LDA(dst, b, h)                                                                                               \
;   _Pragma("unroll") for (int m = 0; m < 4; ++m) _Pragma("unroll") for (int k = 0; k < 2; ++k) dst[m][k] =            \
;       *reinterpret_cast<const bf16x8*>(SA(b, h) + lds_byte(wr * 64 + m * 16 + fr, k * 32 + fq * 8))
; #define LDB(dst, b, h)                                                                                               \
;   _Pragma("unroll") for (int n = 0; n < 2; ++n) _Pragma("unroll") for (int k = 0; k < 2; ++k) dst[n][k] =            \
;       *reinterpret_cast<const bf16x8*>(SB(b, h) + lds_byte(wc * 32 + n * 16 + fr, k * 32 + fq * 8))
; #define WAIT_V(n) asm volatile("s_waitcnt vmcnt(" #n ")" ::: "memory")
; #define WAIT_L(n) asm volatile("s_waitcnt lgkmcnt(" #n ")" ::: "memory")
; #define BAR __builtin_amdgcn_s_barrier()
; template <int EPI>
; __device__ __forceinline__ void gemm_phase(const u16* __restrict__ A, const u16* __restrict__ Bt, const int K,
;                                            const int nN, char* shm, const EpiArgs& ea) {
;     ...
;       LDB(B1, 0, 1); WAIT_V(8); BAR; WAIT_L(0); MMA(0, 1, At, B1); BAR;
;       LDA(At, 0, 1); WAIT_V(4); BAR; WAIT_L(0); MMA(1, 0, At, B0); MMA(1, 1, At, B1); BAR;
;     }
;     {
;       LDB(B0, 1, 0); LDA(At, 1, 0); WAIT_V(2); BAR; WAIT_L(0); MMA(0, 0, At, B0); BAR;
	s_nop 0
	ds_read_b128 v[72:75], v147 offset:16384
	ds_read_b128 v[76:79], v147 offset:17408
	ds_read_b128 v[88:91], v148 offset:16384
	ds_read_b128 v[92:95], v148 offset:17408
	ds_read_b128 v[170:173], v149 offset:16384
	ds_read_b128 v[176:179], v149 offset:17408
	ds_read_b128 v[180:183], v150 offset:16384
	ds_read_b128 v[184:187], v150 offset:17408
	s_waitcnt vmcnt(4)
	s_barrier
	s_waitcnt lgkmcnt(0)
	v_mfma_f32_16x16x32_bf16 v[60:63], v[130:133], v[72:75], v[60:63]
	v_mfma_f32_16x16x32_bf16 v[52:55], v[130:133], v[88:91], v[52:55]
	v_mfma_f32_16x16x32_bf16 v[48:51], v[138:141], v[88:91], v[48:51]
	v_mfma_f32_16x16x32_bf16 v[36:39], v[130:133], v[180:183], v[36:39]
	v_mfma_f32_16x16x32_bf16 v[32:35], v[138:141], v[180:183], v[32:35]
	v_mfma_f32_16x16x32_bf16 v[60:63], v[134:137], v[76:79], v[60:63]
	v_mfma_f32_16x16x32_bf16 v[56:59], v[138:141], v[72:75], v[56:59]
	v_mfma_f32_16x16x32_bf16 v[52:55], v[134:137], v[92:95], v[52:55]
	v_mfma_f32_16x16x32_bf16 v[48:51], v[154:157], v[92:95], v[48:51]
	v_mfma_f32_16x16x32_bf16 v[44:47], v[130:133], v[170:173], v[44:47]
	v_mfma_f32_16x16x32_bf16 v[40:43], v[138:141], v[170:173], v[40:43]
	v_mfma_f32_16x16x32_bf16 v[36:39], v[134:137], v[184:187], v[36:39]
	v_mfma_f32_16x16x32_bf16 v[32:35], v[154:157], v[184:187], v[32:35]
	v_mfma_f32_16x16x32_bf16 v[188:191], v[154:157], v[76:79], v[56:59]
	v_mfma_f32_16x16x32_bf16 v[212:215], v[134:137], v[176:179], v[44:47]
	v_mfma_f32_16x16x32_bf16 v[216:219], v[154:157], v[176:179], v[40:43]
	v_mfma_f32_16x16x32_bf16 v[20:23], v[104:107], v[88:91], v[20:23]
	v_mfma_f32_16x16x32_bf16 v[16:19], v[200:203], v[88:91], v[16:19]
	v_mfma_f32_16x16x32_bf16 v[4:7], v[104:107], v[180:183], v[4:7]
	v_mfma_f32_16x16x32_bf16 v[0:3], v[200:203], v[180:183], v[0:3]
	v_mfma_f32_16x16x32_bf16 v[28:31], v[104:107], v[72:75], v[28:31]
	v_mfma_f32_16x16x32_bf16 v[24:27], v[200:203], v[72:75], v[24:27]
	v_mfma_f32_16x16x32_bf16 v[20:23], v[108:111], v[92:95], v[20:23]
	v_mfma_f32_16x16x32_bf16 v[16:19], v[204:207], v[92:95], v[16:19]
	v_mfma_f32_16x16x32_bf16 v[12:15], v[104:107], v[170:173], v[12:15]
	v_mfma_f32_16x16x32_bf16 v[8:11], v[200:203], v[170:173], v[8:11]
	v_mfma_f32_16x16x32_bf16 v[4:7], v[108:111], v[184:187], v[4:7]
	v_mfma_f32_16x16x32_bf16 v[0:3], v[204:207], v[184:187], v[0:3]
	v_mfma_f32_16x16x32_bf16 v[130:133], v[108:111], v[76:79], v[28:31]
	v_mfma_f32_16x16x32_bf16 v[134:137], v[204:207], v[76:79], v[24:27]
	v_mfma_f32_16x16x32_bf16 v[138:141], v[108:111], v[176:179], v[12:15]
	v_mfma_f32_16x16x32_bf16 v[154:157], v[204:207], v[176:179], v[8:11]
	s_barrier
	s_nop 0
	ds_read_b128 v[8:11], v152
	ds_read_b128 v[12:15], v152 offset:1024
	ds_read_b128 v[170:173], v152 offset:2048
	ds_read_b128 v[176:179], v152 offset:3072
	ds_read_b128 v[24:27], v147 offset:32768
	ds_read_b128 v[28:31], v147 offset:33792
	ds_read_b128 v[40:43], v148 offset:32768
	ds_read_b128 v[44:47], v148 offset:33792
	ds_read_b128 v[56:59], v149 offset:32768
	ds_read_b128 v[180:183], v149 offset:33792
	ds_read_b128 v[184:187], v150 offset:32768
	ds_read_b128 v[200:203], v150 offset:33792
	s_waitcnt vmcnt(2)
	s_barrier
	s_waitcnt lgkmcnt(0)
	v_mfma_f32_16x16x32_bf16 v[72:75], v[8:11], v[24:27], v[124:127]
	v_mfma_f32_16x16x32_bf16 v[124:127], v[12:15], v[28:31], v[72:75]
	v_mfma_f32_16x16x32_bf16 v[72:75], v[170:173], v[24:27], v[120:123]
	v_mfma_f32_16x16x32_bf16 v[120:123], v[176:179], v[28:31], v[72:75]
	v_mfma_f32_16x16x32_bf16 v[72:75], v[8:11], v[40:43], v[116:119]
	v_mfma_f32_16x16x32_bf16 v[104:107], v[12:15], v[44:47], v[72:75]
	v_mfma_f32_16x16x32_bf16 v[72:75], v[170:173], v[40:43], v[112:115]
	v_mfma_f32_16x16x32_bf16 v[108:111], v[176:179], v[44:47], v[72:75]
	v_mfma_f32_16x16x32_bf16 v[72:75], v[8:11], v[56:59], v[192:195]
	v_mfma_f32_16x16x32_bf16 v[88:91], v[12:15], v[180:183], v[72:75]
	v_mfma_f32_16x16x32_bf16 v[72:75], v[170:173], v[56:59], v[196:199]
	v_mfma_f32_16x16x32_bf16 v[92:95], v[176:179], v[180:183], v[72:75]
	v_mfma_f32_16x16x32_bf16 v[72:75], v[8:11], v[184:187], v[100:103]
	v_mfma_f32_16x16x32_bf16 v[76:79], v[170:173], v[184:187], v[96:99]
	v_mfma_f32_16x16x32_bf16 v[72:75], v[12:15], v[200:203], v[72:75]
	v_mfma_f32_16x16x32_bf16 v[76:79], v[176:179], v[200:203], v[76:79]
	s_barrier
; #define LDA(dst, b, h)                                                                                               \
;   _Pragma("unroll") for (int m = 0; m < 4; ++m) _Pragma("unroll") for (int k = 0; k < 2; ++k) dst[m][k] =            \
;       *reinterpret_cast<const bf16x8*>(SA(b, h) + lds_byte(wr * 64 + m * 16 + fr, k * 32 + fq * 8))
; #define LDB(dst, b, h)                                                                                               \
;   _Pragma("unroll") for (int n = 0; n < 2; ++n) _Pragma("unroll") for (int k = 0; k < 2; ++k) dst[n][k] =            \
;       *reinterpret_cast<const bf16x8*>(SB(b, h) + lds_byte(wc * 32 + n * 16 + fr, k * 32 + fq * 8))
; #define WAIT_V(n) asm volatile("s_waitcnt vmcnt(" #n ")" ::: "memory")
; #define WAIT_L(n) asm volatile("s_waitcnt lgkmcnt(" #n ")" ::: "memory")
; #define BAR __builtin_amdgcn_s_barrier()
; template <int EPI>
; __device__ __forceinline__ void gemm_phase(const u16* __restrict__ A, const u16* __restrict__ Bt, const int K,
;                                            const int nN, char* shm, const EpiArgs& ea) {
;     ...
;       LDB(B0, 1, 0); LDA(At, 1, 0); WAIT_V(2); BAR; WAIT_L(0); MMA(0, 0, At, B0); BAR;
;       LDB(B1, 1, 1); WAIT_V(0); BAR; WAIT_L(0); MMA(0, 1, At, B1); BAR;
;       LDA(At, 1, 1); BAR; WAIT_L(0); MMA(1, 0, At, B0); MMA(1, 1, At, B1); BAR;
;     }
;     if (wr == 0) BAR;
	ds_read_b128 v[192:195], v153
	ds_read_b128 v[196:199], v153 offset:1024
	ds_read_b128 v[204:207], v153 offset:2048
	ds_read_b128 v[220:223], v153 offset:3072
	s_waitcnt vmcnt(0)
	s_barrier
	s_waitcnt lgkmcnt(0)
	v_mfma_f32_16x16x32_bf16 v[96:99], v[192:195], v[24:27], v[208:211]
	v_mfma_f32_16x16x32_bf16 v[24:27], v[204:207], v[24:27], v[158:161]
	v_mfma_f32_16x16x32_bf16 v[112:115], v[220:223], v[28:31], v[24:27]
	v_mfma_f32_16x16x32_bf16 v[24:27], v[192:195], v[40:43], v[84:87]
	v_mfma_f32_16x16x32_bf16 v[100:103], v[196:199], v[44:47], v[24:27]
	v_mfma_f32_16x16x32_bf16 v[24:27], v[204:207], v[40:43], v[80:83]
	v_mfma_f32_16x16x32_bf16 v[116:119], v[196:199], v[28:31], v[96:99]
	v_mfma_f32_16x16x32_bf16 v[96:99], v[220:223], v[44:47], v[24:27]
	v_mfma_f32_16x16x32_bf16 v[24:27], v[192:195], v[56:59], v[162:165]
	v_mfma_f32_16x16x32_bf16 v[84:87], v[196:199], v[180:183], v[24:27]
	v_mfma_f32_16x16x32_bf16 v[24:27], v[204:207], v[56:59], v[166:169]
	v_mfma_f32_16x16x32_bf16 v[80:83], v[220:223], v[180:183], v[24:27]
	v_mfma_f32_16x16x32_bf16 v[24:27], v[192:195], v[184:187], v[68:71]
	v_mfma_f32_16x16x32_bf16 v[68:71], v[196:199], v[200:203], v[24:27]
	v_mfma_f32_16x16x32_bf16 v[24:27], v[204:207], v[184:187], v[64:67]
	v_mfma_f32_16x16x32_bf16 v[64:67], v[220:223], v[200:203], v[24:27]
	s_barrier
	ds_read_b128 v[158:161], v147 offset:49152
	ds_read_b128 v[162:165], v147 offset:50176
	ds_read_b128 v[166:169], v148 offset:49152
	ds_read_b128 v[180:183], v148 offset:50176
	ds_read_b128 v[184:187], v149 offset:49152
	ds_read_b128 v[200:203], v149 offset:50176
	ds_read_b128 v[208:211], v150 offset:49152
	ds_read_b128 v[224:227], v150 offset:50176
	s_barrier
	s_waitcnt lgkmcnt(0)
	v_mfma_f32_16x16x32_bf16 v[24:27], v[8:11], v[158:161], v[60:63]
	v_mfma_f32_16x16x32_bf16 v[56:59], v[12:15], v[162:165], v[24:27]
	v_mfma_f32_16x16x32_bf16 v[24:27], v[170:173], v[158:161], v[188:191]
	v_mfma_f32_16x16x32_bf16 v[60:63], v[176:179], v[162:165], v[24:27]
	v_mfma_f32_16x16x32_bf16 v[24:27], v[8:11], v[166:169], v[52:55]
	v_mfma_f32_16x16x32_bf16 v[40:43], v[12:15], v[180:183], v[24:27]
	v_mfma_f32_16x16x32_bf16 v[24:27], v[170:173], v[166:169], v[48:51]
	v_mfma_f32_16x16x32_bf16 v[44:47], v[176:179], v[180:183], v[24:27]
	v_mfma_f32_16x16x32_bf16 v[24:27], v[8:11], v[184:187], v[212:215]
	v_mfma_f32_16x16x32_bf16 v[8:11], v[8:11], v[208:211], v[36:39]
	v_mfma_f32_16x16x32_bf16 v[24:27], v[12:15], v[200:203], v[24:27]
	v_mfma_f32_16x16x32_bf16 v[28:31], v[170:173], v[184:187], v[216:219]
	v_mfma_f32_16x16x32_bf16 v[8:11], v[12:15], v[224:227], v[8:11]
	v_mfma_f32_16x16x32_bf16 v[12:15], v[170:173], v[208:211], v[32:35]
	v_mfma_f32_16x16x32_bf16 v[28:31], v[176:179], v[200:203], v[28:31]
	v_mfma_f32_16x16x32_bf16 v[12:15], v[176:179], v[224:227], v[12:15]
	v_mfma_f32_16x16x32_bf16 v[32:35], v[192:195], v[158:161], v[130:133]
	v_mfma_f32_16x16x32_bf16 v[52:55], v[196:199], v[162:165], v[32:35]
	v_mfma_f32_16x16x32_bf16 v[32:35], v[204:207], v[158:161], v[134:137]
	v_mfma_f32_16x16x32_bf16 v[16:19], v[204:207], v[166:169], v[16:19]
	v_mfma_f32_16x16x32_bf16 v[48:51], v[220:223], v[162:165], v[32:35]
	v_mfma_f32_16x16x32_bf16 v[20:23], v[192:195], v[166:169], v[20:23]
	v_mfma_f32_16x16x32_bf16 v[32:35], v[220:223], v[180:183], v[16:19]
	v_mfma_f32_16x16x32_bf16 v[16:19], v[192:195], v[184:187], v[138:141]
	v_mfma_f32_16x16x32_bf16 v[36:39], v[196:199], v[180:183], v[20:23]
	v_mfma_f32_16x16x32_bf16 v[20:23], v[196:199], v[200:203], v[16:19]
	v_mfma_f32_16x16x32_bf16 v[16:19], v[204:207], v[184:187], v[154:157]
	v_mfma_f32_16x16x32_bf16 v[4:7], v[192:195], v[208:211], v[4:7]
	v_mfma_f32_16x16x32_bf16 v[0:3], v[204:207], v[208:211], v[0:3]
	v_mfma_f32_16x16x32_bf16 v[16:19], v[220:223], v[200:203], v[16:19]
	v_mfma_f32_16x16x32_bf16 v[4:7], v[196:199], v[224:227], v[4:7]
	v_mfma_f32_16x16x32_bf16 v[0:3], v[220:223], v[224:227], v[0:3]
	s_andn2_b64 vcc, exec, s[18:19]
	s_barrier
	s_cbranch_vccnz .LBB0_495
	s_barrier

; #define LDA(dst, b, h)                                                                                               \
;   _Pragma("unroll") for (int m = 0; m < 4; ++m) _Pragma("unroll") for (int k = 0; k < 2; ++k) dst[m][k] =            \
;       *reinterpret_cast<const bf16x8*>(SA(b, h) + lds_byte(wr * 64 + m * 16 + fr, k * 32 + fq * 8))
; #define LDB(dst, b, h)                                                                                               \
;   _Pragma("unroll") for (int n = 0; n < 2; ++n) _Pragma("unroll") for (int k = 0; k < 2; ++k) dst[n][k] =            \
;       *reinterpret_cast<const bf16x8*>(SB(b, h) + lds_byte(wc * 32 + n * 16 + fr, k * 32 + fq * 8))
; #define WAIT_V(n) asm volatile("s_waitcnt vmcnt(" #n ")" ::: "memory")
; #define WAIT_L(n) asm volatile("s_waitcnt lgkmcnt(" #n ")" ::: "memory")
; #define BAR __builtin_amdgcn_s_barrier()
; #define SCHED __builtin_amdgcn_sched_barrier(0)
; template <int EPI>
; __device__ __forceinline__ void gemm_phase(const u16* __restrict__ A, const u16* __restrict__ Bt, const int K,
;                                            const int nN, char* shm, const EpiArgs& ea) {
;     ...
;       LDB(B0, 0, 0); SCHED; LDA(At, 0, 0); STAGE(SA(1, 1), rA, brow + HALF, t + 1);
;       WAIT_V(10); WAIT_L(8); BAR; WAIT_L(0); MMA(0, 0, At, B0); BAR; SCHED;
;       LDB(B1, 0, 1); STAGE(SB(0, 0), rB, bcol, t + 2);
;       WAIT_V(10); BAR; WAIT_L(0); MMA(0, 1, At, B1); BAR;
;       LDA(At, 0, 1); STAGE(SA(0, 0), rA, brow, t + 2);
;       BAR; WAIT_L(0); MMA(1, 0, At, B0); BAR; SCHED;
;       STAGE(SB(0, 1), rB, bcol + HALF, t + 2);
;       WAIT_V(10); BAR; MMA(1, 1, At, B1); BAR;
.LBB0_565:
	ds_read_b128 v[128:131], v183
	ds_read_b128 v[132:135], v183 offset:1024
	ds_read_b128 v[136:139], v183 offset:2048
	ds_read_b128 v[140:143], v183 offset:3072
	s_add_i32 s64, s58, s63
	s_mov_b32 m0, s46
	s_add_i32 s6, s64, 0x4000
	ds_read_b128 v[144:147], v184
	ds_read_b128 v[148:151], v184 offset:1024
	ds_read_b128 v[152:155], v185
	ds_read_b128 v[156:159], v185 offset:1024
	ds_read_b128 v[160:163], v186
	ds_read_b128 v[164:167], v186 offset:1024
	ds_read_b128 v[168:171], v187
	ds_read_b128 v[192:195], v187 offset:1024
	buffer_load_dwordx4 v175, s[0:3], s6 offen lds
	s_add_i32 s6, s64, 0x6000
	s_mov_b32 m0, s47
	s_nop 0
	buffer_load_dwordx4 v175, s[0:3], s6 offen lds
	s_waitcnt vmcnt(10)
	s_waitcnt lgkmcnt(8)
	s_barrier
	s_waitcnt lgkmcnt(0)
	v_mfma_f32_16x16x32_bf16 v[124:127], v[128:131], v[144:147], v[124:127]
	v_mfma_f32_16x16x32_bf16 v[120:123], v[136:139], v[144:147], v[120:123]
	v_mfma_f32_16x16x32_bf16 v[116:119], v[128:131], v[152:155], v[116:119]
	v_mfma_f32_16x16x32_bf16 v[112:115], v[136:139], v[152:155], v[112:115]
	v_mfma_f32_16x16x32_bf16 v[108:111], v[128:131], v[160:163], v[108:111]
	v_mfma_f32_16x16x32_bf16 v[104:107], v[136:139], v[160:163], v[104:107]
	v_mfma_f32_16x16x32_bf16 v[100:103], v[128:131], v[168:171], v[100:103]
	v_mfma_f32_16x16x32_bf16 v[96:99], v[136:139], v[168:171], v[96:99]
	v_mfma_f32_16x16x32_bf16 v[124:127], v[132:135], v[148:151], v[124:127]
	v_mfma_f32_16x16x32_bf16 v[120:123], v[140:143], v[148:151], v[120:123]
	v_mfma_f32_16x16x32_bf16 v[116:119], v[132:135], v[156:159], v[116:119]
	v_mfma_f32_16x16x32_bf16 v[112:115], v[140:143], v[156:159], v[112:115]
	v_mfma_f32_16x16x32_bf16 v[108:111], v[132:135], v[164:167], v[108:111]
	v_mfma_f32_16x16x32_bf16 v[104:107], v[140:143], v[164:167], v[104:107]
	v_mfma_f32_16x16x32_bf16 v[100:103], v[132:135], v[192:195], v[100:103]
	v_mfma_f32_16x16x32_bf16 v[96:99], v[140:143], v[192:195], v[96:99]
	s_barrier
	s_add_i32 s65, s61, s63
	s_mov_b32 m0, s30
	s_add_i32 s66, s65, 0x8000
	s_mov_b32 s6, s2
	s_mov_b32 s7, s3
	ds_read_b128 v[196:199], v188
	ds_read_b128 v[200:203], v188 offset:1024
	ds_read_b128 v[204:207], v188 offset:2048
	ds_read_b128 v[208:211], v188 offset:3072
	buffer_load_dwordx4 v175, s[4:7], s66 offen lds
	s_add_i32 s66, s65, 0xa000
	s_mov_b32 m0, s31
	s_nop 0
	buffer_load_dwordx4 v175, s[4:7], s66 offen lds
	s_waitcnt vmcnt(10)
	s_barrier
	s_waitcnt lgkmcnt(0)
	v_mfma_f32_16x16x32_bf16 v[92:95], v[196:199], v[144:147], v[92:95]
	v_mfma_f32_16x16x32_bf16 v[88:91], v[204:207], v[144:147], v[88:91]
	v_mfma_f32_16x16x32_bf16 v[84:87], v[196:199], v[152:155], v[84:87]
	v_mfma_f32_16x16x32_bf16 v[80:83], v[204:207], v[152:155], v[80:83]
	v_mfma_f32_16x16x32_bf16 v[76:79], v[196:199], v[160:163], v[76:79]
	v_mfma_f32_16x16x32_bf16 v[72:75], v[204:207], v[160:163], v[72:75]
	v_mfma_f32_16x16x32_bf16 v[68:71], v[196:199], v[168:171], v[68:71]
	v_mfma_f32_16x16x32_bf16 v[64:67], v[204:207], v[168:171], v[64:67]
	v_mfma_f32_16x16x32_bf16 v[92:95], v[200:203], v[148:151], v[92:95]
	v_mfma_f32_16x16x32_bf16 v[88:91], v[208:211], v[148:151], v[88:91]
	v_mfma_f32_16x16x32_bf16 v[84:87], v[200:203], v[156:159], v[84:87]
	v_mfma_f32_16x16x32_bf16 v[80:83], v[208:211], v[156:159], v[80:83]
	v_mfma_f32_16x16x32_bf16 v[76:79], v[200:203], v[164:167], v[76:79]
	v_mfma_f32_16x16x32_bf16 v[72:75], v[208:211], v[164:167], v[72:75]
	v_mfma_f32_16x16x32_bf16 v[68:71], v[200:203], v[192:195], v[68:71]
	v_mfma_f32_16x16x32_bf16 v[64:67], v[208:211], v[192:195], v[64:67]
	s_add_i32 s66, s60, s63
	s_mov_b32 m0, s33
	s_add_i32 s67, s66, 0x8000
	s_barrier
	ds_read_b128 v[144:147], v184 offset:16384
	ds_read_b128 v[148:151], v184 offset:17408
	ds_read_b128 v[152:155], v185 offset:16384
	ds_read_b128 v[156:159], v185 offset:17408
	ds_read_b128 v[160:163], v186 offset:16384
	ds_read_b128 v[164:167], v186 offset:17408
	ds_read_b128 v[168:171], v187 offset:16384
	ds_read_b128 v[192:195], v187 offset:17408
	buffer_load_dwordx4 v175, s[0:3], s67 offen lds
	s_add_i32 s67, s66, 0xa000
	s_mov_b32 m0, s34
	s_nop 0
	buffer_load_dwordx4 v175, s[0:3], s67 offen lds
	s_barrier
	s_waitcnt lgkmcnt(0)
	v_mfma_f32_16x16x32_bf16 v[60:63], v[128:131], v[144:147], v[60:63]
	v_mfma_f32_16x16x32_bf16 v[56:59], v[136:139], v[144:147], v[56:59]
	v_mfma_f32_16x16x32_bf16 v[52:55], v[128:131], v[152:155], v[52:55]
	v_mfma_f32_16x16x32_bf16 v[48:51], v[136:139], v[152:155], v[48:51]
	v_mfma_f32_16x16x32_bf16 v[44:47], v[128:131], v[160:163], v[44:47]
	v_mfma_f32_16x16x32_bf16 v[40:43], v[136:139], v[160:163], v[40:43]
	v_mfma_f32_16x16x32_bf16 v[36:39], v[128:131], v[168:171], v[36:39]
	v_mfma_f32_16x16x32_bf16 v[32:35], v[136:139], v[168:171], v[32:35]
	v_mfma_f32_16x16x32_bf16 v[60:63], v[132:135], v[148:151], v[60:63]
	v_mfma_f32_16x16x32_bf16 v[56:59], v[140:143], v[148:151], v[56:59]
	v_mfma_f32_16x16x32_bf16 v[52:55], v[132:135], v[156:159], v[52:55]
	v_mfma_f32_16x16x32_bf16 v[48:51], v[140:143], v[156:159], v[48:51]
	v_mfma_f32_16x16x32_bf16 v[44:47], v[132:135], v[164:167], v[44:47]
	v_mfma_f32_16x16x32_bf16 v[40:43], v[140:143], v[164:167], v[40:43]
	v_mfma_f32_16x16x32_bf16 v[36:39], v[132:135], v[192:195], v[36:39]
	v_mfma_f32_16x16x32_bf16 v[32:35], v[140:143], v[192:195], v[32:35]
	s_barrier
	s_add_i32 s67, s59, s63
	s_mov_b32 m0, s35
	s_add_i32 s68, s67, 0x8000
	buffer_load_dwordx4 v175, s[4:7], s68 offen lds
	s_add_i32 s68, s67, 0xa000
	s_mov_b32 m0, s36
	s_nop 0
	buffer_load_dwordx4 v175, s[4:7], s68 offen lds
	s_waitcnt vmcnt(10)
	s_barrier
; #define LDA(dst, b, h)                                                                                               \
;   _Pragma("unroll") for (int m = 0; m < 4; ++m) _Pragma("unroll") for (int k = 0; k < 2; ++k) dst[m][k] =            \
;       *reinterpret_cast<const bf16x8*>(SA(b, h) + lds_byte(wr * 64 + m * 16 + fr, k * 32 + fq * 8))
; #define LDB(dst, b, h)                                                                                               \
;   _Pragma("unroll") for (int n = 0; n < 2; ++n) _Pragma("unroll") for (int k = 0; k < 2; ++k) dst[n][k] =            \
;       *reinterpret_cast<const bf16x8*>(SB(b, h) + lds_byte(wc * 32 + n * 16 + fr, k * 32 + fq * 8))
; #define WAIT_V(n) asm volatile("s_waitcnt vmcnt(" #n ")" ::: "memory")
; #define WAIT_L(n) asm volatile("s_waitcnt lgkmcnt(" #n ")" ::: "memory")
; #define BAR __builtin_amdgcn_s_barrier()
; #define SCHED __builtin_amdgcn_sched_barrier(0)
; template <int EPI>
; __device__ __forceinline__ void gemm_phase(const u16* __restrict__ A, const u16* __restrict__ Bt, const int K,
;                                            const int nN, char* shm, const EpiArgs& ea) {
;     ...
;       WAIT_V(10); BAR; MMA(1, 1, At, B1); BAR;
;       LDB(B0, 1, 0); SCHED; LDA(At, 1, 0); STAGE(SA(0, 1), rA, brow + HALF, t + 2);
;       WAIT_V(10); WAIT_L(8); BAR; WAIT_L(0); MMA(0, 0, At, B0); BAR; SCHED;
;       LDB(B1, 1, 1); STAGE(SB(1, 0), rB, bcol, t + 3);
;       WAIT_V(10); BAR; WAIT_L(0); MMA(0, 1, At, B1); BAR;
	v_mfma_f32_16x16x32_bf16 v[28:31], v[196:199], v[144:147], v[28:31]
	v_mfma_f32_16x16x32_bf16 v[24:27], v[204:207], v[144:147], v[24:27]
	v_mfma_f32_16x16x32_bf16 v[20:23], v[196:199], v[152:155], v[20:23]
	v_mfma_f32_16x16x32_bf16 v[16:19], v[204:207], v[152:155], v[16:19]
	v_mfma_f32_16x16x32_bf16 v[12:15], v[196:199], v[160:163], v[12:15]
	v_mfma_f32_16x16x32_bf16 v[8:11], v[204:207], v[160:163], v[8:11]
	v_mfma_f32_16x16x32_bf16 v[4:7], v[196:199], v[168:171], v[4:7]
	v_mfma_f32_16x16x32_bf16 v[0:3], v[204:207], v[168:171], v[0:3]
	v_mfma_f32_16x16x32_bf16 v[28:31], v[200:203], v[148:151], v[28:31]
	v_mfma_f32_16x16x32_bf16 v[24:27], v[208:211], v[148:151], v[24:27]
	v_mfma_f32_16x16x32_bf16 v[20:23], v[200:203], v[156:159], v[20:23]
	v_mfma_f32_16x16x32_bf16 v[16:19], v[208:211], v[156:159], v[16:19]
	v_mfma_f32_16x16x32_bf16 v[12:15], v[200:203], v[164:167], v[12:15]
	v_mfma_f32_16x16x32_bf16 v[8:11], v[208:211], v[164:167], v[8:11]
	v_mfma_f32_16x16x32_bf16 v[4:7], v[200:203], v[192:195], v[4:7]
	v_mfma_f32_16x16x32_bf16 v[0:3], v[208:211], v[192:195], v[0:3]
	s_barrier
	ds_read_b128 v[128:131], v189
	ds_read_b128 v[132:135], v189 offset:1024
	ds_read_b128 v[136:139], v189 offset:2048
	ds_read_b128 v[140:143], v189 offset:3072
	s_mov_b32 m0, s37
	s_add_i32 s68, s64, 0x8000
	ds_read_b128 v[144:147], v184 offset:32768
	ds_read_b128 v[148:151], v184 offset:33792
	ds_read_b128 v[152:155], v185 offset:32768
	ds_read_b128 v[156:159], v185 offset:33792
	ds_read_b128 v[160:163], v186 offset:32768
	ds_read_b128 v[164:167], v186 offset:33792
	ds_read_b128 v[168:171], v187 offset:32768
	ds_read_b128 v[192:195], v187 offset:33792
	buffer_load_dwordx4 v175, s[0:3], s68 offen lds
	s_add_i32 s64, s64, 0xa000
	s_mov_b32 m0, s38
	s_nop 0
	buffer_load_dwordx4 v175, s[0:3], s64 offen lds
	s_waitcnt vmcnt(10)
	s_waitcnt lgkmcnt(8)
	s_barrier
	s_waitcnt lgkmcnt(0)
	v_mfma_f32_16x16x32_bf16 v[124:127], v[128:131], v[144:147], v[124:127]
	v_mfma_f32_16x16x32_bf16 v[120:123], v[136:139], v[144:147], v[120:123]
	v_mfma_f32_16x16x32_bf16 v[116:119], v[128:131], v[152:155], v[116:119]
	v_mfma_f32_16x16x32_bf16 v[112:115], v[136:139], v[152:155], v[112:115]
	v_mfma_f32_16x16x32_bf16 v[108:111], v[128:131], v[160:163], v[108:111]
	v_mfma_f32_16x16x32_bf16 v[104:107], v[136:139], v[160:163], v[104:107]
	v_mfma_f32_16x16x32_bf16 v[100:103], v[128:131], v[168:171], v[100:103]
	v_mfma_f32_16x16x32_bf16 v[96:99], v[136:139], v[168:171], v[96:99]
	v_mfma_f32_16x16x32_bf16 v[124:127], v[132:135], v[148:151], v[124:127]
	v_mfma_f32_16x16x32_bf16 v[120:123], v[140:143], v[148:151], v[120:123]
	v_mfma_f32_16x16x32_bf16 v[116:119], v[132:135], v[156:159], v[116:119]
	v_mfma_f32_16x16x32_bf16 v[112:115], v[140:143], v[156:159], v[112:115]
	v_mfma_f32_16x16x32_bf16 v[108:111], v[132:135], v[164:167], v[108:111]
	v_mfma_f32_16x16x32_bf16 v[104:107], v[140:143], v[164:167], v[104:107]
	v_mfma_f32_16x16x32_bf16 v[100:103], v[132:135], v[192:195], v[100:103]
	v_mfma_f32_16x16x32_bf16 v[96:99], v[140:143], v[192:195], v[96:99]
	s_barrier
	s_mov_b32 m0, s39
	s_add_i32 s64, s65, 0xc000
	ds_read_b128 v[196:199], v190
	ds_read_b128 v[200:203], v190 offset:1024
	ds_read_b128 v[204:207], v190 offset:2048
	ds_read_b128 v[208:211], v190 offset:3072
	buffer_load_dwordx4 v175, s[4:7], s64 offen lds
	s_add_i32 s65, s65, 0xe000
	s_mov_b32 m0, s40
	s_nop 0
	buffer_load_dwordx4 v175, s[4:7], s65 offen lds
	s_waitcnt vmcnt(10)
	s_barrier
; #define LDA(dst, b, h)                                                                                               \
;   _Pragma("unroll") for (int m = 0; m < 4; ++m) _Pragma("unroll") for (int k = 0; k < 2; ++k) dst[m][k] =            \
;       *reinterpret_cast<const bf16x8*>(SA(b, h) + lds_byte(wr * 64 + m * 16 + fr, k * 32 + fq * 8))
; #define WAIT_V(n) asm volatile("s_waitcnt vmcnt(" #n ")" ::: "memory")
; #define WAIT_L(n) asm volatile("s_waitcnt lgkmcnt(" #n ")" ::: "memory")
; #define BAR __builtin_amdgcn_s_barrier()
; #define SCHED __builtin_amdgcn_sched_barrier(0)
; template <int EPI>
; __device__ __forceinline__ void gemm_phase(const u16* __restrict__ A, const u16* __restrict__ Bt, const int K,
;                                            const int nN, char* shm, const EpiArgs& ea) {
;     ...
;       WAIT_V(10); BAR; WAIT_L(0); MMA(0, 1, At, B1); BAR;
;       LDA(At, 1, 1); STAGE(SA(1, 0), rA, brow, t + 3);
;       BAR; WAIT_L(0); MMA(1, 0, At, B0); BAR; SCHED;
;       STAGE(SB(1, 1), rB, bcol + HALF, t + 3);
;       WAIT_V(10); BAR; MMA(1, 1, At, B1); BAR;
;     }
;     float eC = 0.f, eB = 0.f;
;     float2 eS = make_float2(0.f, 0.f);
;     if (EPI == EPI_IN || EPI == EPI_SWIGLU_LN) {
;       if (wr == 0) {
;         eC = ea.c1[bcol + tid];
;         eS = *(const float2*)(ea.st_in + (size_t)(brow + tid) * 2);
;       } else {
;         eC = ea.c2[bcol + tid - 256];
;         if (EPI == EPI_IN) eB = ea.bias[bcol + tid - 256];
;       }
;     }
	s_waitcnt lgkmcnt(0)
	v_mfma_f32_16x16x32_bf16 v[92:95], v[196:199], v[144:147], v[92:95]
	v_mfma_f32_16x16x32_bf16 v[88:91], v[204:207], v[144:147], v[88:91]
	v_mfma_f32_16x16x32_bf16 v[84:87], v[196:199], v[152:155], v[84:87]
	v_mfma_f32_16x16x32_bf16 v[80:83], v[204:207], v[152:155], v[80:83]
	v_mfma_f32_16x16x32_bf16 v[76:79], v[196:199], v[160:163], v[76:79]
	v_mfma_f32_16x16x32_bf16 v[72:75], v[204:207], v[160:163], v[72:75]
	v_mfma_f32_16x16x32_bf16 v[68:71], v[196:199], v[168:171], v[68:71]
	v_mfma_f32_16x16x32_bf16 v[64:67], v[204:207], v[168:171], v[64:67]
	v_mfma_f32_16x16x32_bf16 v[92:95], v[200:203], v[148:151], v[92:95]
	v_mfma_f32_16x16x32_bf16 v[88:91], v[208:211], v[148:151], v[88:91]
	v_mfma_f32_16x16x32_bf16 v[84:87], v[200:203], v[156:159], v[84:87]
	v_mfma_f32_16x16x32_bf16 v[80:83], v[208:211], v[156:159], v[80:83]
	v_mfma_f32_16x16x32_bf16 v[76:79], v[200:203], v[164:167], v[76:79]
	v_mfma_f32_16x16x32_bf16 v[72:75], v[208:211], v[164:167], v[72:75]
	v_mfma_f32_16x16x32_bf16 v[68:71], v[200:203], v[192:195], v[68:71]
	v_mfma_f32_16x16x32_bf16 v[64:67], v[208:211], v[192:195], v[64:67]
	s_mov_b32 m0, s41
	s_add_i32 s64, s66, 0xc000
	s_barrier
	ds_read_b128 v[144:147], v184 offset:49152
	ds_read_b128 v[148:151], v184 offset:50176
	ds_read_b128 v[152:155], v185 offset:49152
	ds_read_b128 v[156:159], v185 offset:50176
	ds_read_b128 v[160:163], v186 offset:49152
	ds_read_b128 v[164:167], v186 offset:50176
	ds_read_b128 v[168:171], v187 offset:49152
	ds_read_b128 v[192:195], v187 offset:50176
	buffer_load_dwordx4 v175, s[0:3], s64 offen lds
	s_add_i32 s66, s66, 0xe000
	s_mov_b32 m0, s42
	s_nop 0
	buffer_load_dwordx4 v175, s[0:3], s66 offen lds
	s_barrier
	s_waitcnt lgkmcnt(0)
	v_mfma_f32_16x16x32_bf16 v[60:63], v[128:131], v[144:147], v[60:63]
	v_mfma_f32_16x16x32_bf16 v[56:59], v[136:139], v[144:147], v[56:59]
	v_mfma_f32_16x16x32_bf16 v[52:55], v[128:131], v[152:155], v[52:55]
	v_mfma_f32_16x16x32_bf16 v[48:51], v[136:139], v[152:155], v[48:51]
	v_mfma_f32_16x16x32_bf16 v[44:47], v[128:131], v[160:163], v[44:47]
	v_mfma_f32_16x16x32_bf16 v[40:43], v[136:139], v[160:163], v[40:43]
	v_mfma_f32_16x16x32_bf16 v[36:39], v[128:131], v[168:171], v[36:39]
	v_mfma_f32_16x16x32_bf16 v[32:35], v[136:139], v[168:171], v[32:35]
	v_mfma_f32_16x16x32_bf16 v[60:63], v[132:135], v[148:151], v[60:63]
	v_mfma_f32_16x16x32_bf16 v[56:59], v[140:143], v[148:151], v[56:59]
	v_mfma_f32_16x16x32_bf16 v[52:55], v[132:135], v[156:159], v[52:55]
	v_mfma_f32_16x16x32_bf16 v[48:51], v[140:143], v[156:159], v[48:51]
	v_mfma_f32_16x16x32_bf16 v[44:47], v[132:135], v[164:167], v[44:47]
	v_mfma_f32_16x16x32_bf16 v[40:43], v[140:143], v[164:167], v[40:43]
	v_mfma_f32_16x16x32_bf16 v[36:39], v[132:135], v[192:195], v[36:39]
	v_mfma_f32_16x16x32_bf16 v[32:35], v[140:143], v[192:195], v[32:35]
	s_barrier
	s_mov_b32 m0, s43
	s_add_i32 s64, s67, 0xc000
	buffer_load_dwordx4 v175, s[4:7], s64 offen lds
	s_add_i32 s67, s67, 0xe000
	s_mov_b32 m0, s44
	s_nop 0
	buffer_load_dwordx4 v175, s[4:7], s67 offen lds
	s_waitcnt vmcnt(10)
	s_barrier
	v_mfma_f32_16x16x32_bf16 v[28:31], v[196:199], v[144:147], v[28:31]
	v_mfma_f32_16x16x32_bf16 v[24:27], v[204:207], v[144:147], v[24:27]
	v_mfma_f32_16x16x32_bf16 v[20:23], v[196:199], v[152:155], v[20:23]
	v_mfma_f32_16x16x32_bf16 v[16:19], v[204:207], v[152:155], v[16:19]
	v_mfma_f32_16x16x32_bf16 v[12:15], v[196:199], v[160:163], v[12:15]
	v_mfma_f32_16x16x32_bf16 v[8:11], v[204:207], v[160:163], v[8:11]
	v_mfma_f32_16x16x32_bf16 v[4:7], v[196:199], v[168:171], v[4:7]
	v_mfma_f32_16x16x32_bf16 v[0:3], v[204:207], v[168:171], v[0:3]
	v_mfma_f32_16x16x32_bf16 v[28:31], v[200:203], v[148:151], v[28:31]
	v_mfma_f32_16x16x32_bf16 v[24:27], v[208:211], v[148:151], v[24:27]
	v_mfma_f32_16x16x32_bf16 v[20:23], v[200:203], v[156:159], v[20:23]
	v_mfma_f32_16x16x32_bf16 v[16:19], v[208:211], v[156:159], v[16:19]
	v_mfma_f32_16x16x32_bf16 v[12:15], v[200:203], v[164:167], v[12:15]
	v_mfma_f32_16x16x32_bf16 v[8:11], v[208:211], v[164:167], v[8:11]
	v_mfma_f32_16x16x32_bf16 v[4:7], v[200:203], v[192:195], v[4:7]
	v_mfma_f32_16x16x32_bf16 v[0:3], v[208:211], v[192:195], v[0:3]
	s_add_i32 s62, s62, 2
	s_add_i32 s63, s63, 0x8000
	s_cmp_lt_u32 s62, 28
	s_barrier
	s_cbranch_scc1 .LBB0_565
	v_add_u32_e32 v128, s57, v174
	v_ashrrev_i32_e32 v129, 31, v128
	s_mov_b64 s[6:7], -1
	s_and_b64 vcc, exec, s[18:19]
	s_cbranch_vccz .LBB0_568
	v_lshl_add_u64 v[130:131], v[128:129], 2, s[90:91]
	v_lshl_add_u64 v[130:131], v[130:131], 0, s[20:21]
	s_mov_b64 s[6:7], 0

; #define LDA(dst, b, h)                                                                                               \
;   _Pragma("unroll") for (int m = 0; m < 4; ++m) _Pragma("unroll") for (int k = 0; k < 2; ++k) dst[m][k] =            \
;       *reinterpret_cast<const bf16x8*>(SA(b, h) + lds_byte(wr * 64 + m * 16 + fr, k * 32 + fq * 8))
; #define LDB(dst, b, h)                                                                                               \
;   _Pragma("unroll") for (int n = 0; n < 2; ++n) _Pragma("unroll") for (int k = 0; k < 2; ++k) dst[n][k] =            \
;       *reinterpret_cast<const bf16x8*>(SB(b, h) + lds_byte(wc * 32 + n * 16 + fr, k * 32 + fq * 8))
; #define WAIT_V(n) asm volatile("s_waitcnt vmcnt(" #n ")" ::: "memory")
; #define WAIT_L(n) asm volatile("s_waitcnt lgkmcnt(" #n ")" ::: "memory")
; #define BAR __builtin_amdgcn_s_barrier()
; template <int EPI>
; __device__ __forceinline__ void gemm_phase(const u16* __restrict__ A, const u16* __restrict__ Bt, const int K,
;                                            const int nN, char* shm, const EpiArgs& ea) {
;     ...
;         eC = ea.c1[bcol + tid];
;         eS = *(const float2*)(ea.st_in + (size_t)(brow + tid) * 2);
;       } else {
;         eC = ea.c2[bcol + tid - 256];
;         if (EPI == EPI_IN) eB = ea.bias[bcol + tid - 256];
;       }
;     }
;     {
;       LDB(B0, 0, 0); LDA(At, 0, 0); STAGE(SA(1, 1), rA, brow + HALF, nt - 1);
;       WAIT_V(10); BAR; WAIT_L(0); MMA(0, 0, At, B0); BAR;
;       LDB(B1, 0, 1); WAIT_V(8); BAR; WAIT_L(0); MMA(0, 1, At, B1); BAR;
;       LDA(At, 0, 1); WAIT_V(4); BAR; WAIT_L(0); MMA(1, 0, At, B0); MMA(1, 1, At, B1); BAR;
;     }
.LBB0_570:
	s_mov_b32 m0, s46
	s_add_i32 s6, s58, 0x7c000
	global_load_dword v154, v[130:131], off
	ds_read_b128 v[128:131], v183
	ds_read_b128 v[132:135], v183 offset:1024
	ds_read_b128 v[136:139], v183 offset:2048
	ds_read_b128 v[140:143], v183 offset:3072
	ds_read_b128 v[144:147], v184
	ds_read_b128 v[148:151], v184 offset:1024
	ds_read_b128 v[156:159], v185
	ds_read_b128 v[160:163], v185 offset:1024
	ds_read_b128 v[164:167], v186
	ds_read_b128 v[168:171], v186 offset:1024
	ds_read_b128 v[192:195], v187
	ds_read_b128 v[196:199], v187 offset:1024
	buffer_load_dwordx4 v175, s[0:3], s6 offen lds
	s_add_i32 s58, s58, 0x7e000
	s_mov_b32 m0, s47
	s_nop 0
	buffer_load_dwordx4 v175, s[0:3], s58 offen lds
	s_waitcnt vmcnt(10)
	s_barrier
	s_waitcnt lgkmcnt(0)
	v_mfma_f32_16x16x32_bf16 v[124:127], v[128:131], v[144:147], v[124:127]
	v_mfma_f32_16x16x32_bf16 v[120:123], v[136:139], v[144:147], v[120:123]
	v_mfma_f32_16x16x32_bf16 v[116:119], v[128:131], v[156:159], v[116:119]
	v_mfma_f32_16x16x32_bf16 v[112:115], v[136:139], v[156:159], v[112:115]
	v_mfma_f32_16x16x32_bf16 v[108:111], v[128:131], v[164:167], v[108:111]
	v_mfma_f32_16x16x32_bf16 v[104:107], v[136:139], v[164:167], v[104:107]
	v_mfma_f32_16x16x32_bf16 v[100:103], v[128:131], v[192:195], v[100:103]
	v_mfma_f32_16x16x32_bf16 v[96:99], v[136:139], v[192:195], v[96:99]
	v_mfma_f32_16x16x32_bf16 v[124:127], v[132:135], v[148:151], v[124:127]
	v_mfma_f32_16x16x32_bf16 v[120:123], v[140:143], v[148:151], v[120:123]
	v_mfma_f32_16x16x32_bf16 v[116:119], v[132:135], v[160:163], v[116:119]
	v_mfma_f32_16x16x32_bf16 v[112:115], v[140:143], v[160:163], v[112:115]
	v_mfma_f32_16x16x32_bf16 v[108:111], v[132:135], v[168:171], v[108:111]
	v_mfma_f32_16x16x32_bf16 v[104:107], v[140:143], v[168:171], v[104:107]
	v_mfma_f32_16x16x32_bf16 v[100:103], v[132:135], v[196:199], v[100:103]
	v_mfma_f32_16x16x32_bf16 v[96:99], v[140:143], v[196:199], v[96:99]
	s_barrier
	ds_read_b128 v[200:203], v188
	ds_read_b128 v[204:207], v188 offset:1024
	ds_read_b128 v[208:211], v188 offset:2048
	ds_read_b128 v[212:215], v188 offset:3072
	s_waitcnt vmcnt(8)
	s_barrier
	s_waitcnt lgkmcnt(0)
	v_mfma_f32_16x16x32_bf16 v[92:95], v[200:203], v[144:147], v[92:95]
	v_mfma_f32_16x16x32_bf16 v[88:91], v[208:211], v[144:147], v[88:91]
	v_mfma_f32_16x16x32_bf16 v[84:87], v[200:203], v[156:159], v[84:87]
	v_mfma_f32_16x16x32_bf16 v[80:83], v[208:211], v[156:159], v[80:83]
	v_mfma_f32_16x16x32_bf16 v[76:79], v[200:203], v[164:167], v[76:79]
	v_mfma_f32_16x16x32_bf16 v[72:75], v[208:211], v[164:167], v[72:75]
	v_mfma_f32_16x16x32_bf16 v[68:71], v[200:203], v[192:195], v[68:71]
	v_mfma_f32_16x16x32_bf16 v[92:95], v[204:207], v[148:151], v[92:95]
	v_mfma_f32_16x16x32_bf16 v[88:91], v[212:215], v[148:151], v[88:91]
	v_mfma_f32_16x16x32_bf16 v[84:87], v[204:207], v[160:163], v[84:87]
	v_mfma_f32_16x16x32_bf16 v[80:83], v[212:215], v[160:163], v[80:83]
	v_mfma_f32_16x16x32_bf16 v[76:79], v[204:207], v[168:171], v[76:79]
	v_mfma_f32_16x16x32_bf16 v[72:75], v[212:215], v[168:171], v[72:75]
	v_mfma_f32_16x16x32_bf16 v[68:71], v[204:207], v[196:199], v[68:71]
	v_mfma_f32_16x16x32_bf16 v[64:67], v[208:211], v[192:195], v[64:67]
	v_mfma_f32_16x16x32_bf16 v[64:67], v[212:215], v[196:199], v[64:67]
	s_barrier
	ds_read_b128 v[144:147], v184 offset:16384
	ds_read_b128 v[148:151], v184 offset:17408
	ds_read_b128 v[156:159], v185 offset:16384
	ds_read_b128 v[160:163], v185 offset:17408
	ds_read_b128 v[164:167], v186 offset:16384
	ds_read_b128 v[168:171], v186 offset:17408
	ds_read_b128 v[192:195], v187 offset:16384
	ds_read_b128 v[196:199], v187 offset:17408
	s_waitcnt vmcnt(4)
	s_barrier
	s_waitcnt lgkmcnt(0)
	v_mfma_f32_16x16x32_bf16 v[40:43], v[136:139], v[164:167], v[40:43]
	v_mfma_f32_16x16x32_bf16 v[36:39], v[128:131], v[192:195], v[36:39]
	v_mfma_f32_16x16x32_bf16 v[60:63], v[128:131], v[144:147], v[60:63]
	v_mfma_f32_16x16x32_bf16 v[56:59], v[136:139], v[144:147], v[56:59]
	v_mfma_f32_16x16x32_bf16 v[52:55], v[128:131], v[156:159], v[52:55]
	v_mfma_f32_16x16x32_bf16 v[48:51], v[136:139], v[156:159], v[48:51]
	v_mfma_f32_16x16x32_bf16 v[44:47], v[128:131], v[164:167], v[44:47]
	v_mfma_f32_16x16x32_bf16 v[40:43], v[140:143], v[168:171], v[40:43]
	v_mfma_f32_16x16x32_bf16 v[36:39], v[132:135], v[196:199], v[36:39]
	v_mfma_f32_16x16x32_bf16 v[32:35], v[136:139], v[192:195], v[32:35]
	v_mfma_f32_16x16x32_bf16 v[60:63], v[132:135], v[148:151], v[60:63]
	v_mfma_f32_16x16x32_bf16 v[56:59], v[140:143], v[148:151], v[56:59]
	v_mfma_f32_16x16x32_bf16 v[52:55], v[132:135], v[160:163], v[52:55]
	v_mfma_f32_16x16x32_bf16 v[48:51], v[140:143], v[160:163], v[48:51]
	v_mfma_f32_16x16x32_bf16 v[44:47], v[132:135], v[168:171], v[44:47]
	v_mfma_f32_16x16x32_bf16 v[32:35], v[140:143], v[196:199], v[32:35]
	v_mfma_f32_16x16x32_bf16 v[12:15], v[200:203], v[164:167], v[12:15]
	v_mfma_f32_16x16x32_bf16 v[8:11], v[208:211], v[164:167], v[8:11]
	v_mfma_f32_16x16x32_bf16 v[4:7], v[200:203], v[192:195], v[4:7]
	v_mfma_f32_16x16x32_bf16 v[0:3], v[208:211], v[192:195], v[0:3]
	v_mfma_f32_16x16x32_bf16 v[28:31], v[200:203], v[144:147], v[28:31]
	v_mfma_f32_16x16x32_bf16 v[24:27], v[208:211], v[144:147], v[24:27]
	v_mfma_f32_16x16x32_bf16 v[20:23], v[200:203], v[156:159], v[20:23]
	v_mfma_f32_16x16x32_bf16 v[16:19], v[208:211], v[156:159], v[16:19]
	v_mfma_f32_16x16x32_bf16 v[12:15], v[204:207], v[168:171], v[12:15]
	v_mfma_f32_16x16x32_bf16 v[8:11], v[212:215], v[168:171], v[8:11]
	v_mfma_f32_16x16x32_bf16 v[4:7], v[204:207], v[196:199], v[4:7]
	v_mfma_f32_16x16x32_bf16 v[0:3], v[212:215], v[196:199], v[0:3]
	v_mfma_f32_16x16x32_bf16 v[216:219], v[204:207], v[148:151], v[28:31]
	v_mfma_f32_16x16x32_bf16 v[220:223], v[212:215], v[148:151], v[24:27]
	v_mfma_f32_16x16x32_bf16 v[224:227], v[204:207], v[160:163], v[20:23]
	v_mfma_f32_16x16x32_bf16 v[160:163], v[212:215], v[160:163], v[16:19]
	s_barrier
; #define LDA(dst, b, h)                                                                                               \
;   _Pragma("unroll") for (int m = 0; m < 4; ++m) _Pragma("unroll") for (int k = 0; k < 2; ++k) dst[m][k] =            \
;       *reinterpret_cast<const bf16x8*>(SA(b, h) + lds_byte(wr * 64 + m * 16 + fr, k * 32 + fq * 8))
; #define LDB(dst, b, h)                                                                                               \
;   _Pragma("unroll") for (int n = 0; n < 2; ++n) _Pragma("unroll") for (int k = 0; k < 2; ++k) dst[n][k] =            \
;       *reinterpret_cast<const bf16x8*>(SB(b, h) + lds_byte(wc * 32 + n * 16 + fr, k * 32 + fq * 8))
; #define WAIT_V(n) asm volatile("s_waitcnt vmcnt(" #n ")" ::: "memory")
; #define WAIT_L(n) asm volatile("s_waitcnt lgkmcnt(" #n ")" ::: "memory")
; #define BAR __builtin_amdgcn_s_barrier()
; template <int EPI>
; __device__ __forceinline__ void gemm_phase(const u16* __restrict__ A, const u16* __restrict__ Bt, const int K,
;                                            const int nN, char* shm, const EpiArgs& ea) {
;     ...
;       LDA(At, 0, 1); WAIT_V(4); BAR; WAIT_L(0); MMA(1, 0, At, B0); MMA(1, 1, At, B1); BAR;
;     }
;     {
;       LDB(B0, 1, 0); LDA(At, 1, 0); WAIT_V(2); BAR; WAIT_L(0); MMA(0, 0, At, B0); BAR;
;       LDB(B1, 1, 1); WAIT_V(0); BAR; WAIT_L(0); MMA(0, 1, At, B1); BAR;
;       LDA(At, 1, 1); BAR; WAIT_L(0); MMA(1, 0, At, B0); MMA(1, 1, At, B1); BAR;
;     }
;     if (wr == 0) BAR;
	s_nop 0
	ds_read_b128 v[16:19], v189
	ds_read_b128 v[20:23], v189 offset:1024
	ds_read_b128 v[164:167], v189 offset:2048
	ds_read_b128 v[168:171], v189 offset:3072
	ds_read_b128 v[24:27], v184 offset:32768
	ds_read_b128 v[28:31], v184 offset:33792
	ds_read_b128 v[192:195], v185 offset:32768
	ds_read_b128 v[196:199], v185 offset:33792
	ds_read_b128 v[200:203], v186 offset:32768
	ds_read_b128 v[204:207], v186 offset:33792
	ds_read_b128 v[208:211], v187 offset:32768
	ds_read_b128 v[212:215], v187 offset:33792
	s_waitcnt vmcnt(2)
	s_barrier
	s_waitcnt lgkmcnt(0)
	v_mfma_f32_16x16x32_bf16 v[124:127], v[16:19], v[24:27], v[124:127]
	v_mfma_f32_16x16x32_bf16 v[120:123], v[164:167], v[24:27], v[120:123]
	v_mfma_f32_16x16x32_bf16 v[116:119], v[16:19], v[192:195], v[116:119]
	v_mfma_f32_16x16x32_bf16 v[112:115], v[164:167], v[192:195], v[112:115]
	v_mfma_f32_16x16x32_bf16 v[108:111], v[16:19], v[200:203], v[108:111]
	v_mfma_f32_16x16x32_bf16 v[104:107], v[164:167], v[200:203], v[104:107]
	v_mfma_f32_16x16x32_bf16 v[100:103], v[16:19], v[208:211], v[100:103]
	v_mfma_f32_16x16x32_bf16 v[96:99], v[164:167], v[208:211], v[96:99]
	v_mfma_f32_16x16x32_bf16 v[156:159], v[20:23], v[28:31], v[124:127]
	v_mfma_f32_16x16x32_bf16 v[148:151], v[168:171], v[28:31], v[120:123]
	v_mfma_f32_16x16x32_bf16 v[144:147], v[20:23], v[196:199], v[116:119]
	v_mfma_f32_16x16x32_bf16 v[140:143], v[168:171], v[196:199], v[112:115]
	v_mfma_f32_16x16x32_bf16 v[120:123], v[20:23], v[204:207], v[108:111]
	v_mfma_f32_16x16x32_bf16 v[116:119], v[168:171], v[204:207], v[104:107]
	v_mfma_f32_16x16x32_bf16 v[112:115], v[20:23], v[212:215], v[100:103]
	v_mfma_f32_16x16x32_bf16 v[108:111], v[168:171], v[212:215], v[96:99]
	s_barrier
	ds_read_b128 v[228:231], v190
	ds_read_b128 v[232:235], v190 offset:1024
	ds_read_b128 v[236:239], v190 offset:2048
	ds_read_b128 v[240:243], v190 offset:3072
	s_waitcnt vmcnt(0)
	s_barrier
	s_waitcnt lgkmcnt(0)
	v_mfma_f32_16x16x32_bf16 v[92:95], v[228:231], v[24:27], v[92:95]
	v_mfma_f32_16x16x32_bf16 v[24:27], v[236:239], v[24:27], v[88:91]
	v_mfma_f32_16x16x32_bf16 v[132:135], v[240:243], v[28:31], v[24:27]
	v_mfma_f32_16x16x32_bf16 v[24:27], v[228:231], v[192:195], v[84:87]
	v_mfma_f32_16x16x32_bf16 v[128:131], v[232:235], v[196:199], v[24:27]
	v_mfma_f32_16x16x32_bf16 v[24:27], v[236:239], v[192:195], v[80:83]
	v_mfma_f32_16x16x32_bf16 v[124:127], v[240:243], v[196:199], v[24:27]
	v_mfma_f32_16x16x32_bf16 v[24:27], v[228:231], v[200:203], v[76:79]
	v_mfma_f32_16x16x32_bf16 v[104:107], v[232:235], v[204:207], v[24:27]
	v_mfma_f32_16x16x32_bf16 v[24:27], v[236:239], v[200:203], v[72:75]
	v_mfma_f32_16x16x32_bf16 v[100:103], v[240:243], v[204:207], v[24:27]
	v_mfma_f32_16x16x32_bf16 v[24:27], v[228:231], v[208:211], v[68:71]
	v_mfma_f32_16x16x32_bf16 v[96:99], v[232:235], v[212:215], v[24:27]
	v_mfma_f32_16x16x32_bf16 v[24:27], v[236:239], v[208:211], v[64:67]
	v_mfma_f32_16x16x32_bf16 v[136:139], v[232:235], v[28:31], v[92:95]
	v_mfma_f32_16x16x32_bf16 v[92:95], v[240:243], v[212:215], v[24:27]
	s_barrier
	ds_read_b128 v[64:67], v184 offset:49152
	ds_read_b128 v[68:71], v184 offset:50176
	ds_read_b128 v[192:195], v185 offset:49152
	ds_read_b128 v[196:199], v185 offset:50176
	ds_read_b128 v[200:203], v186 offset:49152
	ds_read_b128 v[204:207], v186 offset:50176
	ds_read_b128 v[208:211], v187 offset:49152
	ds_read_b128 v[212:215], v187 offset:50176
	s_barrier
	s_waitcnt lgkmcnt(0)
	v_mfma_f32_16x16x32_bf16 v[24:27], v[16:19], v[64:67], v[60:63]
	v_mfma_f32_16x16x32_bf16 v[88:91], v[20:23], v[68:71], v[24:27]
	v_mfma_f32_16x16x32_bf16 v[24:27], v[164:167], v[64:67], v[56:59]
	v_mfma_f32_16x16x32_bf16 v[84:87], v[168:171], v[68:71], v[24:27]
	v_mfma_f32_16x16x32_bf16 v[24:27], v[16:19], v[192:195], v[52:55]
	v_mfma_f32_16x16x32_bf16 v[80:83], v[20:23], v[196:199], v[24:27]
	v_mfma_f32_16x16x32_bf16 v[24:27], v[164:167], v[192:195], v[48:51]
	v_mfma_f32_16x16x32_bf16 v[76:79], v[168:171], v[196:199], v[24:27]
	v_mfma_f32_16x16x32_bf16 v[24:27], v[16:19], v[200:203], v[44:47]
	v_mfma_f32_16x16x32_bf16 v[16:19], v[16:19], v[208:211], v[36:39]
	v_mfma_f32_16x16x32_bf16 v[28:31], v[20:23], v[204:207], v[24:27]
	v_mfma_f32_16x16x32_bf16 v[24:27], v[164:167], v[200:203], v[40:43]
	v_mfma_f32_16x16x32_bf16 v[20:23], v[20:23], v[212:215], v[16:19]
	v_mfma_f32_16x16x32_bf16 v[16:19], v[164:167], v[208:211], v[32:35]
	v_mfma_f32_16x16x32_bf16 v[24:27], v[168:171], v[204:207], v[24:27]
	v_mfma_f32_16x16x32_bf16 v[16:19], v[168:171], v[212:215], v[16:19]
	v_mfma_f32_16x16x32_bf16 v[32:35], v[228:231], v[64:67], v[216:219]
	v_mfma_f32_16x16x32_bf16 v[72:75], v[232:235], v[68:71], v[32:35]
	v_mfma_f32_16x16x32_bf16 v[32:35], v[236:239], v[64:67], v[220:223]
	v_mfma_f32_16x16x32_bf16 v[68:71], v[240:243], v[68:71], v[32:35]
	v_mfma_f32_16x16x32_bf16 v[32:35], v[228:231], v[192:195], v[224:227]
	v_mfma_f32_16x16x32_bf16 v[40:43], v[232:235], v[196:199], v[32:35]
	v_mfma_f32_16x16x32_bf16 v[32:35], v[236:239], v[192:195], v[160:163]
	v_mfma_f32_16x16x32_bf16 v[12:15], v[228:231], v[200:203], v[12:15]
	v_mfma_f32_16x16x32_bf16 v[8:11], v[236:239], v[200:203], v[8:11]
	v_mfma_f32_16x16x32_bf16 v[4:7], v[228:231], v[208:211], v[4:7]
	v_mfma_f32_16x16x32_bf16 v[0:3], v[236:239], v[208:211], v[0:3]
	v_mfma_f32_16x16x32_bf16 v[36:39], v[240:243], v[196:199], v[32:35]
	v_mfma_f32_16x16x32_bf16 v[12:15], v[232:235], v[204:207], v[12:15]
	v_mfma_f32_16x16x32_bf16 v[8:11], v[240:243], v[204:207], v[8:11]
	v_mfma_f32_16x16x32_bf16 v[4:7], v[232:235], v[212:215], v[4:7]
	v_mfma_f32_16x16x32_bf16 v[0:3], v[240:243], v[212:215], v[0:3]
	s_andn2_b64 vcc, exec, s[16:17]
	s_barrier
	s_cbranch_vccz .LBB0_574
	s_andn2_b64 vcc, exec, s[28:29]
	s_cbranch_vccz .LBB0_575

; #define LDA(dst, b, h)                                                                                               \
;   _Pragma("unroll") for (int m = 0; m < 4; ++m) _Pragma("unroll") for (int k = 0; k < 2; ++k) dst[m][k] =            \
;       *reinterpret_cast<const bf16x8*>(SA(b, h) + lds_byte(wr * 64 + m * 16 + fr, k * 32 + fq * 8))
; #define LDB(dst, b, h)                                                                                               \
;   _Pragma("unroll") for (int n = 0; n < 2; ++n) _Pragma("unroll") for (int k = 0; k < 2; ++k) dst[n][k] =            \
;       *reinterpret_cast<const bf16x8*>(SB(b, h) + lds_byte(wc * 32 + n * 16 + fr, k * 32 + fq * 8))
; #define WAIT_V(n) asm volatile("s_waitcnt vmcnt(" #n ")" ::: "memory")
; #define WAIT_L(n) asm volatile("s_waitcnt lgkmcnt(" #n ")" ::: "memory")
; #define BAR __builtin_amdgcn_s_barrier()
; #define SCHED __builtin_amdgcn_sched_barrier(0)
; template <int EPI>
; __device__ __forceinline__ void gemm_phase(const u16* __restrict__ A, const u16* __restrict__ Bt, const int K,
;                                            const int nN, char* shm, const EpiArgs& ea) {
;     ...
;       LDB(B0, 0, 0); SCHED; LDA(At, 0, 0); STAGE(SA(1, 1), rA, brow + HALF, t + 1);
;       WAIT_V(10); WAIT_L(8); BAR; WAIT_L(0); MMA(0, 0, At, B0); BAR; SCHED;
;       LDB(B1, 0, 1); STAGE(SB(0, 0), rB, bcol, t + 2);
;       WAIT_V(10); BAR; WAIT_L(0); MMA(0, 1, At, B1); BAR;
;       LDA(At, 0, 1); STAGE(SA(0, 0), rA, brow, t + 2);
;       BAR; WAIT_L(0); MMA(1, 0, At, B0); BAR; SCHED;
;       STAGE(SB(0, 1), rB, bcol + HALF, t + 2);
;       WAIT_V(10); BAR; MMA(1, 1, At, B1); BAR;
.LBB0_631:
	ds_read_b128 v[130:133], v141
	ds_read_b128 v[134:137], v141 offset:1024
	ds_read_b128 v[150:153], v141 offset:2048
	ds_read_b128 v[154:157], v141 offset:3072
	s_add_i32 s54, s48, s53
	s_mov_b32 m0, s41
	s_add_i32 s6, s54, 0x4000
	ds_read_b128 v[158:161], v142
	ds_read_b128 v[162:165], v142 offset:1024
	ds_read_b128 v[166:169], v143
	ds_read_b128 v[170:173], v143 offset:1024
	ds_read_b128 v[176:179], v144
	ds_read_b128 v[180:183], v144 offset:1024
	ds_read_b128 v[184:187], v145
	ds_read_b128 v[188:191], v145 offset:1024
	buffer_load_dwordx4 v138, s[0:3], s6 offen lds
	s_add_i32 s6, s54, 0x6000
	s_mov_b32 m0, s42
	s_nop 0
	buffer_load_dwordx4 v138, s[0:3], s6 offen lds
	s_waitcnt vmcnt(10)
	s_waitcnt lgkmcnt(8)
	s_barrier
	s_waitcnt lgkmcnt(0)
	v_mfma_f32_16x16x32_bf16 v[124:127], v[130:133], v[158:161], v[124:127]
	v_mfma_f32_16x16x32_bf16 v[120:123], v[150:153], v[158:161], v[120:123]
	v_mfma_f32_16x16x32_bf16 v[116:119], v[130:133], v[166:169], v[116:119]
	v_mfma_f32_16x16x32_bf16 v[112:115], v[150:153], v[166:169], v[112:115]
	v_mfma_f32_16x16x32_bf16 v[108:111], v[130:133], v[176:179], v[108:111]
	v_mfma_f32_16x16x32_bf16 v[104:107], v[150:153], v[176:179], v[104:107]
	v_mfma_f32_16x16x32_bf16 v[100:103], v[130:133], v[184:187], v[100:103]
	v_mfma_f32_16x16x32_bf16 v[96:99], v[150:153], v[184:187], v[96:99]
	v_mfma_f32_16x16x32_bf16 v[124:127], v[134:137], v[162:165], v[124:127]
	v_mfma_f32_16x16x32_bf16 v[120:123], v[154:157], v[162:165], v[120:123]
	v_mfma_f32_16x16x32_bf16 v[116:119], v[134:137], v[170:173], v[116:119]
	v_mfma_f32_16x16x32_bf16 v[112:115], v[154:157], v[170:173], v[112:115]
	v_mfma_f32_16x16x32_bf16 v[108:111], v[134:137], v[180:183], v[108:111]
	v_mfma_f32_16x16x32_bf16 v[104:107], v[154:157], v[180:183], v[104:107]
	v_mfma_f32_16x16x32_bf16 v[100:103], v[134:137], v[188:191], v[100:103]
	v_mfma_f32_16x16x32_bf16 v[96:99], v[154:157], v[188:191], v[96:99]
	s_barrier
	s_add_i32 s55, s51, s53
	s_mov_b32 m0, s19
	s_add_i32 s56, s55, 0x8000
	s_mov_b32 s6, s2
	s_mov_b32 s7, s3
	ds_read_b128 v[192:195], v146
	ds_read_b128 v[196:199], v146 offset:1024
	ds_read_b128 v[200:203], v146 offset:2048
	ds_read_b128 v[204:207], v146 offset:3072
	buffer_load_dwordx4 v138, s[4:7], s56 offen lds
	s_add_i32 s56, s55, 0xa000
	s_mov_b32 m0, s26
	s_nop 0
	buffer_load_dwordx4 v138, s[4:7], s56 offen lds
	s_waitcnt vmcnt(10)
	s_barrier
	s_waitcnt lgkmcnt(0)
	v_mfma_f32_16x16x32_bf16 v[92:95], v[192:195], v[158:161], v[92:95]
	v_mfma_f32_16x16x32_bf16 v[88:91], v[200:203], v[158:161], v[88:91]
	v_mfma_f32_16x16x32_bf16 v[84:87], v[192:195], v[166:169], v[84:87]
	v_mfma_f32_16x16x32_bf16 v[80:83], v[200:203], v[166:169], v[80:83]
	v_mfma_f32_16x16x32_bf16 v[76:79], v[192:195], v[176:179], v[76:79]
	v_mfma_f32_16x16x32_bf16 v[72:75], v[200:203], v[176:179], v[72:75]
	v_mfma_f32_16x16x32_bf16 v[68:71], v[192:195], v[184:187], v[68:71]
	v_mfma_f32_16x16x32_bf16 v[64:67], v[200:203], v[184:187], v[64:67]
	v_mfma_f32_16x16x32_bf16 v[92:95], v[196:199], v[162:165], v[92:95]
	v_mfma_f32_16x16x32_bf16 v[88:91], v[204:207], v[162:165], v[88:91]
	v_mfma_f32_16x16x32_bf16 v[84:87], v[196:199], v[170:173], v[84:87]
	v_mfma_f32_16x16x32_bf16 v[80:83], v[204:207], v[170:173], v[80:83]
	v_mfma_f32_16x16x32_bf16 v[76:79], v[196:199], v[180:183], v[76:79]
	v_mfma_f32_16x16x32_bf16 v[72:75], v[204:207], v[180:183], v[72:75]
	v_mfma_f32_16x16x32_bf16 v[68:71], v[196:199], v[188:191], v[68:71]
	v_mfma_f32_16x16x32_bf16 v[64:67], v[204:207], v[188:191], v[64:67]
	s_add_i32 s56, s50, s53
	s_mov_b32 m0, s27
	s_add_i32 s57, s56, 0x8000
	s_barrier
	ds_read_b128 v[158:161], v142 offset:16384
	ds_read_b128 v[162:165], v142 offset:17408
	ds_read_b128 v[166:169], v143 offset:16384
	ds_read_b128 v[170:173], v143 offset:17408
	ds_read_b128 v[176:179], v144 offset:16384
	ds_read_b128 v[180:183], v144 offset:17408
	ds_read_b128 v[184:187], v145 offset:16384
	ds_read_b128 v[188:191], v145 offset:17408
	buffer_load_dwordx4 v138, s[0:3], s57 offen lds
	s_add_i32 s57, s56, 0xa000
	s_mov_b32 m0, s28
	s_nop 0
	buffer_load_dwordx4 v138, s[0:3], s57 offen lds
	s_barrier
	s_waitcnt lgkmcnt(0)
	v_mfma_f32_16x16x32_bf16 v[60:63], v[130:133], v[158:161], v[60:63]
	v_mfma_f32_16x16x32_bf16 v[56:59], v[150:153], v[158:161], v[56:59]
	v_mfma_f32_16x16x32_bf16 v[52:55], v[130:133], v[166:169], v[52:55]
	v_mfma_f32_16x16x32_bf16 v[48:51], v[150:153], v[166:169], v[48:51]
	v_mfma_f32_16x16x32_bf16 v[44:47], v[130:133], v[176:179], v[44:47]
	v_mfma_f32_16x16x32_bf16 v[40:43], v[150:153], v[176:179], v[40:43]
	v_mfma_f32_16x16x32_bf16 v[36:39], v[130:133], v[184:187], v[36:39]
	v_mfma_f32_16x16x32_bf16 v[32:35], v[150:153], v[184:187], v[32:35]
	v_mfma_f32_16x16x32_bf16 v[60:63], v[134:137], v[162:165], v[60:63]
	v_mfma_f32_16x16x32_bf16 v[56:59], v[154:157], v[162:165], v[56:59]
	v_mfma_f32_16x16x32_bf16 v[52:55], v[134:137], v[170:173], v[52:55]
	v_mfma_f32_16x16x32_bf16 v[48:51], v[154:157], v[170:173], v[48:51]
	v_mfma_f32_16x16x32_bf16 v[44:47], v[134:137], v[180:183], v[44:47]
	v_mfma_f32_16x16x32_bf16 v[40:43], v[154:157], v[180:183], v[40:43]
	v_mfma_f32_16x16x32_bf16 v[36:39], v[134:137], v[188:191], v[36:39]
	v_mfma_f32_16x16x32_bf16 v[32:35], v[154:157], v[188:191], v[32:35]
	s_barrier
	s_add_i32 s57, s49, s53
	s_mov_b32 m0, s29
	s_add_i32 s58, s57, 0x8000
	buffer_load_dwordx4 v138, s[4:7], s58 offen lds
	s_add_i32 s58, s57, 0xa000
	s_mov_b32 m0, s30
	s_nop 0
	buffer_load_dwordx4 v138, s[4:7], s58 offen lds
	s_waitcnt vmcnt(10)
	s_barrier
; #define LDA(dst, b, h)                                                                                               \
;   _Pragma("unroll") for (int m = 0; m < 4; ++m) _Pragma("unroll") for (int k = 0; k < 2; ++k) dst[m][k] =            \
;       *reinterpret_cast<const bf16x8*>(SA(b, h) + lds_byte(wr * 64 + m * 16 + fr, k * 32 + fq * 8))
; #define LDB(dst, b, h)                                                                                               \
;   _Pragma("unroll") for (int n = 0; n < 2; ++n) _Pragma("unroll") for (int k = 0; k < 2; ++k) dst[n][k] =            \
;       *reinterpret_cast<const bf16x8*>(SB(b, h) + lds_byte(wc * 32 + n * 16 + fr, k * 32 + fq * 8))
; #define WAIT_V(n) asm volatile("s_waitcnt vmcnt(" #n ")" ::: "memory")
; #define WAIT_L(n) asm volatile("s_waitcnt lgkmcnt(" #n ")" ::: "memory")
; #define BAR __builtin_amdgcn_s_barrier()
; #define SCHED __builtin_amdgcn_sched_barrier(0)
; template <int EPI>
; __device__ __forceinline__ void gemm_phase(const u16* __restrict__ A, const u16* __restrict__ Bt, const int K,
;                                            const int nN, char* shm, const EpiArgs& ea) {
;     ...
;       WAIT_V(10); BAR; MMA(1, 1, At, B1); BAR;
;       LDB(B0, 1, 0); SCHED; LDA(At, 1, 0); STAGE(SA(0, 1), rA, brow + HALF, t + 2);
;       WAIT_V(10); WAIT_L(8); BAR; WAIT_L(0); MMA(0, 0, At, B0); BAR; SCHED;
;       LDB(B1, 1, 1); STAGE(SB(1, 0), rB, bcol, t + 3);
;       WAIT_V(10); BAR; WAIT_L(0); MMA(0, 1, At, B1); BAR;
;       LDA(At, 1, 1); STAGE(SA(1, 0), rA, brow, t + 3);
;       BAR; WAIT_L(0); MMA(1, 0, At, B0); BAR; SCHED;
;       STAGE(SB(1, 1), rB, bcol + HALF, t + 3);
	v_mfma_f32_16x16x32_bf16 v[28:31], v[192:195], v[158:161], v[28:31]
	v_mfma_f32_16x16x32_bf16 v[24:27], v[200:203], v[158:161], v[24:27]
	v_mfma_f32_16x16x32_bf16 v[20:23], v[192:195], v[166:169], v[20:23]
	v_mfma_f32_16x16x32_bf16 v[16:19], v[200:203], v[166:169], v[16:19]
	v_mfma_f32_16x16x32_bf16 v[12:15], v[192:195], v[176:179], v[12:15]
	v_mfma_f32_16x16x32_bf16 v[8:11], v[200:203], v[176:179], v[8:11]
	v_mfma_f32_16x16x32_bf16 v[4:7], v[192:195], v[184:187], v[4:7]
	v_mfma_f32_16x16x32_bf16 v[0:3], v[200:203], v[184:187], v[0:3]
	v_mfma_f32_16x16x32_bf16 v[28:31], v[196:199], v[162:165], v[28:31]
	v_mfma_f32_16x16x32_bf16 v[24:27], v[204:207], v[162:165], v[24:27]
	v_mfma_f32_16x16x32_bf16 v[20:23], v[196:199], v[170:173], v[20:23]
	v_mfma_f32_16x16x32_bf16 v[16:19], v[204:207], v[170:173], v[16:19]
	v_mfma_f32_16x16x32_bf16 v[12:15], v[196:199], v[180:183], v[12:15]
	v_mfma_f32_16x16x32_bf16 v[8:11], v[204:207], v[180:183], v[8:11]
	v_mfma_f32_16x16x32_bf16 v[4:7], v[196:199], v[188:191], v[4:7]
	v_mfma_f32_16x16x32_bf16 v[0:3], v[204:207], v[188:191], v[0:3]
	s_barrier
	ds_read_b128 v[130:133], v147
	ds_read_b128 v[134:137], v147 offset:1024
	ds_read_b128 v[150:153], v147 offset:2048
	ds_read_b128 v[154:157], v147 offset:3072
	s_mov_b32 m0, s31
	s_add_i32 s58, s54, 0x8000
	ds_read_b128 v[158:161], v142 offset:32768
	ds_read_b128 v[162:165], v142 offset:33792
	ds_read_b128 v[166:169], v143 offset:32768
	ds_read_b128 v[170:173], v143 offset:33792
	ds_read_b128 v[176:179], v144 offset:32768
	ds_read_b128 v[180:183], v144 offset:33792
	ds_read_b128 v[184:187], v145 offset:32768
	ds_read_b128 v[188:191], v145 offset:33792
	buffer_load_dwordx4 v138, s[0:3], s58 offen lds
	s_add_i32 s54, s54, 0xa000
	s_mov_b32 m0, s34
	s_nop 0
	buffer_load_dwordx4 v138, s[0:3], s54 offen lds
	s_waitcnt vmcnt(10)
	s_waitcnt lgkmcnt(8)
	s_barrier
	s_waitcnt lgkmcnt(0)
	v_mfma_f32_16x16x32_bf16 v[124:127], v[130:133], v[158:161], v[124:127]
	v_mfma_f32_16x16x32_bf16 v[120:123], v[150:153], v[158:161], v[120:123]
	v_mfma_f32_16x16x32_bf16 v[116:119], v[130:133], v[166:169], v[116:119]
	v_mfma_f32_16x16x32_bf16 v[112:115], v[150:153], v[166:169], v[112:115]
	v_mfma_f32_16x16x32_bf16 v[108:111], v[130:133], v[176:179], v[108:111]
	v_mfma_f32_16x16x32_bf16 v[104:107], v[150:153], v[176:179], v[104:107]
	v_mfma_f32_16x16x32_bf16 v[100:103], v[130:133], v[184:187], v[100:103]
	v_mfma_f32_16x16x32_bf16 v[96:99], v[150:153], v[184:187], v[96:99]
	v_mfma_f32_16x16x32_bf16 v[124:127], v[134:137], v[162:165], v[124:127]
	v_mfma_f32_16x16x32_bf16 v[120:123], v[154:157], v[162:165], v[120:123]
	v_mfma_f32_16x16x32_bf16 v[116:119], v[134:137], v[170:173], v[116:119]
	v_mfma_f32_16x16x32_bf16 v[112:115], v[154:157], v[170:173], v[112:115]
	v_mfma_f32_16x16x32_bf16 v[108:111], v[134:137], v[180:183], v[108:111]
	v_mfma_f32_16x16x32_bf16 v[104:107], v[154:157], v[180:183], v[104:107]
	v_mfma_f32_16x16x32_bf16 v[100:103], v[134:137], v[188:191], v[100:103]
	v_mfma_f32_16x16x32_bf16 v[96:99], v[154:157], v[188:191], v[96:99]
	s_barrier
	s_mov_b32 m0, s35
	s_add_i32 s54, s55, 0xc000
	ds_read_b128 v[192:195], v148
	ds_read_b128 v[196:199], v148 offset:1024
	ds_read_b128 v[200:203], v148 offset:2048
	ds_read_b128 v[204:207], v148 offset:3072
	buffer_load_dwordx4 v138, s[4:7], s54 offen lds
	s_add_i32 s55, s55, 0xe000
	s_mov_b32 m0, s36
	s_nop 0
	buffer_load_dwordx4 v138, s[4:7], s55 offen lds
	s_waitcnt vmcnt(10)
	s_barrier
	s_waitcnt lgkmcnt(0)
	v_mfma_f32_16x16x32_bf16 v[92:95], v[192:195], v[158:161], v[92:95]
	v_mfma_f32_16x16x32_bf16 v[88:91], v[200:203], v[158:161], v[88:91]
	v_mfma_f32_16x16x32_bf16 v[84:87], v[192:195], v[166:169], v[84:87]
	v_mfma_f32_16x16x32_bf16 v[80:83], v[200:203], v[166:169], v[80:83]
	v_mfma_f32_16x16x32_bf16 v[76:79], v[192:195], v[176:179], v[76:79]
	v_mfma_f32_16x16x32_bf16 v[72:75], v[200:203], v[176:179], v[72:75]
	v_mfma_f32_16x16x32_bf16 v[68:71], v[192:195], v[184:187], v[68:71]
	v_mfma_f32_16x16x32_bf16 v[64:67], v[200:203], v[184:187], v[64:67]
	v_mfma_f32_16x16x32_bf16 v[92:95], v[196:199], v[162:165], v[92:95]
	v_mfma_f32_16x16x32_bf16 v[88:91], v[204:207], v[162:165], v[88:91]
	v_mfma_f32_16x16x32_bf16 v[84:87], v[196:199], v[170:173], v[84:87]
	v_mfma_f32_16x16x32_bf16 v[80:83], v[204:207], v[170:173], v[80:83]
	v_mfma_f32_16x16x32_bf16 v[76:79], v[196:199], v[180:183], v[76:79]
	v_mfma_f32_16x16x32_bf16 v[72:75], v[204:207], v[180:183], v[72:75]
	v_mfma_f32_16x16x32_bf16 v[68:71], v[196:199], v[188:191], v[68:71]
	v_mfma_f32_16x16x32_bf16 v[64:67], v[204:207], v[188:191], v[64:67]
	s_mov_b32 m0, s37
	s_add_i32 s54, s56, 0xc000
	s_barrier
	ds_read_b128 v[158:161], v142 offset:49152
	ds_read_b128 v[162:165], v142 offset:50176
	ds_read_b128 v[166:169], v143 offset:49152
	ds_read_b128 v[170:173], v143 offset:50176
	ds_read_b128 v[176:179], v144 offset:49152
	ds_read_b128 v[180:183], v144 offset:50176
	ds_read_b128 v[184:187], v145 offset:49152
	ds_read_b128 v[188:191], v145 offset:50176
	buffer_load_dwordx4 v138, s[0:3], s54 offen lds
	s_add_i32 s56, s56, 0xe000
	s_mov_b32 m0, s38
	s_nop 0
	buffer_load_dwordx4 v138, s[0:3], s56 offen lds
	s_barrier
; #define LDA(dst, b, h)                                                                                               \
;   _Pragma("unroll") for (int m = 0; m < 4; ++m) _Pragma("unroll") for (int k = 0; k < 2; ++k) dst[m][k] =            \
;       *reinterpret_cast<const bf16x8*>(SA(b, h) + lds_byte(wr * 64 + m * 16 + fr, k * 32 + fq * 8))
; #define LDB(dst, b, h)                                                                                               \
;   _Pragma("unroll") for (int n = 0; n < 2; ++n) _Pragma("unroll") for (int k = 0; k < 2; ++k) dst[n][k] =            \
;       *reinterpret_cast<const bf16x8*>(SB(b, h) + lds_byte(wc * 32 + n * 16 + fr, k * 32 + fq * 8))
; #define WAIT_V(n) asm volatile("s_waitcnt vmcnt(" #n ")" ::: "memory")
; #define WAIT_L(n) asm volatile("s_waitcnt lgkmcnt(" #n ")" ::: "memory")
; #define BAR __builtin_amdgcn_s_barrier()
; #define SCHED __builtin_amdgcn_sched_barrier(0)
; template <int EPI>
; __device__ __forceinline__ void gemm_phase(const u16* __restrict__ A, const u16* __restrict__ Bt, const int K,
;                                            const int nN, char* shm, const EpiArgs& ea) {
;     ...
;       WAIT_V(10); WAIT_L(8); BAR; WAIT_L(0); MMA(0, 0, At, B0); BAR; SCHED;
;       LDB(B1, 1, 1); STAGE(SB(1, 0), rB, bcol, t + 3);
;       WAIT_V(10); BAR; WAIT_L(0); MMA(0, 1, At, B1); BAR;
;       LDA(At, 1, 1); STAGE(SA(1, 0), rA, brow, t + 3);
;       BAR; WAIT_L(0); MMA(1, 0, At, B0); BAR; SCHED;
;       STAGE(SB(1, 1), rB, bcol + HALF, t + 3);
;       WAIT_V(10); BAR; MMA(1, 1, At, B1); BAR;
;     }
;     float eC = 0.f, eB = 0.f;
;     float2 eS = make_float2(0.f, 0.f);
;     if (EPI == EPI_IN || EPI == EPI_SWIGLU_LN) {
;       if (wr == 0) {
;         eC = ea.c1[bcol + tid];
;         eS = *(const float2*)(ea.st_in + (size_t)(brow + tid) * 2);
;       } else {
;         eC = ea.c2[bcol + tid - 256];
;         if (EPI == EPI_IN) eB = ea.bias[bcol + tid - 256];
;       }
;     }
;     {
;       LDB(B0, 0, 0); LDA(At, 0, 0); STAGE(SA(1, 1), rA, brow + HALF, nt - 1);
;       WAIT_V(10); BAR; WAIT_L(0); MMA(0, 0, At, B0); BAR;
;       LDB(B1, 0, 1); WAIT_V(8); BAR; WAIT_L(0); MMA(0, 1, At, B1); BAR;
;       LDA(At, 0, 1); WAIT_V(4); BAR; WAIT_L(0); MMA(1, 0, At, B0); MMA(1, 1, At, B1); BAR;
	s_waitcnt lgkmcnt(0)
	v_mfma_f32_16x16x32_bf16 v[60:63], v[130:133], v[158:161], v[60:63]
	v_mfma_f32_16x16x32_bf16 v[56:59], v[150:153], v[158:161], v[56:59]
	v_mfma_f32_16x16x32_bf16 v[52:55], v[130:133], v[166:169], v[52:55]
	v_mfma_f32_16x16x32_bf16 v[48:51], v[150:153], v[166:169], v[48:51]
	v_mfma_f32_16x16x32_bf16 v[44:47], v[130:133], v[176:179], v[44:47]
	v_mfma_f32_16x16x32_bf16 v[40:43], v[150:153], v[176:179], v[40:43]
	v_mfma_f32_16x16x32_bf16 v[36:39], v[130:133], v[184:187], v[36:39]
	v_mfma_f32_16x16x32_bf16 v[32:35], v[150:153], v[184:187], v[32:35]
	v_mfma_f32_16x16x32_bf16 v[60:63], v[134:137], v[162:165], v[60:63]
	v_mfma_f32_16x16x32_bf16 v[56:59], v[154:157], v[162:165], v[56:59]
	v_mfma_f32_16x16x32_bf16 v[52:55], v[134:137], v[170:173], v[52:55]
	v_mfma_f32_16x16x32_bf16 v[48:51], v[154:157], v[170:173], v[48:51]
	v_mfma_f32_16x16x32_bf16 v[44:47], v[134:137], v[180:183], v[44:47]
	v_mfma_f32_16x16x32_bf16 v[40:43], v[154:157], v[180:183], v[40:43]
	v_mfma_f32_16x16x32_bf16 v[36:39], v[134:137], v[188:191], v[36:39]
	v_mfma_f32_16x16x32_bf16 v[32:35], v[154:157], v[188:191], v[32:35]
	s_barrier
	s_mov_b32 m0, s39
	s_add_i32 s54, s57, 0xc000
	buffer_load_dwordx4 v138, s[4:7], s54 offen lds
	s_add_i32 s57, s57, 0xe000
	s_mov_b32 m0, s40
	s_nop 0
	buffer_load_dwordx4 v138, s[4:7], s57 offen lds
	s_waitcnt vmcnt(10)
	s_barrier
	v_mfma_f32_16x16x32_bf16 v[28:31], v[192:195], v[158:161], v[28:31]
	v_mfma_f32_16x16x32_bf16 v[24:27], v[200:203], v[158:161], v[24:27]
	v_mfma_f32_16x16x32_bf16 v[20:23], v[192:195], v[166:169], v[20:23]
	v_mfma_f32_16x16x32_bf16 v[16:19], v[200:203], v[166:169], v[16:19]
	v_mfma_f32_16x16x32_bf16 v[12:15], v[192:195], v[176:179], v[12:15]
	v_mfma_f32_16x16x32_bf16 v[8:11], v[200:203], v[176:179], v[8:11]
	v_mfma_f32_16x16x32_bf16 v[4:7], v[192:195], v[184:187], v[4:7]
	v_mfma_f32_16x16x32_bf16 v[0:3], v[200:203], v[184:187], v[0:3]
	v_mfma_f32_16x16x32_bf16 v[28:31], v[196:199], v[162:165], v[28:31]
	v_mfma_f32_16x16x32_bf16 v[24:27], v[204:207], v[162:165], v[24:27]
	v_mfma_f32_16x16x32_bf16 v[20:23], v[196:199], v[170:173], v[20:23]
	v_mfma_f32_16x16x32_bf16 v[16:19], v[204:207], v[170:173], v[16:19]
	v_mfma_f32_16x16x32_bf16 v[12:15], v[196:199], v[180:183], v[12:15]
	v_mfma_f32_16x16x32_bf16 v[8:11], v[204:207], v[180:183], v[8:11]
	v_mfma_f32_16x16x32_bf16 v[4:7], v[196:199], v[188:191], v[4:7]
	v_mfma_f32_16x16x32_bf16 v[0:3], v[204:207], v[188:191], v[0:3]
	s_add_i32 s52, s52, 2
	s_add_i32 s53, s53, 0x8000
	s_cmpk_lt_u32 s52, 0x54
	s_barrier
	s_cbranch_scc1 .LBB0_631
	s_mov_b32 m0, s41
	s_add_i32 s6, s48, 0x15c000
	ds_read_b128 v[130:133], v141
	ds_read_b128 v[134:137], v141 offset:1024
	ds_read_b128 v[150:153], v141 offset:2048
	ds_read_b128 v[154:157], v141 offset:3072
	ds_read_b128 v[158:161], v142
	ds_read_b128 v[162:165], v142 offset:1024
	ds_read_b128 v[166:169], v143
	ds_read_b128 v[170:173], v143 offset:1024
	ds_read_b128 v[176:179], v144
	ds_read_b128 v[180:183], v144 offset:1024
	ds_read_b128 v[184:187], v145
	ds_read_b128 v[188:191], v145 offset:1024
	buffer_load_dwordx4 v138, s[0:3], s6 offen lds
	s_add_i32 s48, s48, 0x15e000
	s_mov_b32 m0, s42
	s_nop 0
	buffer_load_dwordx4 v138, s[0:3], s48 offen lds
	s_waitcnt vmcnt(10)
	s_barrier
	s_waitcnt lgkmcnt(0)
	v_mfma_f32_16x16x32_bf16 v[124:127], v[130:133], v[158:161], v[124:127]
	v_mfma_f32_16x16x32_bf16 v[120:123], v[150:153], v[158:161], v[120:123]
	v_mfma_f32_16x16x32_bf16 v[116:119], v[130:133], v[166:169], v[116:119]
	v_mfma_f32_16x16x32_bf16 v[112:115], v[150:153], v[166:169], v[112:115]
	v_mfma_f32_16x16x32_bf16 v[100:103], v[130:133], v[184:187], v[100:103]
	v_mfma_f32_16x16x32_bf16 v[96:99], v[150:153], v[184:187], v[96:99]
	v_mfma_f32_16x16x32_bf16 v[124:127], v[134:137], v[162:165], v[124:127]
	v_mfma_f32_16x16x32_bf16 v[120:123], v[154:157], v[162:165], v[120:123]
	v_mfma_f32_16x16x32_bf16 v[116:119], v[134:137], v[170:173], v[116:119]
	v_mfma_f32_16x16x32_bf16 v[112:115], v[154:157], v[170:173], v[112:115]
	v_mfma_f32_16x16x32_bf16 v[108:111], v[130:133], v[176:179], v[108:111]
	v_mfma_f32_16x16x32_bf16 v[104:107], v[150:153], v[176:179], v[104:107]
	v_mfma_f32_16x16x32_bf16 v[100:103], v[134:137], v[188:191], v[100:103]
	v_mfma_f32_16x16x32_bf16 v[96:99], v[154:157], v[188:191], v[96:99]
	v_mfma_f32_16x16x32_bf16 v[192:195], v[134:137], v[180:183], v[108:111]
	v_mfma_f32_16x16x32_bf16 v[196:199], v[154:157], v[180:183], v[104:107]
	s_barrier
	s_nop 0
	ds_read_b128 v[104:107], v146
	ds_read_b128 v[108:111], v146 offset:1024
	ds_read_b128 v[200:203], v146 offset:2048
	ds_read_b128 v[204:207], v146 offset:3072
	s_waitcnt vmcnt(8)
	s_barrier
	s_waitcnt lgkmcnt(0)
	v_mfma_f32_16x16x32_bf16 v[84:87], v[104:107], v[166:169], v[84:87]
	v_mfma_f32_16x16x32_bf16 v[80:83], v[200:203], v[166:169], v[80:83]
	v_mfma_f32_16x16x32_bf16 v[68:71], v[104:107], v[184:187], v[68:71]
	v_mfma_f32_16x16x32_bf16 v[64:67], v[200:203], v[184:187], v[64:67]
	v_mfma_f32_16x16x32_bf16 v[92:95], v[104:107], v[158:161], v[92:95]
	v_mfma_f32_16x16x32_bf16 v[88:91], v[200:203], v[158:161], v[88:91]
	v_mfma_f32_16x16x32_bf16 v[84:87], v[108:111], v[170:173], v[84:87]
	v_mfma_f32_16x16x32_bf16 v[80:83], v[204:207], v[170:173], v[80:83]
	v_mfma_f32_16x16x32_bf16 v[76:79], v[104:107], v[176:179], v[76:79]
	v_mfma_f32_16x16x32_bf16 v[72:75], v[200:203], v[176:179], v[72:75]
	v_mfma_f32_16x16x32_bf16 v[68:71], v[108:111], v[188:191], v[68:71]
	v_mfma_f32_16x16x32_bf16 v[64:67], v[204:207], v[188:191], v[64:67]
	v_mfma_f32_16x16x32_bf16 v[208:211], v[108:111], v[162:165], v[92:95]
	v_mfma_f32_16x16x32_bf16 v[158:161], v[204:207], v[162:165], v[88:91]
	v_mfma_f32_16x16x32_bf16 v[162:165], v[108:111], v[180:183], v[76:79]
	v_mfma_f32_16x16x32_bf16 v[166:169], v[204:207], v[180:183], v[72:75]
	s_barrier
; #define LDA(dst, b, h)                                                                                               \
;   _Pragma("unroll") for (int m = 0; m < 4; ++m) _Pragma("unroll") for (int k = 0; k < 2; ++k) dst[m][k] =            \
;       *reinterpret_cast<const bf16x8*>(SA(b, h) + lds_byte(wr * 64 + m * 16 + fr, k * 32 + fq * 8))
; #define LDB(dst, b, h)                                                                                               \
;   _Pragma("unroll") for (int n = 0; n < 2; ++n) _Pragma("unroll") for (int k = 0; k < 2; ++k) dst[n][k] =            \
;       *reinterpret_cast<const bf16x8*>(SB(b, h) + lds_byte(wc * 32 + n * 16 + fr, k * 32 + fq * 8))
; #define WAIT_V(n) asm volatile("s_waitcnt vmcnt(" #n ")" ::: "memory")
; #define WAIT_L(n) asm volatile("s_waitcnt lgkmcnt(" #n ")" ::: "memory")
; #define BAR __builtin_amdgcn_s_barrier()
; template <int EPI>
; __device__ __forceinline__ void gemm_phase(const u16* __restrict__ A, const u16* __restrict__ Bt, const int K,
;                                            const int nN, char* shm, const EpiArgs& ea) {
;     ...
;       LDB(B1, 0, 1); WAIT_V(8); BAR; WAIT_L(0); MMA(0, 1, At, B1); BAR;
;       LDA(At, 0, 1); WAIT_V(4); BAR; WAIT_L(0); MMA(1, 0, At, B0); MMA(1, 1, At, B1); BAR;
;     }
;     {
;       LDB(B0, 1, 0); LDA(At, 1, 0); WAIT_V(2); BAR; WAIT_L(0); MMA(0, 0, At, B0); BAR;
;       LDB(B1, 1, 1); WAIT_V(0); BAR; WAIT_L(0); MMA(0, 1, At, B1); BAR;
;       LDA(At, 1, 1); BAR; WAIT_L(0); MMA(1, 0, At, B0); MMA(1, 1, At, B1); BAR;
	s_nop 0
	ds_read_b128 v[72:75], v142 offset:16384
	ds_read_b128 v[76:79], v142 offset:17408
	ds_read_b128 v[88:91], v143 offset:16384
	ds_read_b128 v[92:95], v143 offset:17408
	ds_read_b128 v[170:173], v144 offset:16384
	ds_read_b128 v[176:179], v144 offset:17408
	ds_read_b128 v[180:183], v145 offset:16384
	ds_read_b128 v[184:187], v145 offset:17408
	s_waitcnt vmcnt(4)
	s_barrier
	s_waitcnt lgkmcnt(0)
	v_mfma_f32_16x16x32_bf16 v[60:63], v[130:133], v[72:75], v[60:63]
	v_mfma_f32_16x16x32_bf16 v[56:59], v[150:153], v[72:75], v[56:59]
	v_mfma_f32_16x16x32_bf16 v[52:55], v[130:133], v[88:91], v[52:55]
	v_mfma_f32_16x16x32_bf16 v[48:51], v[150:153], v[88:91], v[48:51]
	v_mfma_f32_16x16x32_bf16 v[36:39], v[130:133], v[180:183], v[36:39]
	v_mfma_f32_16x16x32_bf16 v[32:35], v[150:153], v[180:183], v[32:35]
	v_mfma_f32_16x16x32_bf16 v[60:63], v[134:137], v[76:79], v[60:63]
	v_mfma_f32_16x16x32_bf16 v[56:59], v[154:157], v[76:79], v[56:59]
	v_mfma_f32_16x16x32_bf16 v[52:55], v[134:137], v[92:95], v[52:55]
	v_mfma_f32_16x16x32_bf16 v[48:51], v[154:157], v[92:95], v[48:51]
	v_mfma_f32_16x16x32_bf16 v[44:47], v[130:133], v[170:173], v[44:47]
	v_mfma_f32_16x16x32_bf16 v[40:43], v[150:153], v[170:173], v[40:43]
	v_mfma_f32_16x16x32_bf16 v[36:39], v[134:137], v[184:187], v[36:39]
	v_mfma_f32_16x16x32_bf16 v[32:35], v[154:157], v[184:187], v[32:35]
	v_mfma_f32_16x16x32_bf16 v[188:191], v[134:137], v[176:179], v[44:47]
	v_mfma_f32_16x16x32_bf16 v[212:215], v[154:157], v[176:179], v[40:43]
	v_mfma_f32_16x16x32_bf16 v[20:23], v[104:107], v[88:91], v[20:23]
	v_mfma_f32_16x16x32_bf16 v[16:19], v[200:203], v[88:91], v[16:19]
	v_mfma_f32_16x16x32_bf16 v[4:7], v[104:107], v[180:183], v[4:7]
	v_mfma_f32_16x16x32_bf16 v[0:3], v[200:203], v[180:183], v[0:3]
	v_mfma_f32_16x16x32_bf16 v[28:31], v[104:107], v[72:75], v[28:31]
	v_mfma_f32_16x16x32_bf16 v[24:27], v[200:203], v[72:75], v[24:27]
	v_mfma_f32_16x16x32_bf16 v[20:23], v[108:111], v[92:95], v[20:23]
	v_mfma_f32_16x16x32_bf16 v[16:19], v[204:207], v[92:95], v[16:19]
	v_mfma_f32_16x16x32_bf16 v[12:15], v[104:107], v[170:173], v[12:15]
	v_mfma_f32_16x16x32_bf16 v[8:11], v[200:203], v[170:173], v[8:11]
	v_mfma_f32_16x16x32_bf16 v[4:7], v[108:111], v[184:187], v[4:7]
	v_mfma_f32_16x16x32_bf16 v[0:3], v[204:207], v[184:187], v[0:3]
	v_mfma_f32_16x16x32_bf16 v[130:133], v[108:111], v[76:79], v[28:31]
	v_mfma_f32_16x16x32_bf16 v[134:137], v[204:207], v[76:79], v[24:27]
	v_mfma_f32_16x16x32_bf16 v[150:153], v[108:111], v[176:179], v[12:15]
	v_mfma_f32_16x16x32_bf16 v[154:157], v[204:207], v[176:179], v[8:11]
	s_barrier
	s_nop 0
	ds_read_b128 v[8:11], v147
	ds_read_b128 v[12:15], v147 offset:1024
	ds_read_b128 v[170:173], v147 offset:2048
	ds_read_b128 v[176:179], v147 offset:3072
	ds_read_b128 v[24:27], v142 offset:32768
	ds_read_b128 v[28:31], v142 offset:33792
	ds_read_b128 v[40:43], v143 offset:32768
	ds_read_b128 v[44:47], v143 offset:33792
	ds_read_b128 v[180:183], v144 offset:32768
	ds_read_b128 v[184:187], v144 offset:33792
	ds_read_b128 v[200:203], v145 offset:32768
	ds_read_b128 v[204:207], v145 offset:33792
	s_waitcnt vmcnt(2)
	s_barrier
	s_waitcnt lgkmcnt(0)
	v_mfma_f32_16x16x32_bf16 v[72:75], v[8:11], v[24:27], v[124:127]
	v_mfma_f32_16x16x32_bf16 v[124:127], v[12:15], v[28:31], v[72:75]
	v_mfma_f32_16x16x32_bf16 v[72:75], v[170:173], v[24:27], v[120:123]
	v_mfma_f32_16x16x32_bf16 v[120:123], v[176:179], v[28:31], v[72:75]
	v_mfma_f32_16x16x32_bf16 v[72:75], v[8:11], v[40:43], v[116:119]
	v_mfma_f32_16x16x32_bf16 v[108:111], v[12:15], v[44:47], v[72:75]
	v_mfma_f32_16x16x32_bf16 v[72:75], v[170:173], v[40:43], v[112:115]
	v_mfma_f32_16x16x32_bf16 v[104:107], v[176:179], v[44:47], v[72:75]
	v_mfma_f32_16x16x32_bf16 v[72:75], v[8:11], v[180:183], v[192:195]
	v_mfma_f32_16x16x32_bf16 v[92:95], v[12:15], v[184:187], v[72:75]
	v_mfma_f32_16x16x32_bf16 v[72:75], v[170:173], v[180:183], v[196:199]
	v_mfma_f32_16x16x32_bf16 v[88:91], v[176:179], v[184:187], v[72:75]
	v_mfma_f32_16x16x32_bf16 v[72:75], v[8:11], v[200:203], v[100:103]
	v_mfma_f32_16x16x32_bf16 v[76:79], v[12:15], v[204:207], v[72:75]
	v_mfma_f32_16x16x32_bf16 v[72:75], v[170:173], v[200:203], v[96:99]
	v_mfma_f32_16x16x32_bf16 v[72:75], v[176:179], v[204:207], v[72:75]
	s_barrier
; #define LDA(dst, b, h)                                                                                               \
;   _Pragma("unroll") for (int m = 0; m < 4; ++m) _Pragma("unroll") for (int k = 0; k < 2; ++k) dst[m][k] =            \
;       *reinterpret_cast<const bf16x8*>(SA(b, h) + lds_byte(wr * 64 + m * 16 + fr, k * 32 + fq * 8))
; #define LDB(dst, b, h)                                                                                               \
;   _Pragma("unroll") for (int n = 0; n < 2; ++n) _Pragma("unroll") for (int k = 0; k < 2; ++k) dst[n][k] =            \
;       *reinterpret_cast<const bf16x8*>(SB(b, h) + lds_byte(wc * 32 + n * 16 + fr, k * 32 + fq * 8))
; #define WAIT_V(n) asm volatile("s_waitcnt vmcnt(" #n ")" ::: "memory")
; #define WAIT_L(n) asm volatile("s_waitcnt lgkmcnt(" #n ")" ::: "memory")
; #define BAR __builtin_amdgcn_s_barrier()
; template <int EPI>
; __device__ __forceinline__ void gemm_phase(const u16* __restrict__ A, const u16* __restrict__ Bt, const int K,
;                                            const int nN, char* shm, const EpiArgs& ea) {
;     ...
;       LDB(B0, 1, 0); LDA(At, 1, 0); WAIT_V(2); BAR; WAIT_L(0); MMA(0, 0, At, B0); BAR;
;       LDB(B1, 1, 1); WAIT_V(0); BAR; WAIT_L(0); MMA(0, 1, At, B1); BAR;
;       LDA(At, 1, 1); BAR; WAIT_L(0); MMA(1, 0, At, B0); MMA(1, 1, At, B1); BAR;
;     }
;     if (wr == 0) BAR;
	ds_read_b128 v[192:195], v148
	ds_read_b128 v[196:199], v148 offset:1024
	ds_read_b128 v[216:219], v148 offset:2048
	ds_read_b128 v[220:223], v148 offset:3072
	s_waitcnt vmcnt(0)
	s_barrier
	s_waitcnt lgkmcnt(0)
	v_mfma_f32_16x16x32_bf16 v[96:99], v[192:195], v[24:27], v[208:211]
	v_mfma_f32_16x16x32_bf16 v[24:27], v[216:219], v[24:27], v[158:161]
	v_mfma_f32_16x16x32_bf16 v[112:115], v[220:223], v[28:31], v[24:27]
	v_mfma_f32_16x16x32_bf16 v[24:27], v[192:195], v[40:43], v[84:87]
	v_mfma_f32_16x16x32_bf16 v[100:103], v[196:199], v[44:47], v[24:27]
	v_mfma_f32_16x16x32_bf16 v[24:27], v[216:219], v[40:43], v[80:83]
	v_mfma_f32_16x16x32_bf16 v[116:119], v[196:199], v[28:31], v[96:99]
	v_mfma_f32_16x16x32_bf16 v[96:99], v[220:223], v[44:47], v[24:27]
	v_mfma_f32_16x16x32_bf16 v[24:27], v[192:195], v[180:183], v[162:165]
	v_mfma_f32_16x16x32_bf16 v[84:87], v[196:199], v[184:187], v[24:27]
	v_mfma_f32_16x16x32_bf16 v[24:27], v[216:219], v[180:183], v[166:169]
	v_mfma_f32_16x16x32_bf16 v[80:83], v[220:223], v[184:187], v[24:27]
	v_mfma_f32_16x16x32_bf16 v[24:27], v[192:195], v[200:203], v[68:71]
	v_mfma_f32_16x16x32_bf16 v[68:71], v[196:199], v[204:207], v[24:27]
	v_mfma_f32_16x16x32_bf16 v[24:27], v[216:219], v[200:203], v[64:67]
	v_mfma_f32_16x16x32_bf16 v[64:67], v[220:223], v[204:207], v[24:27]
	s_barrier
	ds_read_b128 v[158:161], v142 offset:49152
	ds_read_b128 v[162:165], v142 offset:50176
	ds_read_b128 v[166:169], v143 offset:49152
	ds_read_b128 v[180:183], v143 offset:50176
	ds_read_b128 v[184:187], v144 offset:49152
	ds_read_b128 v[200:203], v144 offset:50176
	ds_read_b128 v[204:207], v145 offset:49152
	ds_read_b128 v[208:211], v145 offset:50176
	s_barrier
	s_waitcnt lgkmcnt(0)
	v_mfma_f32_16x16x32_bf16 v[24:27], v[8:11], v[158:161], v[60:63]
	v_mfma_f32_16x16x32_bf16 v[60:63], v[12:15], v[162:165], v[24:27]
	v_mfma_f32_16x16x32_bf16 v[24:27], v[170:173], v[158:161], v[56:59]
	v_mfma_f32_16x16x32_bf16 v[56:59], v[176:179], v[162:165], v[24:27]
	v_mfma_f32_16x16x32_bf16 v[24:27], v[8:11], v[166:169], v[52:55]
	v_mfma_f32_16x16x32_bf16 v[44:47], v[12:15], v[180:183], v[24:27]
	v_mfma_f32_16x16x32_bf16 v[24:27], v[170:173], v[166:169], v[48:51]
	v_mfma_f32_16x16x32_bf16 v[40:43], v[176:179], v[180:183], v[24:27]
	v_mfma_f32_16x16x32_bf16 v[24:27], v[8:11], v[184:187], v[188:191]
	v_mfma_f32_16x16x32_bf16 v[8:11], v[8:11], v[204:207], v[36:39]
	v_mfma_f32_16x16x32_bf16 v[28:31], v[12:15], v[200:203], v[24:27]
	v_mfma_f32_16x16x32_bf16 v[24:27], v[170:173], v[184:187], v[212:215]
	v_mfma_f32_16x16x32_bf16 v[12:15], v[12:15], v[208:211], v[8:11]
	v_mfma_f32_16x16x32_bf16 v[8:11], v[170:173], v[204:207], v[32:35]
	v_mfma_f32_16x16x32_bf16 v[24:27], v[176:179], v[200:203], v[24:27]
	v_mfma_f32_16x16x32_bf16 v[8:11], v[176:179], v[208:211], v[8:11]
	v_mfma_f32_16x16x32_bf16 v[32:35], v[192:195], v[158:161], v[130:133]
	v_mfma_f32_16x16x32_bf16 v[52:55], v[196:199], v[162:165], v[32:35]
	v_mfma_f32_16x16x32_bf16 v[32:35], v[216:219], v[158:161], v[134:137]
	v_mfma_f32_16x16x32_bf16 v[16:19], v[216:219], v[166:169], v[16:19]
	v_mfma_f32_16x16x32_bf16 v[48:51], v[220:223], v[162:165], v[32:35]
	v_mfma_f32_16x16x32_bf16 v[20:23], v[192:195], v[166:169], v[20:23]
	v_mfma_f32_16x16x32_bf16 v[32:35], v[220:223], v[180:183], v[16:19]
	v_mfma_f32_16x16x32_bf16 v[16:19], v[192:195], v[184:187], v[150:153]
	v_mfma_f32_16x16x32_bf16 v[36:39], v[196:199], v[180:183], v[20:23]
	v_mfma_f32_16x16x32_bf16 v[20:23], v[196:199], v[200:203], v[16:19]
	v_mfma_f32_16x16x32_bf16 v[16:19], v[216:219], v[184:187], v[154:157]
	v_mfma_f32_16x16x32_bf16 v[4:7], v[192:195], v[204:207], v[4:7]
	v_mfma_f32_16x16x32_bf16 v[0:3], v[216:219], v[204:207], v[0:3]
	v_mfma_f32_16x16x32_bf16 v[16:19], v[220:223], v[200:203], v[16:19]
	v_mfma_f32_16x16x32_bf16 v[4:7], v[196:199], v[208:211], v[4:7]
	v_mfma_f32_16x16x32_bf16 v[0:3], v[220:223], v[208:211], v[0:3]
	s_andn2_b64 vcc, exec, s[14:15]
	s_barrier
	s_cbranch_vccnz .LBB0_634
	s_barrier
